# nt cache hint on once-read f32 inputs (weights in P0, x in P1 and in the out-proj residual) + residual GEMM epilogues issue loads a row ahead with counted waits instead of 32 serial round trips
# speedup vs baseline: 1.0449x; 1.0341x over previous
; __device__ __forceinline__ u32x2 pk4bf(f32x4 y) { u32x2 r; r.x = cvt_pk_bf16(y[0], y[1]); r.y = cvt_pk_bf16(y[2], y[3]); return r; }
;     __device__ __forceinline__ void operator()(const f32x4 (&acc)[2][2][4][2], const Unit& u, int wr, int wc, int fr, int fq) const {
;     ...
;         if (relu2 == 2) { const float* bp = base + (size_t)t0 * 1024; bf16_t* op = (bf16_t*)out + (size_t)t0 * 1024;
;             PG8_RES_LOOP(b = *(const f32x4*)(bp + o2), *(u32x2*)(op + o2) = pk4bf(y)); }
;         else if (relu2 == 3) { const bf16_t* bp = (const bf16_t*)base + (size_t)t0 * 1024; bf16_t* op = (bf16_t*)out + (size_t)t0 * 1024;
;             PG8_RES_LOOP(const u32x2 w = *(const u32x2*)(bp + o2); b = unpk4bf(w), *(u32x2*)(op + o2) = pk4bf(y)); }
.LBB0_1059:
	s_andn2_b64 vcc, exec, s[2:3]
	s_cbranch_vccnz .LBB0_1067
	s_ashr_i32 s1, s0, 31
	s_lshl_b64 s[0:1], s[0:1], 10
	v_lshlrev_b64 v[150:151], 10, v[148:149]
	v_readlane_b32 s2, v243, 29
	v_lshl_add_u64 v[150:151], v[150:151], 0, v[146:147]
	s_cmp_gt_i32 s2, 2
	s_mov_b64 s[2:3], -1
	s_cbranch_scc0 .LBB0_1062
	s_lshl_b64 s[2:3], s[0:1], 1
	s_add_u32 s8, s34, s2
	s_addc_u32 s9, s35, s3
	v_lshlrev_b64 v[152:153], 1, v[150:151]
	s_add_u32 s2, s30, s2
	s_addc_u32 s3, s31, s3
	v_lshl_add_u64 v[154:155], s[8:9], 0, v[152:153]
	v_lshl_add_u64 v[156:157], s[2:3], 0, v[152:153]
	v_mov_b64_e32 v[184:185], v[154:155]
	global_load_dwordx2 v[164:165], v[184:185], off
	global_load_dwordx2 v[166:167], v[184:185], off offset:32
	global_load_dwordx2 v[168:169], v[184:185], off offset:256
	global_load_dwordx2 v[174:175], v[184:185], off offset:288
	s_mov_b64 s[4:5], 0x8000
	v_lshl_add_u64 v[184:185], v[154:155], 0, s[4:5]
	global_load_dwordx2 v[176:177], v[184:185], off
	global_load_dwordx2 v[178:179], v[184:185], off offset:32
	global_load_dwordx2 v[180:181], v[184:185], off offset:256
	global_load_dwordx2 v[182:183], v[184:185], off offset:288
	v_mov_b64_e32 v[158:159], v[156:157]
	s_waitcnt vmcnt(7)
	v_lshlrev_b32_e32 v214, 16, v164
	v_and_b32_e32 v215, 0xffff0000, v164
	v_lshlrev_b32_e32 v216, 16, v165
	v_and_b32_e32 v217, 0xffff0000, v165
	v_pk_fma_f32 v[214:215], v[138:139], v[14:15], v[214:215]
	v_pk_fma_f32 v[216:217], v[140:141], v[16:17], v[216:217]
	v_cvt_pk_bf16_f32 v218, v214, v215
	v_cvt_pk_bf16_f32 v219, v216, v217
	global_store_dwordx2 v[158:159], v[218:219], off
	s_waitcnt vmcnt(7)
	v_lshlrev_b32_e32 v214, 16, v166
	v_and_b32_e32 v215, 0xffff0000, v166
	v_lshlrev_b32_e32 v216, 16, v167
	v_and_b32_e32 v217, 0xffff0000, v167
	v_pk_fma_f32 v[214:215], v[142:143], v[10:11], v[214:215]
	v_pk_fma_f32 v[216:217], v[144:145], v[12:13], v[216:217]
	v_cvt_pk_bf16_f32 v220, v214, v215
	v_cvt_pk_bf16_f32 v221, v216, v217
	global_store_dwordx2 v[158:159], v[220:221], off offset:32
	s_waitcnt vmcnt(7)
	v_lshlrev_b32_e32 v214, 16, v168
	v_and_b32_e32 v215, 0xffff0000, v168
	v_lshlrev_b32_e32 v216, 16, v169
	v_and_b32_e32 v217, 0xffff0000, v169
	v_pk_fma_f32 v[214:215], v[134:135], v[6:7], v[214:215]
	v_pk_fma_f32 v[216:217], v[136:137], v[8:9], v[216:217]
	v_cvt_pk_bf16_f32 v218, v214, v215
	v_cvt_pk_bf16_f32 v219, v216, v217
	global_store_dwordx2 v[158:159], v[218:219], off offset:256
	s_waitcnt vmcnt(7)
	v_lshlrev_b32_e32 v214, 16, v174
	v_and_b32_e32 v215, 0xffff0000, v174
	v_lshlrev_b32_e32 v216, 16, v175
	v_and_b32_e32 v217, 0xffff0000, v175
	v_pk_fma_f32 v[214:215], v[130:131], v[2:3], v[214:215]
	v_pk_fma_f32 v[216:217], v[132:133], v[4:5], v[216:217]
	v_cvt_pk_bf16_f32 v220, v214, v215
	v_cvt_pk_bf16_f32 v221, v216, v217
	global_store_dwordx2 v[158:159], v[220:221], off offset:288
	s_mov_b64 s[4:5], 0x10000
	v_lshl_add_u64 v[184:185], v[154:155], 0, s[4:5]
	global_load_dwordx2 v[164:165], v[184:185], off
	global_load_dwordx2 v[166:167], v[184:185], off offset:32
	global_load_dwordx2 v[168:169], v[184:185], off offset:256
	global_load_dwordx2 v[174:175], v[184:185], off offset:288
	s_mov_b64 s[4:5], 0x8000
	v_lshl_add_u64 v[158:159], v[156:157], 0, s[4:5]
	s_waitcnt vmcnt(11)
	v_lshlrev_b32_e32 v214, 16, v176
	v_and_b32_e32 v215, 0xffff0000, v176
	v_lshlrev_b32_e32 v216, 16, v177
	v_and_b32_e32 v217, 0xffff0000, v177
	v_pk_fma_f32 v[214:215], v[126:127], v[14:15], v[214:215]
	v_pk_fma_f32 v[216:217], v[128:129], v[16:17], v[216:217]
	v_cvt_pk_bf16_f32 v218, v214, v215
	v_cvt_pk_bf16_f32 v219, v216, v217
	global_store_dwordx2 v[158:159], v[218:219], off
	s_waitcnt vmcnt(11)
	v_lshlrev_b32_e32 v214, 16, v178
	v_and_b32_e32 v215, 0xffff0000, v178
	v_lshlrev_b32_e32 v216, 16, v179
	v_and_b32_e32 v217, 0xffff0000, v179
	v_pk_fma_f32 v[214:215], v[122:123], v[10:11], v[214:215]
	v_pk_fma_f32 v[216:217], v[124:125], v[12:13], v[216:217]
	v_cvt_pk_bf16_f32 v220, v214, v215
	v_cvt_pk_bf16_f32 v221, v216, v217
	global_store_dwordx2 v[158:159], v[220:221], off offset:32
	s_waitcnt vmcnt(11)
	v_lshlrev_b32_e32 v214, 16, v180
	v_and_b32_e32 v215, 0xffff0000, v180
	v_lshlrev_b32_e32 v216, 16, v181
	v_and_b32_e32 v217, 0xffff0000, v181
	v_pk_fma_f32 v[214:215], v[118:119], v[6:7], v[214:215]
	v_pk_fma_f32 v[216:217], v[120:121], v[8:9], v[216:217]
	v_cvt_pk_bf16_f32 v218, v214, v215
	v_cvt_pk_bf16_f32 v219, v216, v217
	global_store_dwordx2 v[158:159], v[218:219], off offset:256
	s_waitcnt vmcnt(11)
	v_lshlrev_b32_e32 v214, 16, v182
	v_and_b32_e32 v215, 0xffff0000, v182
	v_lshlrev_b32_e32 v216, 16, v183
	v_and_b32_e32 v217, 0xffff0000, v183
	v_pk_fma_f32 v[214:215], v[114:115], v[2:3], v[214:215]
	v_pk_fma_f32 v[216:217], v[116:117], v[4:5], v[216:217]
	v_cvt_pk_bf16_f32 v220, v214, v215
	v_cvt_pk_bf16_f32 v221, v216, v217
	global_store_dwordx2 v[158:159], v[220:221], off offset:288
	s_mov_b64 s[4:5], 0x18000
	v_lshl_add_u64 v[184:185], v[154:155], 0, s[4:5]
	global_load_dwordx2 v[176:177], v[184:185], off
	global_load_dwordx2 v[178:179], v[184:185], off offset:32
	global_load_dwordx2 v[180:181], v[184:185], off offset:256
	global_load_dwordx2 v[182:183], v[184:185], off offset:288
	s_mov_b64 s[4:5], 0x10000
	v_lshl_add_u64 v[158:159], v[156:157], 0, s[4:5]
	s_waitcnt vmcnt(11)
	v_lshlrev_b32_e32 v214, 16, v164
	v_and_b32_e32 v215, 0xffff0000, v164
	v_lshlrev_b32_e32 v216, 16, v165
	v_and_b32_e32 v217, 0xffff0000, v165
	v_pk_fma_f32 v[214:215], v[110:111], v[14:15], v[214:215]
	v_pk_fma_f32 v[216:217], v[112:113], v[16:17], v[216:217]
	v_cvt_pk_bf16_f32 v218, v214, v215
	v_cvt_pk_bf16_f32 v219, v216, v217
	global_store_dwordx2 v[158:159], v[218:219], off
	s_waitcnt vmcnt(11)
; __device__ __forceinline__ u32x2 pk4bf(f32x4 y) { u32x2 r; r.x = cvt_pk_bf16(y[0], y[1]); r.y = cvt_pk_bf16(y[2], y[3]); return r; }
;     __device__ __forceinline__ void operator()(const f32x4 (&acc)[2][2][4][2], const Unit& u, int wr, int wc, int fr, int fq) const {
;     ...
;         if (relu2 == 2) { const float* bp = base + (size_t)t0 * 1024; bf16_t* op = (bf16_t*)out + (size_t)t0 * 1024;
;             PG8_RES_LOOP(b = *(const f32x4*)(bp + o2), *(u32x2*)(op + o2) = pk4bf(y)); }
;         else if (relu2 == 3) { const bf16_t* bp = (const bf16_t*)base + (size_t)t0 * 1024; bf16_t* op = (bf16_t*)out + (size_t)t0 * 1024;
;             PG8_RES_LOOP(const u32x2 w = *(const u32x2*)(bp + o2); b = unpk4bf(w), *(u32x2*)(op + o2) = pk4bf(y)); }
	v_lshlrev_b32_e32 v214, 16, v166
	v_and_b32_e32 v215, 0xffff0000, v166
	v_lshlrev_b32_e32 v216, 16, v167
	v_and_b32_e32 v217, 0xffff0000, v167
	v_pk_fma_f32 v[214:215], v[106:107], v[10:11], v[214:215]
	v_pk_fma_f32 v[216:217], v[108:109], v[12:13], v[216:217]
	v_cvt_pk_bf16_f32 v220, v214, v215
	v_cvt_pk_bf16_f32 v221, v216, v217
	global_store_dwordx2 v[158:159], v[220:221], off offset:32
	s_waitcnt vmcnt(11)
	v_lshlrev_b32_e32 v214, 16, v168
	v_and_b32_e32 v215, 0xffff0000, v168
	v_lshlrev_b32_e32 v216, 16, v169
	v_and_b32_e32 v217, 0xffff0000, v169
	v_pk_fma_f32 v[214:215], v[102:103], v[6:7], v[214:215]
	v_pk_fma_f32 v[216:217], v[104:105], v[8:9], v[216:217]
	v_cvt_pk_bf16_f32 v218, v214, v215
	v_cvt_pk_bf16_f32 v219, v216, v217
	global_store_dwordx2 v[158:159], v[218:219], off offset:256
	s_waitcnt vmcnt(11)
	v_lshlrev_b32_e32 v214, 16, v174
	v_and_b32_e32 v215, 0xffff0000, v174
	v_lshlrev_b32_e32 v216, 16, v175
	v_and_b32_e32 v217, 0xffff0000, v175
	v_pk_fma_f32 v[214:215], v[98:99], v[2:3], v[214:215]
	v_pk_fma_f32 v[216:217], v[100:101], v[4:5], v[216:217]
	v_cvt_pk_bf16_f32 v220, v214, v215
	v_cvt_pk_bf16_f32 v221, v216, v217
	global_store_dwordx2 v[158:159], v[220:221], off offset:288
	s_mov_b64 s[4:5], 0x40000
	v_lshl_add_u64 v[184:185], v[154:155], 0, s[4:5]
	global_load_dwordx2 v[164:165], v[184:185], off
	global_load_dwordx2 v[166:167], v[184:185], off offset:32
	global_load_dwordx2 v[168:169], v[184:185], off offset:256
	global_load_dwordx2 v[174:175], v[184:185], off offset:288
	s_mov_b64 s[4:5], 0x18000
	v_lshl_add_u64 v[158:159], v[156:157], 0, s[4:5]
	s_waitcnt vmcnt(11)
	v_lshlrev_b32_e32 v214, 16, v176
	v_and_b32_e32 v215, 0xffff0000, v176
	v_lshlrev_b32_e32 v216, 16, v177
	v_and_b32_e32 v217, 0xffff0000, v177
	v_pk_fma_f32 v[214:215], v[94:95], v[14:15], v[214:215]
	v_pk_fma_f32 v[216:217], v[96:97], v[16:17], v[216:217]
	v_cvt_pk_bf16_f32 v218, v214, v215
	v_cvt_pk_bf16_f32 v219, v216, v217
	global_store_dwordx2 v[158:159], v[218:219], off
	s_waitcnt vmcnt(11)
	v_lshlrev_b32_e32 v214, 16, v178
	v_and_b32_e32 v215, 0xffff0000, v178
	v_lshlrev_b32_e32 v216, 16, v179
	v_and_b32_e32 v217, 0xffff0000, v179
	v_pk_fma_f32 v[214:215], v[90:91], v[10:11], v[214:215]
	v_pk_fma_f32 v[216:217], v[92:93], v[12:13], v[216:217]
	v_cvt_pk_bf16_f32 v220, v214, v215
	v_cvt_pk_bf16_f32 v221, v216, v217
	global_store_dwordx2 v[158:159], v[220:221], off offset:32
	s_waitcnt vmcnt(11)
	v_lshlrev_b32_e32 v214, 16, v180
	v_and_b32_e32 v215, 0xffff0000, v180
	v_lshlrev_b32_e32 v216, 16, v181
	v_and_b32_e32 v217, 0xffff0000, v181
	v_pk_fma_f32 v[214:215], v[86:87], v[6:7], v[214:215]
	v_pk_fma_f32 v[216:217], v[88:89], v[8:9], v[216:217]
	v_cvt_pk_bf16_f32 v218, v214, v215
	v_cvt_pk_bf16_f32 v219, v216, v217
	global_store_dwordx2 v[158:159], v[218:219], off offset:256
	s_waitcnt vmcnt(11)
	v_lshlrev_b32_e32 v214, 16, v182
	v_and_b32_e32 v215, 0xffff0000, v182
	v_lshlrev_b32_e32 v216, 16, v183
	v_and_b32_e32 v217, 0xffff0000, v183
	v_pk_fma_f32 v[214:215], v[82:83], v[2:3], v[214:215]
	v_pk_fma_f32 v[216:217], v[84:85], v[4:5], v[216:217]
	v_cvt_pk_bf16_f32 v220, v214, v215
	v_cvt_pk_bf16_f32 v221, v216, v217
	global_store_dwordx2 v[158:159], v[220:221], off offset:288
	s_mov_b64 s[4:5], 0x48000
	v_lshl_add_u64 v[184:185], v[154:155], 0, s[4:5]
	global_load_dwordx2 v[176:177], v[184:185], off
	global_load_dwordx2 v[178:179], v[184:185], off offset:32
	global_load_dwordx2 v[180:181], v[184:185], off offset:256
	global_load_dwordx2 v[182:183], v[184:185], off offset:288
	s_mov_b64 s[4:5], 0x40000
	v_lshl_add_u64 v[158:159], v[156:157], 0, s[4:5]
	s_waitcnt vmcnt(11)
	v_lshlrev_b32_e32 v214, 16, v164
	v_and_b32_e32 v215, 0xffff0000, v164
	v_lshlrev_b32_e32 v216, 16, v165
	v_and_b32_e32 v217, 0xffff0000, v165
	v_pk_fma_f32 v[214:215], v[78:79], v[14:15], v[214:215]
	v_pk_fma_f32 v[216:217], v[80:81], v[16:17], v[216:217]
	v_cvt_pk_bf16_f32 v218, v214, v215
	v_cvt_pk_bf16_f32 v219, v216, v217
	global_store_dwordx2 v[158:159], v[218:219], off
	s_waitcnt vmcnt(11)
	v_lshlrev_b32_e32 v214, 16, v166
	v_and_b32_e32 v215, 0xffff0000, v166
	v_lshlrev_b32_e32 v216, 16, v167
	v_and_b32_e32 v217, 0xffff0000, v167
	v_pk_fma_f32 v[214:215], v[74:75], v[10:11], v[214:215]
	v_pk_fma_f32 v[216:217], v[76:77], v[12:13], v[216:217]
	v_cvt_pk_bf16_f32 v220, v214, v215
	v_cvt_pk_bf16_f32 v221, v216, v217
	global_store_dwordx2 v[158:159], v[220:221], off offset:32
	s_waitcnt vmcnt(11)
	v_lshlrev_b32_e32 v214, 16, v168
	v_and_b32_e32 v215, 0xffff0000, v168
	v_lshlrev_b32_e32 v216, 16, v169
	v_and_b32_e32 v217, 0xffff0000, v169
	v_pk_fma_f32 v[214:215], v[70:71], v[6:7], v[214:215]
	v_pk_fma_f32 v[216:217], v[72:73], v[8:9], v[216:217]
	v_cvt_pk_bf16_f32 v218, v214, v215
	v_cvt_pk_bf16_f32 v219, v216, v217
	global_store_dwordx2 v[158:159], v[218:219], off offset:256
	s_waitcnt vmcnt(11)
	v_lshlrev_b32_e32 v214, 16, v174
	v_and_b32_e32 v215, 0xffff0000, v174
	v_lshlrev_b32_e32 v216, 16, v175
	v_and_b32_e32 v217, 0xffff0000, v175
	v_pk_fma_f32 v[214:215], v[66:67], v[2:3], v[214:215]
	v_pk_fma_f32 v[216:217], v[68:69], v[4:5], v[216:217]
	v_cvt_pk_bf16_f32 v220, v214, v215
	v_cvt_pk_bf16_f32 v221, v216, v217
	global_store_dwordx2 v[158:159], v[220:221], off offset:288
	s_mov_b64 s[4:5], 0x50000
	v_lshl_add_u64 v[184:185], v[154:155], 0, s[4:5]
	global_load_dwordx2 v[164:165], v[184:185], off
	global_load_dwordx2 v[166:167], v[184:185], off offset:32
	global_load_dwordx2 v[168:169], v[184:185], off offset:256
	global_load_dwordx2 v[174:175], v[184:185], off offset:288
	s_mov_b64 s[4:5], 0x48000
	v_lshl_add_u64 v[158:159], v[156:157], 0, s[4:5]
	s_waitcnt vmcnt(11)
; __device__ __forceinline__ u32x2 pk4bf(f32x4 y) { u32x2 r; r.x = cvt_pk_bf16(y[0], y[1]); r.y = cvt_pk_bf16(y[2], y[3]); return r; }
;     __device__ __forceinline__ void operator()(const f32x4 (&acc)[2][2][4][2], const Unit& u, int wr, int wc, int fr, int fq) const {
;     ...
;         if (relu2 == 2) { const float* bp = base + (size_t)t0 * 1024; bf16_t* op = (bf16_t*)out + (size_t)t0 * 1024;
;             PG8_RES_LOOP(b = *(const f32x4*)(bp + o2), *(u32x2*)(op + o2) = pk4bf(y)); }
;         else if (relu2 == 3) { const bf16_t* bp = (const bf16_t*)base + (size_t)t0 * 1024; bf16_t* op = (bf16_t*)out + (size_t)t0 * 1024;
;             PG8_RES_LOOP(const u32x2 w = *(const u32x2*)(bp + o2); b = unpk4bf(w), *(u32x2*)(op + o2) = pk4bf(y)); }
	v_lshlrev_b32_e32 v214, 16, v176
	v_and_b32_e32 v215, 0xffff0000, v176
	v_lshlrev_b32_e32 v216, 16, v177
	v_and_b32_e32 v217, 0xffff0000, v177
	v_pk_fma_f32 v[214:215], v[62:63], v[14:15], v[214:215]
	v_pk_fma_f32 v[216:217], v[64:65], v[16:17], v[216:217]
	v_cvt_pk_bf16_f32 v218, v214, v215
	v_cvt_pk_bf16_f32 v219, v216, v217
	global_store_dwordx2 v[158:159], v[218:219], off
	s_waitcnt vmcnt(11)
	v_lshlrev_b32_e32 v214, 16, v178
	v_and_b32_e32 v215, 0xffff0000, v178
	v_lshlrev_b32_e32 v216, 16, v179
	v_and_b32_e32 v217, 0xffff0000, v179
	v_pk_fma_f32 v[214:215], v[58:59], v[10:11], v[214:215]
	v_pk_fma_f32 v[216:217], v[60:61], v[12:13], v[216:217]
	v_cvt_pk_bf16_f32 v220, v214, v215
	v_cvt_pk_bf16_f32 v221, v216, v217
	global_store_dwordx2 v[158:159], v[220:221], off offset:32
	s_waitcnt vmcnt(11)
	v_lshlrev_b32_e32 v214, 16, v180
	v_and_b32_e32 v215, 0xffff0000, v180
	v_lshlrev_b32_e32 v216, 16, v181
	v_and_b32_e32 v217, 0xffff0000, v181
	v_pk_fma_f32 v[214:215], v[54:55], v[6:7], v[214:215]
	v_pk_fma_f32 v[216:217], v[56:57], v[8:9], v[216:217]
	v_cvt_pk_bf16_f32 v218, v214, v215
	v_cvt_pk_bf16_f32 v219, v216, v217
	global_store_dwordx2 v[158:159], v[218:219], off offset:256
	s_waitcnt vmcnt(11)
	v_lshlrev_b32_e32 v214, 16, v182
	v_and_b32_e32 v215, 0xffff0000, v182
	v_lshlrev_b32_e32 v216, 16, v183
	v_and_b32_e32 v217, 0xffff0000, v183
	v_pk_fma_f32 v[214:215], v[50:51], v[2:3], v[214:215]
	v_pk_fma_f32 v[216:217], v[52:53], v[4:5], v[216:217]
	v_cvt_pk_bf16_f32 v220, v214, v215
	v_cvt_pk_bf16_f32 v221, v216, v217
	global_store_dwordx2 v[158:159], v[220:221], off offset:288
	s_mov_b64 s[4:5], 0x58000
	v_lshl_add_u64 v[184:185], v[154:155], 0, s[4:5]
	global_load_dwordx2 v[176:177], v[184:185], off
	global_load_dwordx2 v[178:179], v[184:185], off offset:32
	global_load_dwordx2 v[180:181], v[184:185], off offset:256
	global_load_dwordx2 v[182:183], v[184:185], off offset:288
	s_mov_b64 s[4:5], 0x50000
	v_lshl_add_u64 v[158:159], v[156:157], 0, s[4:5]
	s_waitcnt vmcnt(11)
	v_lshlrev_b32_e32 v214, 16, v164
	v_and_b32_e32 v215, 0xffff0000, v164
	v_lshlrev_b32_e32 v216, 16, v165
	v_and_b32_e32 v217, 0xffff0000, v165
	v_pk_fma_f32 v[214:215], v[46:47], v[14:15], v[214:215]
	v_pk_fma_f32 v[216:217], v[48:49], v[16:17], v[216:217]
	v_cvt_pk_bf16_f32 v218, v214, v215
	v_cvt_pk_bf16_f32 v219, v216, v217
	global_store_dwordx2 v[158:159], v[218:219], off
	s_waitcnt vmcnt(11)
	v_lshlrev_b32_e32 v214, 16, v166
	v_and_b32_e32 v215, 0xffff0000, v166
	v_lshlrev_b32_e32 v216, 16, v167
	v_and_b32_e32 v217, 0xffff0000, v167
	v_pk_fma_f32 v[214:215], v[42:43], v[10:11], v[214:215]
	v_pk_fma_f32 v[216:217], v[44:45], v[12:13], v[216:217]
	v_cvt_pk_bf16_f32 v220, v214, v215
	v_cvt_pk_bf16_f32 v221, v216, v217
	global_store_dwordx2 v[158:159], v[220:221], off offset:32
	s_waitcnt vmcnt(11)
	v_lshlrev_b32_e32 v214, 16, v168
	v_and_b32_e32 v215, 0xffff0000, v168
	v_lshlrev_b32_e32 v216, 16, v169
	v_and_b32_e32 v217, 0xffff0000, v169
	v_pk_fma_f32 v[214:215], v[38:39], v[6:7], v[214:215]
	v_pk_fma_f32 v[216:217], v[40:41], v[8:9], v[216:217]
	v_cvt_pk_bf16_f32 v218, v214, v215
	v_cvt_pk_bf16_f32 v219, v216, v217
	global_store_dwordx2 v[158:159], v[218:219], off offset:256
	s_waitcnt vmcnt(11)
	v_lshlrev_b32_e32 v214, 16, v174
	v_and_b32_e32 v215, 0xffff0000, v174
	v_lshlrev_b32_e32 v216, 16, v175
	v_and_b32_e32 v217, 0xffff0000, v175
	v_pk_fma_f32 v[214:215], v[34:35], v[2:3], v[214:215]
	v_pk_fma_f32 v[216:217], v[36:37], v[4:5], v[216:217]
	v_cvt_pk_bf16_f32 v220, v214, v215
	v_cvt_pk_bf16_f32 v221, v216, v217
	global_store_dwordx2 v[158:159], v[220:221], off offset:288
	s_mov_b64 s[4:5], 0x58000
	v_lshl_add_u64 v[158:159], v[156:157], 0, s[4:5]
	s_waitcnt vmcnt(7)
	v_lshlrev_b32_e32 v214, 16, v176
	v_and_b32_e32 v215, 0xffff0000, v176
	v_lshlrev_b32_e32 v216, 16, v177
	v_and_b32_e32 v217, 0xffff0000, v177
	v_pk_fma_f32 v[214:215], v[30:31], v[14:15], v[214:215]
	v_pk_fma_f32 v[216:217], v[32:33], v[16:17], v[216:217]
	v_cvt_pk_bf16_f32 v218, v214, v215
	v_cvt_pk_bf16_f32 v219, v216, v217
	global_store_dwordx2 v[158:159], v[218:219], off
	s_waitcnt vmcnt(7)
	v_lshlrev_b32_e32 v214, 16, v178
	v_and_b32_e32 v215, 0xffff0000, v178
	v_lshlrev_b32_e32 v216, 16, v179
	v_and_b32_e32 v217, 0xffff0000, v179
	v_pk_fma_f32 v[214:215], v[26:27], v[10:11], v[214:215]
	v_pk_fma_f32 v[216:217], v[28:29], v[12:13], v[216:217]
	v_cvt_pk_bf16_f32 v220, v214, v215
	v_cvt_pk_bf16_f32 v221, v216, v217
	global_store_dwordx2 v[158:159], v[220:221], off offset:32
	s_waitcnt vmcnt(7)
	v_lshlrev_b32_e32 v214, 16, v180
	v_and_b32_e32 v215, 0xffff0000, v180
	v_lshlrev_b32_e32 v216, 16, v181
	v_and_b32_e32 v217, 0xffff0000, v181
	v_pk_fma_f32 v[214:215], v[22:23], v[6:7], v[214:215]
	v_pk_fma_f32 v[216:217], v[24:25], v[8:9], v[216:217]
	v_cvt_pk_bf16_f32 v218, v214, v215
	v_cvt_pk_bf16_f32 v219, v216, v217
	global_store_dwordx2 v[158:159], v[218:219], off offset:256
	s_waitcnt vmcnt(7)
	v_lshlrev_b32_e32 v214, 16, v182
	v_and_b32_e32 v215, 0xffff0000, v182
	v_lshlrev_b32_e32 v216, 16, v183
	v_and_b32_e32 v217, 0xffff0000, v183
	v_pk_fma_f32 v[214:215], v[18:19], v[2:3], v[214:215]
	v_pk_fma_f32 v[216:217], v[20:21], v[4:5], v[216:217]
	v_cvt_pk_bf16_f32 v220, v214, v215
	v_cvt_pk_bf16_f32 v221, v216, v217
	global_store_dwordx2 v[158:159], v[220:221], off offset:288
	s_mov_b64 s[2:3], 0
;     __device__ __forceinline__ void operator()(const f32x4 (&acc)[2][2][4][2], const Unit& u, int wr, int wc, int fr, int fq) const {
;     ...
;         else { const bf16_t* bp = (const bf16_t*)base + (size_t)t0 * 1024; float* op = (float*)out + (size_t)t0 * 1024;
;             PG8_RES_LOOP(const u32x2 w = *(const u32x2*)(bp + o2); b = unpk4bf(w), *(f32x4*)(op + o2) = y); }
.LBB0_1062:
	s_andn2_b64 vcc, exec, s[2:3]
	s_cbranch_vccnz .LBB0_1067
	v_readlane_b32 s2, v243, 29
	s_cmp_lg_u32 s2, 2
	s_mov_b64 s[2:3], -1
	s_cbranch_scc0 .LBB0_1065
	s_lshl_b64 s[2:3], s[0:1], 1
	s_add_u32 s8, s34, s2
	s_addc_u32 s9, s35, s3
	v_lshl_add_u64 v[154:155], v[150:151], 1, s[8:9]
	s_lshl_b64 s[2:3], s[0:1], 2
	s_add_u32 s2, s30, s2
	s_addc_u32 s3, s31, s3
	v_lshl_add_u64 v[156:157], v[150:151], 2, s[2:3]
	v_mov_b64_e32 v[184:185], v[154:155]
	global_load_dwordx2 v[164:165], v[184:185], off
	global_load_dwordx2 v[166:167], v[184:185], off offset:32
	global_load_dwordx2 v[168:169], v[184:185], off offset:256
	global_load_dwordx2 v[174:175], v[184:185], off offset:288
	s_mov_b64 s[4:5], 0x8000
	v_lshl_add_u64 v[184:185], v[154:155], 0, s[4:5]
	global_load_dwordx2 v[176:177], v[184:185], off
	global_load_dwordx2 v[178:179], v[184:185], off offset:32
	global_load_dwordx2 v[180:181], v[184:185], off offset:256
	global_load_dwordx2 v[182:183], v[184:185], off offset:288
	v_mov_b64_e32 v[158:159], v[156:157]
	s_waitcnt vmcnt(7)
	v_lshlrev_b32_e32 v214, 16, v164
	v_and_b32_e32 v215, 0xffff0000, v164
	v_lshlrev_b32_e32 v216, 16, v165
	v_and_b32_e32 v217, 0xffff0000, v165
	v_pk_fma_f32 v[218:219], v[138:139], v[14:15], v[214:215]
	v_pk_fma_f32 v[220:221], v[140:141], v[16:17], v[216:217]
	global_store_dwordx4 v[158:159], v[218:221], off
	s_waitcnt vmcnt(7)
	v_lshlrev_b32_e32 v214, 16, v166
	v_and_b32_e32 v215, 0xffff0000, v166
	v_lshlrev_b32_e32 v216, 16, v167
	v_and_b32_e32 v217, 0xffff0000, v167
	v_pk_fma_f32 v[160:161], v[142:143], v[10:11], v[214:215]
	v_pk_fma_f32 v[162:163], v[144:145], v[12:13], v[216:217]
	global_store_dwordx4 v[158:159], v[160:163], off offset:64
	s_waitcnt vmcnt(7)
	v_lshlrev_b32_e32 v214, 16, v168
	v_and_b32_e32 v215, 0xffff0000, v168
	v_lshlrev_b32_e32 v216, 16, v169
	v_and_b32_e32 v217, 0xffff0000, v169
	v_pk_fma_f32 v[218:219], v[134:135], v[6:7], v[214:215]
	v_pk_fma_f32 v[220:221], v[136:137], v[8:9], v[216:217]
	global_store_dwordx4 v[158:159], v[218:221], off offset:512
	s_waitcnt vmcnt(7)
	v_lshlrev_b32_e32 v214, 16, v174
	v_and_b32_e32 v215, 0xffff0000, v174
	v_lshlrev_b32_e32 v216, 16, v175
	v_and_b32_e32 v217, 0xffff0000, v175
	v_pk_fma_f32 v[160:161], v[130:131], v[2:3], v[214:215]
	v_pk_fma_f32 v[162:163], v[132:133], v[4:5], v[216:217]
	global_store_dwordx4 v[158:159], v[160:163], off offset:576
	s_mov_b64 s[4:5], 0x10000
	v_lshl_add_u64 v[184:185], v[154:155], 0, s[4:5]
	global_load_dwordx2 v[164:165], v[184:185], off
	global_load_dwordx2 v[166:167], v[184:185], off offset:32
	global_load_dwordx2 v[168:169], v[184:185], off offset:256
	global_load_dwordx2 v[174:175], v[184:185], off offset:288
	s_mov_b64 s[4:5], 0x10000
	v_lshl_add_u64 v[158:159], v[156:157], 0, s[4:5]
	s_waitcnt vmcnt(11)
	v_lshlrev_b32_e32 v214, 16, v176
	v_and_b32_e32 v215, 0xffff0000, v176
	v_lshlrev_b32_e32 v216, 16, v177
	v_and_b32_e32 v217, 0xffff0000, v177
	v_pk_fma_f32 v[218:219], v[126:127], v[14:15], v[214:215]
	v_pk_fma_f32 v[220:221], v[128:129], v[16:17], v[216:217]
	global_store_dwordx4 v[158:159], v[218:221], off
	s_waitcnt vmcnt(11)
	v_lshlrev_b32_e32 v214, 16, v178
	v_and_b32_e32 v215, 0xffff0000, v178
	v_lshlrev_b32_e32 v216, 16, v179
	v_and_b32_e32 v217, 0xffff0000, v179
	v_pk_fma_f32 v[160:161], v[122:123], v[10:11], v[214:215]
	v_pk_fma_f32 v[162:163], v[124:125], v[12:13], v[216:217]
	global_store_dwordx4 v[158:159], v[160:163], off offset:64
	s_waitcnt vmcnt(11)
	v_lshlrev_b32_e32 v214, 16, v180
	v_and_b32_e32 v215, 0xffff0000, v180
	v_lshlrev_b32_e32 v216, 16, v181
	v_and_b32_e32 v217, 0xffff0000, v181
	v_pk_fma_f32 v[218:219], v[118:119], v[6:7], v[214:215]
	v_pk_fma_f32 v[220:221], v[120:121], v[8:9], v[216:217]
	global_store_dwordx4 v[158:159], v[218:221], off offset:512
	s_waitcnt vmcnt(11)
	v_lshlrev_b32_e32 v214, 16, v182
	v_and_b32_e32 v215, 0xffff0000, v182
	v_lshlrev_b32_e32 v216, 16, v183
	v_and_b32_e32 v217, 0xffff0000, v183
	v_pk_fma_f32 v[160:161], v[114:115], v[2:3], v[214:215]
	v_pk_fma_f32 v[162:163], v[116:117], v[4:5], v[216:217]
	global_store_dwordx4 v[158:159], v[160:163], off offset:576
	s_mov_b64 s[4:5], 0x18000
	v_lshl_add_u64 v[184:185], v[154:155], 0, s[4:5]
	global_load_dwordx2 v[176:177], v[184:185], off
	global_load_dwordx2 v[178:179], v[184:185], off offset:32
	global_load_dwordx2 v[180:181], v[184:185], off offset:256
	global_load_dwordx2 v[182:183], v[184:185], off offset:288
	s_mov_b64 s[4:5], 0x20000
	v_lshl_add_u64 v[158:159], v[156:157], 0, s[4:5]
	s_waitcnt vmcnt(11)
	v_lshlrev_b32_e32 v214, 16, v164
	v_and_b32_e32 v215, 0xffff0000, v164
	v_lshlrev_b32_e32 v216, 16, v165
	v_and_b32_e32 v217, 0xffff0000, v165
	v_pk_fma_f32 v[218:219], v[110:111], v[14:15], v[214:215]
	v_pk_fma_f32 v[220:221], v[112:113], v[16:17], v[216:217]
	global_store_dwordx4 v[158:159], v[218:221], off
	s_waitcnt vmcnt(11)
	v_lshlrev_b32_e32 v214, 16, v166
	v_and_b32_e32 v215, 0xffff0000, v166
	v_lshlrev_b32_e32 v216, 16, v167
	v_and_b32_e32 v217, 0xffff0000, v167
	v_pk_fma_f32 v[160:161], v[106:107], v[10:11], v[214:215]
	v_pk_fma_f32 v[162:163], v[108:109], v[12:13], v[216:217]
	global_store_dwordx4 v[158:159], v[160:163], off offset:64
	s_waitcnt vmcnt(11)
	v_lshlrev_b32_e32 v214, 16, v168
	v_and_b32_e32 v215, 0xffff0000, v168
	v_lshlrev_b32_e32 v216, 16, v169
	v_and_b32_e32 v217, 0xffff0000, v169
	v_pk_fma_f32 v[218:219], v[102:103], v[6:7], v[214:215]
	v_pk_fma_f32 v[220:221], v[104:105], v[8:9], v[216:217]
	global_store_dwordx4 v[158:159], v[218:221], off offset:512
	s_waitcnt vmcnt(11)
;     __device__ __forceinline__ void operator()(const f32x4 (&acc)[2][2][4][2], const Unit& u, int wr, int wc, int fr, int fq) const {
;     ...
;         else { const bf16_t* bp = (const bf16_t*)base + (size_t)t0 * 1024; float* op = (float*)out + (size_t)t0 * 1024;
;             PG8_RES_LOOP(const u32x2 w = *(const u32x2*)(bp + o2); b = unpk4bf(w), *(f32x4*)(op + o2) = y); }
	v_lshlrev_b32_e32 v214, 16, v174
	v_and_b32_e32 v215, 0xffff0000, v174
	v_lshlrev_b32_e32 v216, 16, v175
	v_and_b32_e32 v217, 0xffff0000, v175
	v_pk_fma_f32 v[160:161], v[98:99], v[2:3], v[214:215]
	v_pk_fma_f32 v[162:163], v[100:101], v[4:5], v[216:217]
	global_store_dwordx4 v[158:159], v[160:163], off offset:576
	s_mov_b64 s[4:5], 0x40000
	v_lshl_add_u64 v[184:185], v[154:155], 0, s[4:5]
	global_load_dwordx2 v[164:165], v[184:185], off
	global_load_dwordx2 v[166:167], v[184:185], off offset:32
	global_load_dwordx2 v[168:169], v[184:185], off offset:256
	global_load_dwordx2 v[174:175], v[184:185], off offset:288
	s_mov_b64 s[4:5], 0x30000
	v_lshl_add_u64 v[158:159], v[156:157], 0, s[4:5]
	s_waitcnt vmcnt(11)
	v_lshlrev_b32_e32 v214, 16, v176
	v_and_b32_e32 v215, 0xffff0000, v176
	v_lshlrev_b32_e32 v216, 16, v177
	v_and_b32_e32 v217, 0xffff0000, v177
	v_pk_fma_f32 v[218:219], v[94:95], v[14:15], v[214:215]
	v_pk_fma_f32 v[220:221], v[96:97], v[16:17], v[216:217]
	global_store_dwordx4 v[158:159], v[218:221], off
	s_waitcnt vmcnt(11)
	v_lshlrev_b32_e32 v214, 16, v178
	v_and_b32_e32 v215, 0xffff0000, v178
	v_lshlrev_b32_e32 v216, 16, v179
	v_and_b32_e32 v217, 0xffff0000, v179
	v_pk_fma_f32 v[160:161], v[90:91], v[10:11], v[214:215]
	v_pk_fma_f32 v[162:163], v[92:93], v[12:13], v[216:217]
	global_store_dwordx4 v[158:159], v[160:163], off offset:64
	s_waitcnt vmcnt(11)
	v_lshlrev_b32_e32 v214, 16, v180
	v_and_b32_e32 v215, 0xffff0000, v180
	v_lshlrev_b32_e32 v216, 16, v181
	v_and_b32_e32 v217, 0xffff0000, v181
	v_pk_fma_f32 v[218:219], v[86:87], v[6:7], v[214:215]
	v_pk_fma_f32 v[220:221], v[88:89], v[8:9], v[216:217]
	global_store_dwordx4 v[158:159], v[218:221], off offset:512
	s_waitcnt vmcnt(11)
	v_lshlrev_b32_e32 v214, 16, v182
	v_and_b32_e32 v215, 0xffff0000, v182
	v_lshlrev_b32_e32 v216, 16, v183
	v_and_b32_e32 v217, 0xffff0000, v183
	v_pk_fma_f32 v[160:161], v[82:83], v[2:3], v[214:215]
	v_pk_fma_f32 v[162:163], v[84:85], v[4:5], v[216:217]
	global_store_dwordx4 v[158:159], v[160:163], off offset:576
	s_mov_b64 s[4:5], 0x48000
	v_lshl_add_u64 v[184:185], v[154:155], 0, s[4:5]
	global_load_dwordx2 v[176:177], v[184:185], off
	global_load_dwordx2 v[178:179], v[184:185], off offset:32
	global_load_dwordx2 v[180:181], v[184:185], off offset:256
	global_load_dwordx2 v[182:183], v[184:185], off offset:288
	s_mov_b64 s[4:5], 0x80000
	v_lshl_add_u64 v[158:159], v[156:157], 0, s[4:5]
	s_waitcnt vmcnt(11)
	v_lshlrev_b32_e32 v214, 16, v164
	v_and_b32_e32 v215, 0xffff0000, v164
	v_lshlrev_b32_e32 v216, 16, v165
	v_and_b32_e32 v217, 0xffff0000, v165
	v_pk_fma_f32 v[218:219], v[78:79], v[14:15], v[214:215]
	v_pk_fma_f32 v[220:221], v[80:81], v[16:17], v[216:217]
	global_store_dwordx4 v[158:159], v[218:221], off
	s_waitcnt vmcnt(11)
	v_lshlrev_b32_e32 v214, 16, v166
	v_and_b32_e32 v215, 0xffff0000, v166
	v_lshlrev_b32_e32 v216, 16, v167
	v_and_b32_e32 v217, 0xffff0000, v167
	v_pk_fma_f32 v[160:161], v[74:75], v[10:11], v[214:215]
	v_pk_fma_f32 v[162:163], v[76:77], v[12:13], v[216:217]
	global_store_dwordx4 v[158:159], v[160:163], off offset:64
	s_waitcnt vmcnt(11)
	v_lshlrev_b32_e32 v214, 16, v168
	v_and_b32_e32 v215, 0xffff0000, v168
	v_lshlrev_b32_e32 v216, 16, v169
	v_and_b32_e32 v217, 0xffff0000, v169
	v_pk_fma_f32 v[218:219], v[70:71], v[6:7], v[214:215]
	v_pk_fma_f32 v[220:221], v[72:73], v[8:9], v[216:217]
	global_store_dwordx4 v[158:159], v[218:221], off offset:512
	s_waitcnt vmcnt(11)
	v_lshlrev_b32_e32 v214, 16, v174
	v_and_b32_e32 v215, 0xffff0000, v174
	v_lshlrev_b32_e32 v216, 16, v175
	v_and_b32_e32 v217, 0xffff0000, v175
	v_pk_fma_f32 v[160:161], v[66:67], v[2:3], v[214:215]
	v_pk_fma_f32 v[162:163], v[68:69], v[4:5], v[216:217]
	global_store_dwordx4 v[158:159], v[160:163], off offset:576
	s_mov_b64 s[4:5], 0x50000
	v_lshl_add_u64 v[184:185], v[154:155], 0, s[4:5]
	global_load_dwordx2 v[164:165], v[184:185], off
	global_load_dwordx2 v[166:167], v[184:185], off offset:32
	global_load_dwordx2 v[168:169], v[184:185], off offset:256
	global_load_dwordx2 v[174:175], v[184:185], off offset:288
	s_mov_b64 s[4:5], 0x90000
	v_lshl_add_u64 v[158:159], v[156:157], 0, s[4:5]
	s_waitcnt vmcnt(11)
	v_lshlrev_b32_e32 v214, 16, v176
	v_and_b32_e32 v215, 0xffff0000, v176
	v_lshlrev_b32_e32 v216, 16, v177
	v_and_b32_e32 v217, 0xffff0000, v177
	v_pk_fma_f32 v[218:219], v[62:63], v[14:15], v[214:215]
	v_pk_fma_f32 v[220:221], v[64:65], v[16:17], v[216:217]
	global_store_dwordx4 v[158:159], v[218:221], off
	s_waitcnt vmcnt(11)
	v_lshlrev_b32_e32 v214, 16, v178
	v_and_b32_e32 v215, 0xffff0000, v178
	v_lshlrev_b32_e32 v216, 16, v179
	v_and_b32_e32 v217, 0xffff0000, v179
	v_pk_fma_f32 v[160:161], v[58:59], v[10:11], v[214:215]
	v_pk_fma_f32 v[162:163], v[60:61], v[12:13], v[216:217]
	global_store_dwordx4 v[158:159], v[160:163], off offset:64
	s_waitcnt vmcnt(11)
	v_lshlrev_b32_e32 v214, 16, v180
	v_and_b32_e32 v215, 0xffff0000, v180
	v_lshlrev_b32_e32 v216, 16, v181
	v_and_b32_e32 v217, 0xffff0000, v181
	v_pk_fma_f32 v[218:219], v[54:55], v[6:7], v[214:215]
	v_pk_fma_f32 v[220:221], v[56:57], v[8:9], v[216:217]
	global_store_dwordx4 v[158:159], v[218:221], off offset:512
	s_waitcnt vmcnt(11)
	v_lshlrev_b32_e32 v214, 16, v182
	v_and_b32_e32 v215, 0xffff0000, v182
	v_lshlrev_b32_e32 v216, 16, v183
	v_and_b32_e32 v217, 0xffff0000, v183
	v_pk_fma_f32 v[160:161], v[50:51], v[2:3], v[214:215]
	v_pk_fma_f32 v[162:163], v[52:53], v[4:5], v[216:217]
	global_store_dwordx4 v[158:159], v[160:163], off offset:576
	s_mov_b64 s[4:5], 0x58000
	v_lshl_add_u64 v[184:185], v[154:155], 0, s[4:5]
	global_load_dwordx2 v[176:177], v[184:185], off
	global_load_dwordx2 v[178:179], v[184:185], off offset:32
	global_load_dwordx2 v[180:181], v[184:185], off offset:256
	global_load_dwordx2 v[182:183], v[184:185], off offset:288
	s_mov_b64 s[4:5], 0xa0000
	v_lshl_add_u64 v[158:159], v[156:157], 0, s[4:5]
	s_waitcnt vmcnt(11)
; __device__ __forceinline__ u32x2 pk4bf(f32x4 y) { u32x2 r; r.x = cvt_pk_bf16(y[0], y[1]); r.y = cvt_pk_bf16(y[2], y[3]); return r; }
;     __device__ __forceinline__ void operator()(const f32x4 (&acc)[2][2][4][2], const Unit& u, int wr, int wc, int fr, int fq) const {
;     ...
;         if (relu2 == 2) { const float* bp = base + (size_t)t0 * 1024; bf16_t* op = (bf16_t*)out + (size_t)t0 * 1024;
;             PG8_RES_LOOP(b = *(const f32x4*)(bp + o2), *(u32x2*)(op + o2) = pk4bf(y)); }
;     ...
;         else { const bf16_t* bp = (const bf16_t*)base + (size_t)t0 * 1024; float* op = (float*)out + (size_t)t0 * 1024;
;             PG8_RES_LOOP(const u32x2 w = *(const u32x2*)(bp + o2); b = unpk4bf(w), *(f32x4*)(op + o2) = y); }
	v_lshlrev_b32_e32 v214, 16, v164
	v_and_b32_e32 v215, 0xffff0000, v164
	v_lshlrev_b32_e32 v216, 16, v165
	v_and_b32_e32 v217, 0xffff0000, v165
	v_pk_fma_f32 v[218:219], v[46:47], v[14:15], v[214:215]
	v_pk_fma_f32 v[220:221], v[48:49], v[16:17], v[216:217]
	global_store_dwordx4 v[158:159], v[218:221], off
	s_waitcnt vmcnt(11)
	v_lshlrev_b32_e32 v214, 16, v166
	v_and_b32_e32 v215, 0xffff0000, v166
	v_lshlrev_b32_e32 v216, 16, v167
	v_and_b32_e32 v217, 0xffff0000, v167
	v_pk_fma_f32 v[160:161], v[42:43], v[10:11], v[214:215]
	v_pk_fma_f32 v[162:163], v[44:45], v[12:13], v[216:217]
	global_store_dwordx4 v[158:159], v[160:163], off offset:64
	s_waitcnt vmcnt(11)
	v_lshlrev_b32_e32 v214, 16, v168
	v_and_b32_e32 v215, 0xffff0000, v168
	v_lshlrev_b32_e32 v216, 16, v169
	v_and_b32_e32 v217, 0xffff0000, v169
	v_pk_fma_f32 v[218:219], v[38:39], v[6:7], v[214:215]
	v_pk_fma_f32 v[220:221], v[40:41], v[8:9], v[216:217]
	global_store_dwordx4 v[158:159], v[218:221], off offset:512
	s_waitcnt vmcnt(11)
	v_lshlrev_b32_e32 v214, 16, v174
	v_and_b32_e32 v215, 0xffff0000, v174
	v_lshlrev_b32_e32 v216, 16, v175
	v_and_b32_e32 v217, 0xffff0000, v175
	v_pk_fma_f32 v[160:161], v[34:35], v[2:3], v[214:215]
	v_pk_fma_f32 v[162:163], v[36:37], v[4:5], v[216:217]
	global_store_dwordx4 v[158:159], v[160:163], off offset:576
	s_mov_b64 s[4:5], 0xb0000
	v_lshl_add_u64 v[158:159], v[156:157], 0, s[4:5]
	s_waitcnt vmcnt(7)
	v_lshlrev_b32_e32 v214, 16, v176
	v_and_b32_e32 v215, 0xffff0000, v176
	v_lshlrev_b32_e32 v216, 16, v177
	v_and_b32_e32 v217, 0xffff0000, v177
	v_pk_fma_f32 v[218:219], v[30:31], v[14:15], v[214:215]
	v_pk_fma_f32 v[220:221], v[32:33], v[16:17], v[216:217]
	global_store_dwordx4 v[158:159], v[218:221], off
	s_waitcnt vmcnt(7)
	v_lshlrev_b32_e32 v214, 16, v178
	v_and_b32_e32 v215, 0xffff0000, v178
	v_lshlrev_b32_e32 v216, 16, v179
	v_and_b32_e32 v217, 0xffff0000, v179
	v_pk_fma_f32 v[160:161], v[26:27], v[10:11], v[214:215]
	v_pk_fma_f32 v[162:163], v[28:29], v[12:13], v[216:217]
	global_store_dwordx4 v[158:159], v[160:163], off offset:64
	s_waitcnt vmcnt(7)
	v_lshlrev_b32_e32 v214, 16, v180
	v_and_b32_e32 v215, 0xffff0000, v180
	v_lshlrev_b32_e32 v216, 16, v181
	v_and_b32_e32 v217, 0xffff0000, v181
	v_pk_fma_f32 v[218:219], v[22:23], v[6:7], v[214:215]
	v_pk_fma_f32 v[220:221], v[24:25], v[8:9], v[216:217]
	global_store_dwordx4 v[158:159], v[218:221], off offset:512
	s_waitcnt vmcnt(7)
	v_lshlrev_b32_e32 v214, 16, v182
	v_and_b32_e32 v215, 0xffff0000, v182
	v_lshlrev_b32_e32 v216, 16, v183
	v_and_b32_e32 v217, 0xffff0000, v183
	v_pk_fma_f32 v[160:161], v[18:19], v[2:3], v[214:215]
	v_pk_fma_f32 v[162:163], v[20:21], v[4:5], v[216:217]
	global_store_dwordx4 v[158:159], v[160:163], off offset:576
	s_mov_b64 s[2:3], 0
.LBB0_1065:
	s_andn2_b64 vcc, exec, s[2:3]
	s_cbranch_vccnz .LBB0_1067
	s_lshl_b64 s[2:3], s[0:1], 2
	s_add_u32 s2, s34, s2
	s_addc_u32 s3, s35, s3
	v_lshl_add_u64 v[214:215], v[150:151], 2, s[2:3]
	s_lshl_b64 s[0:1], s[0:1], 1
	s_add_u32 s0, s30, s0
	s_addc_u32 s1, s31, s1
	v_lshl_add_u64 v[216:217], v[150:151], 1, s[0:1]
	v_mov_b64_e32 v[218:219], v[214:215]
	global_load_dwordx4 v[148:151], v[218:219], off nt
	global_load_dwordx4 v[152:155], v[218:219], off offset:64 nt
	global_load_dwordx4 v[156:159], v[218:219], off offset:512 nt
	global_load_dwordx4 v[160:163], v[218:219], off offset:576 nt
	s_mov_b64 s[4:5], 0x10000
	v_lshl_add_u64 v[218:219], v[214:215], 0, s[4:5]
	global_load_dwordx4 v[164:167], v[218:219], off nt
	global_load_dwordx4 v[174:177], v[218:219], off offset:64 nt
	global_load_dwordx4 v[178:181], v[218:219], off offset:512 nt
	global_load_dwordx4 v[182:185], v[218:219], off offset:576 nt
	v_mov_b64_e32 v[220:221], v[216:217]
	s_waitcnt vmcnt(7)
	v_pk_fma_f32 v[148:149], v[138:139], v[14:15], v[148:149]
	v_pk_fma_f32 v[150:151], v[140:141], v[16:17], v[150:151]
	v_cvt_pk_bf16_f32 v222, v148, v149
	v_cvt_pk_bf16_f32 v223, v150, v151
	global_store_dwordx2 v[220:221], v[222:223], off
	s_waitcnt vmcnt(7)
	v_pk_fma_f32 v[152:153], v[142:143], v[10:11], v[152:153]
	v_pk_fma_f32 v[154:155], v[144:145], v[12:13], v[154:155]
	v_cvt_pk_bf16_f32 v146, v152, v153
	v_cvt_pk_bf16_f32 v147, v154, v155
	global_store_dwordx2 v[220:221], v[146:147], off offset:32
	s_waitcnt vmcnt(7)
	v_pk_fma_f32 v[156:157], v[134:135], v[6:7], v[156:157]
	v_pk_fma_f32 v[158:159], v[136:137], v[8:9], v[158:159]
	v_cvt_pk_bf16_f32 v222, v156, v157
	v_cvt_pk_bf16_f32 v223, v158, v159
	global_store_dwordx2 v[220:221], v[222:223], off offset:256
	s_waitcnt vmcnt(7)
	v_pk_fma_f32 v[160:161], v[130:131], v[2:3], v[160:161]
	v_pk_fma_f32 v[162:163], v[132:133], v[4:5], v[162:163]
	v_cvt_pk_bf16_f32 v146, v160, v161
	v_cvt_pk_bf16_f32 v147, v162, v163
	global_store_dwordx2 v[220:221], v[146:147], off offset:288
	s_mov_b64 s[4:5], 0x20000
	v_lshl_add_u64 v[218:219], v[214:215], 0, s[4:5]
	global_load_dwordx4 v[148:151], v[218:219], off nt
	global_load_dwordx4 v[152:155], v[218:219], off offset:64 nt
	global_load_dwordx4 v[156:159], v[218:219], off offset:512 nt
	global_load_dwordx4 v[160:163], v[218:219], off offset:576 nt
	s_mov_b64 s[4:5], 0x8000
	v_lshl_add_u64 v[220:221], v[216:217], 0, s[4:5]
	s_waitcnt vmcnt(11)
	v_pk_fma_f32 v[164:165], v[126:127], v[14:15], v[164:165]
	v_pk_fma_f32 v[166:167], v[128:129], v[16:17], v[166:167]
	v_cvt_pk_bf16_f32 v222, v164, v165
	v_cvt_pk_bf16_f32 v223, v166, v167
	global_store_dwordx2 v[220:221], v[222:223], off
	s_waitcnt vmcnt(11)
	v_pk_fma_f32 v[174:175], v[122:123], v[10:11], v[174:175]
	v_pk_fma_f32 v[176:177], v[124:125], v[12:13], v[176:177]
	v_cvt_pk_bf16_f32 v146, v174, v175
	v_cvt_pk_bf16_f32 v147, v176, v177
	global_store_dwordx2 v[220:221], v[146:147], off offset:32
	s_waitcnt vmcnt(11)
; __device__ __forceinline__ u32x2 pk4bf(f32x4 y) { u32x2 r; r.x = cvt_pk_bf16(y[0], y[1]); r.y = cvt_pk_bf16(y[2], y[3]); return r; }
;     __device__ __forceinline__ void operator()(const f32x4 (&acc)[2][2][4][2], const Unit& u, int wr, int wc, int fr, int fq) const {
;     ...
;         if (relu2 == 2) { const float* bp = base + (size_t)t0 * 1024; bf16_t* op = (bf16_t*)out + (size_t)t0 * 1024;
;             PG8_RES_LOOP(b = *(const f32x4*)(bp + o2), *(u32x2*)(op + o2) = pk4bf(y)); }
	v_pk_fma_f32 v[178:179], v[118:119], v[6:7], v[178:179]
	v_pk_fma_f32 v[180:181], v[120:121], v[8:9], v[180:181]
	v_cvt_pk_bf16_f32 v222, v178, v179
	v_cvt_pk_bf16_f32 v223, v180, v181
	global_store_dwordx2 v[220:221], v[222:223], off offset:256
	s_waitcnt vmcnt(11)
	v_pk_fma_f32 v[182:183], v[114:115], v[2:3], v[182:183]
	v_pk_fma_f32 v[184:185], v[116:117], v[4:5], v[184:185]
	v_cvt_pk_bf16_f32 v146, v182, v183
	v_cvt_pk_bf16_f32 v147, v184, v185
	global_store_dwordx2 v[220:221], v[146:147], off offset:288
	s_mov_b64 s[4:5], 0x30000
	v_lshl_add_u64 v[218:219], v[214:215], 0, s[4:5]
	global_load_dwordx4 v[164:167], v[218:219], off nt
	global_load_dwordx4 v[174:177], v[218:219], off offset:64 nt
	global_load_dwordx4 v[178:181], v[218:219], off offset:512 nt
	global_load_dwordx4 v[182:185], v[218:219], off offset:576 nt
	s_mov_b64 s[4:5], 0x10000
	v_lshl_add_u64 v[220:221], v[216:217], 0, s[4:5]
	s_waitcnt vmcnt(11)
	v_pk_fma_f32 v[148:149], v[110:111], v[14:15], v[148:149]
	v_pk_fma_f32 v[150:151], v[112:113], v[16:17], v[150:151]
	v_cvt_pk_bf16_f32 v222, v148, v149
	v_cvt_pk_bf16_f32 v223, v150, v151
	global_store_dwordx2 v[220:221], v[222:223], off
	s_waitcnt vmcnt(11)
	v_pk_fma_f32 v[152:153], v[106:107], v[10:11], v[152:153]
	v_pk_fma_f32 v[154:155], v[108:109], v[12:13], v[154:155]
	v_cvt_pk_bf16_f32 v146, v152, v153
	v_cvt_pk_bf16_f32 v147, v154, v155
	global_store_dwordx2 v[220:221], v[146:147], off offset:32
	s_waitcnt vmcnt(11)
	v_pk_fma_f32 v[156:157], v[102:103], v[6:7], v[156:157]
	v_pk_fma_f32 v[158:159], v[104:105], v[8:9], v[158:159]
	v_cvt_pk_bf16_f32 v222, v156, v157
	v_cvt_pk_bf16_f32 v223, v158, v159
	global_store_dwordx2 v[220:221], v[222:223], off offset:256
	s_waitcnt vmcnt(11)
	v_pk_fma_f32 v[160:161], v[98:99], v[2:3], v[160:161]
	v_pk_fma_f32 v[162:163], v[100:101], v[4:5], v[162:163]
	v_cvt_pk_bf16_f32 v146, v160, v161
	v_cvt_pk_bf16_f32 v147, v162, v163
	global_store_dwordx2 v[220:221], v[146:147], off offset:288
	s_mov_b64 s[4:5], 0x80000
	v_lshl_add_u64 v[218:219], v[214:215], 0, s[4:5]
	global_load_dwordx4 v[148:151], v[218:219], off nt
	global_load_dwordx4 v[152:155], v[218:219], off offset:64 nt
	global_load_dwordx4 v[156:159], v[218:219], off offset:512 nt
	global_load_dwordx4 v[160:163], v[218:219], off offset:576 nt
	s_mov_b64 s[4:5], 0x18000
	v_lshl_add_u64 v[220:221], v[216:217], 0, s[4:5]
	s_waitcnt vmcnt(11)
	v_pk_fma_f32 v[164:165], v[94:95], v[14:15], v[164:165]
	v_pk_fma_f32 v[166:167], v[96:97], v[16:17], v[166:167]
	v_cvt_pk_bf16_f32 v222, v164, v165
	v_cvt_pk_bf16_f32 v223, v166, v167
	global_store_dwordx2 v[220:221], v[222:223], off
	s_waitcnt vmcnt(11)
	v_pk_fma_f32 v[174:175], v[90:91], v[10:11], v[174:175]
	v_pk_fma_f32 v[176:177], v[92:93], v[12:13], v[176:177]
	v_cvt_pk_bf16_f32 v146, v174, v175
	v_cvt_pk_bf16_f32 v147, v176, v177
	global_store_dwordx2 v[220:221], v[146:147], off offset:32
	s_waitcnt vmcnt(11)
	v_pk_fma_f32 v[178:179], v[86:87], v[6:7], v[178:179]
	v_pk_fma_f32 v[180:181], v[88:89], v[8:9], v[180:181]
	v_cvt_pk_bf16_f32 v222, v178, v179
	v_cvt_pk_bf16_f32 v223, v180, v181
	global_store_dwordx2 v[220:221], v[222:223], off offset:256
	s_waitcnt vmcnt(11)
	v_pk_fma_f32 v[182:183], v[82:83], v[2:3], v[182:183]
	v_pk_fma_f32 v[184:185], v[84:85], v[4:5], v[184:185]
	v_cvt_pk_bf16_f32 v146, v182, v183
	v_cvt_pk_bf16_f32 v147, v184, v185
	global_store_dwordx2 v[220:221], v[146:147], off offset:288
	s_mov_b64 s[4:5], 0x90000
	v_lshl_add_u64 v[218:219], v[214:215], 0, s[4:5]
	global_load_dwordx4 v[164:167], v[218:219], off nt
	global_load_dwordx4 v[174:177], v[218:219], off offset:64 nt
	global_load_dwordx4 v[178:181], v[218:219], off offset:512 nt
	global_load_dwordx4 v[182:185], v[218:219], off offset:576 nt
	s_mov_b64 s[4:5], 0x40000
	v_lshl_add_u64 v[220:221], v[216:217], 0, s[4:5]
	s_waitcnt vmcnt(11)
	v_pk_fma_f32 v[148:149], v[78:79], v[14:15], v[148:149]
	v_pk_fma_f32 v[150:151], v[80:81], v[16:17], v[150:151]
	v_cvt_pk_bf16_f32 v222, v148, v149
	v_cvt_pk_bf16_f32 v223, v150, v151
	global_store_dwordx2 v[220:221], v[222:223], off
	s_waitcnt vmcnt(11)
	v_pk_fma_f32 v[152:153], v[74:75], v[10:11], v[152:153]
	v_pk_fma_f32 v[154:155], v[76:77], v[12:13], v[154:155]
	v_cvt_pk_bf16_f32 v146, v152, v153
	v_cvt_pk_bf16_f32 v147, v154, v155
	global_store_dwordx2 v[220:221], v[146:147], off offset:32
	s_waitcnt vmcnt(11)
; __device__ __forceinline__ u32x2 pk4bf(f32x4 y) { u32x2 r; r.x = cvt_pk_bf16(y[0], y[1]); r.y = cvt_pk_bf16(y[2], y[3]); return r; }
;     __device__ __forceinline__ void operator()(const f32x4 (&acc)[2][2][4][2], const Unit& u, int wr, int wc, int fr, int fq) const {
;     ...
;         if (relu2 == 2) { const float* bp = base + (size_t)t0 * 1024; bf16_t* op = (bf16_t*)out + (size_t)t0 * 1024;
;             PG8_RES_LOOP(b = *(const f32x4*)(bp + o2), *(u32x2*)(op + o2) = pk4bf(y)); }
	v_pk_fma_f32 v[156:157], v[70:71], v[6:7], v[156:157]
	v_pk_fma_f32 v[158:159], v[72:73], v[8:9], v[158:159]
	v_cvt_pk_bf16_f32 v222, v156, v157
	v_cvt_pk_bf16_f32 v223, v158, v159
	global_store_dwordx2 v[220:221], v[222:223], off offset:256
	s_waitcnt vmcnt(11)
	v_pk_fma_f32 v[160:161], v[66:67], v[2:3], v[160:161]
	v_pk_fma_f32 v[162:163], v[68:69], v[4:5], v[162:163]
	v_cvt_pk_bf16_f32 v146, v160, v161
	v_cvt_pk_bf16_f32 v147, v162, v163
	global_store_dwordx2 v[220:221], v[146:147], off offset:288
	s_mov_b64 s[4:5], 0xa0000
	v_lshl_add_u64 v[218:219], v[214:215], 0, s[4:5]
	global_load_dwordx4 v[148:151], v[218:219], off nt
	global_load_dwordx4 v[152:155], v[218:219], off offset:64 nt
	global_load_dwordx4 v[156:159], v[218:219], off offset:512 nt
	global_load_dwordx4 v[160:163], v[218:219], off offset:576 nt
	s_mov_b64 s[4:5], 0x48000
	v_lshl_add_u64 v[220:221], v[216:217], 0, s[4:5]
	s_waitcnt vmcnt(11)
	v_pk_fma_f32 v[164:165], v[62:63], v[14:15], v[164:165]
	v_pk_fma_f32 v[166:167], v[64:65], v[16:17], v[166:167]
	v_cvt_pk_bf16_f32 v222, v164, v165
	v_cvt_pk_bf16_f32 v223, v166, v167
	global_store_dwordx2 v[220:221], v[222:223], off
	s_waitcnt vmcnt(11)
	v_pk_fma_f32 v[174:175], v[58:59], v[10:11], v[174:175]
	v_pk_fma_f32 v[176:177], v[60:61], v[12:13], v[176:177]
	v_cvt_pk_bf16_f32 v146, v174, v175
	v_cvt_pk_bf16_f32 v147, v176, v177
	global_store_dwordx2 v[220:221], v[146:147], off offset:32
	s_waitcnt vmcnt(11)
	v_pk_fma_f32 v[178:179], v[54:55], v[6:7], v[178:179]
	v_pk_fma_f32 v[180:181], v[56:57], v[8:9], v[180:181]
	v_cvt_pk_bf16_f32 v222, v178, v179
	v_cvt_pk_bf16_f32 v223, v180, v181
	global_store_dwordx2 v[220:221], v[222:223], off offset:256
	s_waitcnt vmcnt(11)
	v_pk_fma_f32 v[182:183], v[50:51], v[2:3], v[182:183]
	v_pk_fma_f32 v[184:185], v[52:53], v[4:5], v[184:185]
	v_cvt_pk_bf16_f32 v146, v182, v183
	v_cvt_pk_bf16_f32 v147, v184, v185
	global_store_dwordx2 v[220:221], v[146:147], off offset:288
	s_mov_b64 s[4:5], 0xb0000
	v_lshl_add_u64 v[218:219], v[214:215], 0, s[4:5]
	global_load_dwordx4 v[164:167], v[218:219], off nt
	global_load_dwordx4 v[174:177], v[218:219], off offset:64 nt
	global_load_dwordx4 v[178:181], v[218:219], off offset:512 nt
	global_load_dwordx4 v[182:185], v[218:219], off offset:576 nt
	s_mov_b64 s[4:5], 0x50000
	v_lshl_add_u64 v[220:221], v[216:217], 0, s[4:5]
	s_waitcnt vmcnt(11)
	v_pk_fma_f32 v[148:149], v[46:47], v[14:15], v[148:149]
	v_pk_fma_f32 v[150:151], v[48:49], v[16:17], v[150:151]
	v_cvt_pk_bf16_f32 v222, v148, v149
	v_cvt_pk_bf16_f32 v223, v150, v151
	global_store_dwordx2 v[220:221], v[222:223], off
	s_waitcnt vmcnt(11)
	v_pk_fma_f32 v[152:153], v[42:43], v[10:11], v[152:153]
	v_pk_fma_f32 v[154:155], v[44:45], v[12:13], v[154:155]
	v_cvt_pk_bf16_f32 v146, v152, v153
	v_cvt_pk_bf16_f32 v147, v154, v155
	global_store_dwordx2 v[220:221], v[146:147], off offset:32
	s_waitcnt vmcnt(11)
	v_pk_fma_f32 v[156:157], v[38:39], v[6:7], v[156:157]
	v_pk_fma_f32 v[158:159], v[40:41], v[8:9], v[158:159]
	v_cvt_pk_bf16_f32 v222, v156, v157
	v_cvt_pk_bf16_f32 v223, v158, v159
	global_store_dwordx2 v[220:221], v[222:223], off offset:256
	s_waitcnt vmcnt(11)
	v_pk_fma_f32 v[160:161], v[34:35], v[2:3], v[160:161]
	v_pk_fma_f32 v[162:163], v[36:37], v[4:5], v[162:163]
	v_cvt_pk_bf16_f32 v146, v160, v161
	v_cvt_pk_bf16_f32 v147, v162, v163
	global_store_dwordx2 v[220:221], v[146:147], off offset:288
	s_mov_b64 s[4:5], 0x58000
	v_lshl_add_u64 v[220:221], v[216:217], 0, s[4:5]
	s_waitcnt vmcnt(7)
	v_pk_fma_f32 v[164:165], v[30:31], v[14:15], v[164:165]
	v_pk_fma_f32 v[166:167], v[32:33], v[16:17], v[166:167]
	v_cvt_pk_bf16_f32 v222, v164, v165
	v_cvt_pk_bf16_f32 v223, v166, v167
	global_store_dwordx2 v[220:221], v[222:223], off
	s_waitcnt vmcnt(7)
	v_pk_fma_f32 v[174:175], v[26:27], v[10:11], v[174:175]
	v_pk_fma_f32 v[176:177], v[28:29], v[12:13], v[176:177]
	v_cvt_pk_bf16_f32 v146, v174, v175
	v_cvt_pk_bf16_f32 v147, v176, v177
	global_store_dwordx2 v[220:221], v[146:147], off offset:32
	s_waitcnt vmcnt(7)
	v_pk_fma_f32 v[178:179], v[22:23], v[6:7], v[178:179]
	v_pk_fma_f32 v[180:181], v[24:25], v[8:9], v[180:181]
	v_cvt_pk_bf16_f32 v222, v178, v179
	v_cvt_pk_bf16_f32 v223, v180, v181
	global_store_dwordx2 v[220:221], v[222:223], off offset:256
	s_waitcnt vmcnt(7)
	v_pk_fma_f32 v[182:183], v[18:19], v[2:3], v[182:183]
	v_pk_fma_f32 v[184:185], v[20:21], v[4:5], v[184:185]
	v_cvt_pk_bf16_f32 v146, v182, v183
	v_cvt_pk_bf16_f32 v147, v184, v185
	global_store_dwordx2 v[220:221], v[146:147], off offset:288
	s_mov_b64 s[0:1], 0
	s_branch .LBB0_1068

; #define GAS __attribute__((address_space(1)))
;     ...
;     for (int m = gw; m < nrows; m += NGW) {
;         const float* xrow = m < ML ? src_lat + (size_t)m * DM : src_ctx + (size_t)(m - ML) * DM;
;         const int cnd = m < SEQ ? 0 : (m < ML ? 1 : 2);
;         const GAS f32x4* xr = (const GAS f32x4*)xrow + F.lane;
;         f32x4 v[4]; float s = 0.f;
;         if (lat_bf16 && m < ML) {
;             const GAS v2u* xb = (const GAS v2u*)((const bf16*)src_lat + (size_t)m * DM) + F.lane;
;             v2u w[4];
; #pragma unroll
;             for (int j = 0; j < 4; ++j) w[j] = xb[64 * j];
; #pragma unroll
;             for (int j = 0; j < 4; ++j) v[j] = f32x4{bflo(w[j].x), bfhi(w[j].x), bflo(w[j].y), bfhi(w[j].y)};
;         } else {
; #pragma unroll
;             for (int j = 0; j < 4; ++j) v[j] = xr[64 * j];
;         }
;         if (nparts > 0 && m >= ML) {
;             for (int p = 0; p < nparts; p += 4) {
;                 const GAS f32x4* pr = (const GAS f32x4*)(parts + (size_t)p * (512 * 1024) + (size_t)(m - ML) * DM) + F.lane;
;                 f32x4 w[4][4];
; #pragma unroll
;                 for (int q = 0; q < 4; ++q)
; #pragma unroll
;                     for (int j = 0; j < 4; ++j) w[q][j] = pr[(size_t)q * (512 * 1024 / 4) + 64 * j];
; #pragma unroll
;                 for (int j = 0; j < 4; ++j) v[j] += (w[0][j] + w[1][j]) + (w[2][j] + w[3][j]); }
;             GAS f32x4* cr = (GAS f32x4*)((float*)(F.ws + WS_CTXRES) + (size_t)(m - ML) * DM) + F.lane;
; #pragma unroll
;             for (int j = 0; j < 4; ++j) cr[64 * j] = v[j];
;         }
; #pragma unroll
;         for (int j = 0; j < 4; ++j) s += (v[j].x * v[j].x + v[j].y * v[j].y) + (v[j].z * v[j].z + v[j].w * v[j].w);
;         const float rstd = 1.f / sqrtf(wave_sum(s, F.lane) * (1.f / DM) + NORM_EPS);
;         if (from_partials && m >= ML) { GAS f32x4* cr = (GAS f32x4*)((float*)(F.ws + WS_CTXRES) + (size_t)(m - ML) * DM) + F.lane;
; #pragma unroll
;             for (int j = 0; j < 4; ++j) cr[64 * j] = v[j]; }
.LBB0_1122:
	v_readlane_b32 s4, v243, 9
	s_add_i32 s12, s0, 0xffffc000
	v_readlane_b32 s5, v243, 10
	s_cmpk_lt_i32 s0, 0x4000
	s_mov_b32 s13, s5
	s_cselect_b64 s[4:5], -1, 0
	v_readlane_b32 s8, v243, 27
	v_readlane_b32 s14, v243, 25
	s_and_b64 vcc, s[4:5], exec
	v_readlane_b32 s9, v243, 28
	v_readlane_b32 s15, v243, 26
	s_cselect_b32 s10, s9, s15
	s_cselect_b32 s11, s8, s14
	s_cselect_b32 s9, s1, 0
	v_writelane_b32 v243, s12, 9
	s_cselect_b32 s8, s0, s12
	s_lshl_b64 s[8:9], s[8:9], 12
	s_add_u32 s8, s11, s8
	s_addc_u32 s9, s10, s9
	global_load_dwordx4 v[30:33], v0, s[8:9] nt
	global_load_dwordx4 v[26:29], v0, s[8:9] offset:1024 nt
	global_load_dwordx4 v[22:25], v0, s[8:9] offset:2048 nt
	global_load_dwordx4 v[18:21], v0, s[8:9] offset:3072 nt
	v_writelane_b32 v243, s13, 10
	s_waitcnt vmcnt(3)
	v_mul_f32_e32 v39, v31, v31
	v_mul_f32_e32 v40, v33, v33
	s_waitcnt vmcnt(2)
	v_mul_f32_e32 v41, v27, v27
	v_mul_f32_e32 v42, v29, v29
	s_waitcnt vmcnt(1)
	v_mul_f32_e32 v43, v23, v23
	v_mul_f32_e32 v44, v25, v25
	v_fmac_f32_e32 v39, v30, v30
	v_fmac_f32_e32 v40, v32, v32
	v_fmac_f32_e32 v41, v26, v26
	v_fmac_f32_e32 v42, v28, v28
	s_waitcnt vmcnt(0)
	v_mul_f32_e32 v45, v19, v19
	v_mul_f32_e32 v46, v21, v21
	v_fmac_f32_e32 v43, v22, v22
	v_fmac_f32_e32 v44, v24, v24
	v_add_f32_e32 v39, v39, v40
	v_add_f32_e32 v40, v41, v42
	v_fmac_f32_e32 v45, v18, v18
	v_fmac_f32_e32 v46, v20, v20
	v_add_f32_e32 v41, v43, v44
	v_add_f32_e32 v39, v39, v40
	v_add_f32_e32 v42, v45, v46
	v_add_f32_e32 v39, v39, v41
	v_add_f32_e32 v39, v39, v42
	s_nop 1
	v_add_f32_dpp v39, v39, v39 row_ror:8 row_mask:0xf bank_mask:0xf bound_ctrl:1
	s_nop 1
	v_add_f32_dpp v39, v39, v39 row_ror:4 row_mask:0xf bank_mask:0xf bound_ctrl:1
	s_nop 1
	v_add_f32_dpp v39, v39, v39 row_ror:2 row_mask:0xf bank_mask:0xf bound_ctrl:1
	s_nop 1
	v_add_f32_dpp v39, v39, v39 row_ror:1 row_mask:0xf bank_mask:0xf bound_ctrl:1
	s_nop 0
	v_readlane_b32 s8, v39, 0
	v_readlane_b32 s10, v39, 16
	v_readlane_b32 s9, v39, 32
	v_readlane_b32 s11, v39, 48
	s_cbranch_vccnz .LBB0_1121
	v_readlane_b32 s12, v243, 9
	v_readlane_b32 s13, v243, 10
	s_lshl_b64 s[12:13], s[12:13], 12
	s_nop 0
	v_lshl_add_u64 v[40:41], v[34:35], 0, s[12:13]
	global_store_dwordx4 v[40:41], v[30:33], off
	global_store_dwordx4 v[40:41], v[26:29], off offset:1024
	global_store_dwordx4 v[40:41], v[22:25], off offset:2048
	global_store_dwordx4 v[40:41], v[18:21], off offset:3072
	s_branch .LBB0_1121

; #define LDS_WAIT() asm volatile("s_waitcnt lgkmcnt(0)" ::: "memory")
; __device__ __forceinline__ void p0_transpose_item(const float* W, int K, int N, bf16* WT, int pmode, LAS float* scr, int item, int lane, bool f8 = false) {
;     const int nblk = N / 32, kb = item / nblk, nb = item % nblk, k0 = 64 * kb, n0 = 32 * nb;
;     int r0 = n0;
;     if (pmode == 1) { const int h = n0 / 96, d = n0 % 96; r0 = d < 64 ? h * 64 + d : 1024 + h * 32 + (d - 64); }
;     else if (pmode == 2) { const int h = n0 / 128, d = n0 % 128; r0 = d < 64 ? h * 64 + d : 1024 + h * 64 + (d - 64); }
; #pragma unroll 8
;     for (int i = 0; i < 32; ++i) { const int kk = 2 * i + (lane >> 5); scr[kk * 33 + (lane & 31)] = W[(size_t)(k0 + kk) * N + n0 + (lane & 31)]; }
;     LDS_WAIT(); asm volatile("" ::: "memory");
.LBB0_1141:
	s_lshl_b32 s10, s7, 1
	s_lshl_b32 s9, s4, 1
	v_or_b32_e32 v56, s10, v2
	s_add_i32 s12, s10, 4
	s_add_i32 s11, s9, 4
	s_add_i32 s13, s9, 8
	s_add_i32 s14, s10, 8
	v_add_u32_e32 v0, s1, v56
	v_or_b32_e32 v58, s12, v2
	v_or_b32_e32 v33, s9, v3
	s_add_i32 s15, s9, 12
	s_add_i32 s16, s10, 12
	s_add_i32 s17, s9, 16
	s_add_i32 s19, s9, 20
	s_add_i32 s21, s9, 24
	s_add_i32 s9, s9, 28
	v_or_b32_e32 v57, s11, v3
	v_or_b32_e32 v59, s13, v3
	v_or_b32_e32 v60, s14, v2
	v_lshlrev_b64 v[50:51], 12, v[0:1]
	v_add_u32_e32 v0, s1, v58
	v_mov_b32_e32 v35, v1
	v_mov_b32_e32 v37, v1
	v_mov_b32_e32 v39, v1
	s_add_i32 s18, s10, 16
	v_add_u32_e32 v34, s5, v33
	v_or_b32_e32 v61, s15, v3
	v_or_b32_e32 v62, s16, v2
	v_or_b32_e32 v63, s17, v3
	v_or_b32_e32 v65, s19, v3
	v_or_b32_e32 v67, s21, v3
	v_or_b32_e32 v69, s9, v3
	v_add_u32_e32 v36, s5, v57
	v_add_u32_e32 v38, s5, v59
	v_lshlrev_b64 v[52:53], 12, v[0:1]
	v_add_u32_e32 v0, s1, v60
	v_mov_b32_e32 v41, v1
	v_mov_b32_e32 v43, v1
	v_mov_b32_e32 v45, v1
	v_mov_b32_e32 v47, v1
	v_mov_b32_e32 v49, v1
	s_add_i32 s20, s10, 20
	v_or_b32_e32 v64, s18, v2
	v_lshlrev_b64 v[34:35], 12, v[34:35]
	v_add_u32_e32 v40, s5, v61
	v_add_u32_e32 v42, s5, v63
	v_add_u32_e32 v44, s5, v65
	v_add_u32_e32 v46, s5, v67
	v_add_u32_e32 v48, s5, v69
	v_lshl_add_u64 v[50:51], v[28:29], 0, v[50:51]
	v_lshlrev_b64 v[36:37], 12, v[36:37]
	v_lshlrev_b64 v[38:39], 12, v[38:39]
	v_lshlrev_b64 v[54:55], 12, v[0:1]
	v_add_u32_e32 v0, s1, v62
	s_add_i32 s22, s10, 24
	v_or_b32_e32 v66, s20, v2
	v_lshl_add_u64 v[34:35], v[28:29], 0, v[34:35]
	v_lshlrev_b64 v[40:41], 12, v[40:41]
	v_lshlrev_b64 v[42:43], 12, v[42:43]
	v_lshlrev_b64 v[44:45], 12, v[44:45]
	v_lshlrev_b64 v[46:47], 12, v[46:47]
	v_lshlrev_b64 v[48:49], 12, v[48:49]
	v_lshl_add_u64 v[52:53], v[28:29], 0, v[52:53]
	v_lshl_add_u64 v[36:37], v[28:29], 0, v[36:37]
	v_lshl_add_u64 v[38:39], v[28:29], 0, v[38:39]
	global_load_dword v71, v[50:51], off nt
	global_load_dword v72, v[34:35], off nt
	v_lshlrev_b64 v[50:51], 12, v[0:1]
	v_add_u32_e32 v0, s1, v64
	s_add_i32 s10, s10, 28
	v_or_b32_e32 v68, s22, v2
	v_lshl_add_u64 v[40:41], v[28:29], 0, v[40:41]
	v_lshl_add_u64 v[42:43], v[28:29], 0, v[42:43]
	v_lshl_add_u64 v[44:45], v[28:29], 0, v[44:45]
	v_lshl_add_u64 v[46:47], v[28:29], 0, v[46:47]
	v_lshl_add_u64 v[48:49], v[28:29], 0, v[48:49]
	global_load_dword v73, v[52:53], off nt
	global_load_dword v74, v[36:37], off nt
	global_load_dword v75, v[38:39], off nt
	global_load_dword v76, v[40:41], off nt
	global_load_dword v77, v[42:43], off nt
	global_load_dword v78, v[44:45], off nt
	global_load_dword v79, v[46:47], off nt
	global_load_dword v80, v[48:49], off nt
	v_lshl_add_u64 v[36:37], v[28:29], 0, v[50:51]
	v_lshlrev_b64 v[38:39], 12, v[0:1]
	v_add_u32_e32 v0, s1, v66
	v_or_b32_e32 v70, s10, v2
	v_lshl_add_u64 v[34:35], v[28:29], 0, v[54:55]
	global_load_dword v81, v[36:37], off nt
	global_load_dword v82, v[34:35], off nt
	v_lshlrev_b64 v[36:37], 12, v[0:1]
	v_add_u32_e32 v0, s1, v68
	v_lshl_add_u64 v[34:35], v[28:29], 0, v[38:39]
	v_lshlrev_b64 v[38:39], 12, v[0:1]
	v_add_u32_e32 v0, s1, v70
	v_lshlrev_b64 v[40:41], 12, v[0:1]
	v_lshl_add_u64 v[40:41], v[28:29], 0, v[40:41]
	v_lshl_add_u64 v[36:37], v[28:29], 0, v[36:37]
	v_lshl_add_u64 v[38:39], v[28:29], 0, v[38:39]
	global_load_dword v0, v[40:41], off nt
	global_load_dword v83, v[38:39], off nt
	global_load_dword v84, v[36:37], off nt
	global_load_dword v85, v[34:35], off nt
	s_add_i32 s7, s7, 16
	s_add_i32 s4, s4, 16
	s_add_i32 s8, s8, -16
	v_mad_u64_u32 v[34:35], s[10:11], v56, s33, v[6:7]
	s_cmp_lg_u32 s8, 0
	v_mad_u64_u32 v[36:37], s[10:11], v33, s33, v[6:7]
	v_mad_u64_u32 v[38:39], s[10:11], v58, s33, v[6:7]
	v_mad_u64_u32 v[40:41], s[10:11], v57, s33, v[6:7]
	v_mad_u64_u32 v[42:43], s[10:11], v60, s33, v[6:7]
	v_mad_u64_u32 v[44:45], s[10:11], v59, s33, v[6:7]
	v_mad_u64_u32 v[46:47], s[10:11], v62, s33, v[6:7]
	v_mad_u64_u32 v[48:49], s[10:11], v61, s33, v[6:7]
	v_mad_u64_u32 v[50:51], s[10:11], v64, s33, v[6:7]
	v_mad_u64_u32 v[52:53], s[10:11], v63, s33, v[6:7]
	v_mad_u64_u32 v[54:55], s[10:11], v66, s33, v[6:7]
	v_mad_u64_u32 v[56:57], s[10:11], v65, s33, v[6:7]
	v_mad_u64_u32 v[58:59], s[10:11], v68, s33, v[6:7]
	v_mad_u64_u32 v[60:61], s[10:11], v67, s33, v[6:7]
	v_mad_u64_u32 v[62:63], s[10:11], v70, s33, v[6:7]
	v_mad_u64_u32 v[64:65], s[10:11], v69, s33, v[6:7]
	s_waitcnt vmcnt(15)
	ds_write_b32 v34, v71
	s_waitcnt vmcnt(14)
	ds_write_b32 v36, v72
	s_waitcnt vmcnt(13)
	ds_write_b32 v38, v73
	s_waitcnt vmcnt(12)
	ds_write_b32 v40, v74
	s_waitcnt vmcnt(4)
	ds_write_b32 v42, v82
	ds_write_b32 v44, v75
	ds_write_b32 v46, v81
	ds_write_b32 v48, v76
	s_waitcnt vmcnt(0)
	ds_write_b32 v50, v85
	ds_write_b32 v52, v77
	ds_write_b32 v54, v84
	ds_write_b32 v56, v78
	ds_write_b32 v58, v83
	ds_write_b32 v60, v79
	ds_write_b32 v62, v0
	ds_write_b32 v64, v80
	s_cbranch_scc1 .LBB0_1141
; #define GAS __attribute__((address_space(1)))
; #define LAS __attribute__((address_space(3)))
; #define LDS_WAIT() asm volatile("s_waitcnt lgkmcnt(0)" ::: "memory")
; __device__ __forceinline__ unsigned pk2(float lo, float hi) { return f2bf(lo) | (f2bf(hi) << 16); }
; __device__ __forceinline__ unsigned pk4f8(float a, float b, float c, float d) { int w = 0; w = __builtin_amdgcn_cvt_pk_fp8_f32(a, b, w, false); w = __builtin_amdgcn_cvt_pk_fp8_f32(c, d, w, true); return (unsigned)w; }
; __device__ __forceinline__ void p0_transpose_item(const float* W, int K, int N, bf16* WT, int pmode, LAS float* scr, int item, int lane, bool f8 = false) {
;     ...
;     const int c = lane & 7;
; #pragma unroll
;     for (int j = 0; j < 4; ++j) { const int n = (lane >> 3) + 8 * j; const LAS float* s = scr + (8 * c) * 33 + n;
;         if (f8) {
;             v2u o; o.x = pk4f8(s[0 * 33] * 32.f, s[1 * 33] * 32.f, s[2 * 33] * 32.f, s[3 * 33] * 32.f); o.y = pk4f8(s[4 * 33] * 32.f, s[5 * 33] * 32.f, s[6 * 33] * 32.f, s[7 * 33] * 32.f);
;             *(GAS v2u*)((unsigned char*)WT + (size_t)(r0 + n) * K + k0 + 8 * c) = o; continue; }
;         v4u o; o.x = pk2(s[0 * 33], s[1 * 33]); o.y = pk2(s[2 * 33], s[3 * 33]); o.z = pk2(s[4 * 33], s[5 * 33]); o.w = pk2(s[6 * 33], s[7 * 33]);
;         *(GAS v4u*)(WT + (size_t)(r0 + n) * K + k0 + 8 * c) = o; }
;     LDS_WAIT(); asm volatile("" ::: "memory");
	s_waitcnt lgkmcnt(0)
	ds_read2_b32 v[28:29], v7 offset1:8
	ds_read2_b32 v[40:41], v7 offset0:33 offset1:41
	ds_read2_b32 v[42:43], v7 offset0:66 offset1:74
	v_readlane_b32 s4, v243, 9
	v_readlane_b32 s5, v243, 10
	s_lshl_b32 s4, s1, 1
	ds_read2_b32 v[44:45], v7 offset0:99 offset1:107
	s_mov_b32 s1, s5
	v_lshl_add_u64 v[38:39], v[8:9], 0, s[4:5]
	s_waitcnt lgkmcnt(3)
	v_bfe_u32 v0, v28, 16, 1
	s_movk_i32 s4, 0x7fff
	v_writelane_b32 v243, s0, 9
	v_add3_u32 v0, v28, v0, s4
	s_waitcnt lgkmcnt(2)
	v_bfe_u32 v28, v40, 16, 1
	ds_read2_b32 v[46:47], v7 offset0:132 offset1:140
	v_writelane_b32 v243, s1, 10
	v_lshrrev_b32_e32 v0, 16, v0
	v_add3_u32 v28, v40, v28, s4
	s_mov_b32 s1, 0xffff0000
	ds_read2_b32 v[48:49], v7 offset0:165 offset1:173
	v_and_or_b32 v34, v28, s1, v0
	s_waitcnt lgkmcnt(3)
	v_bfe_u32 v0, v42, 16, 1
	v_add3_u32 v0, v42, v0, s4
	s_waitcnt lgkmcnt(2)
	v_bfe_u32 v28, v44, 16, 1
	ds_read2_b32 v[50:51], v7 offset0:198 offset1:206
	v_lshrrev_b32_e32 v0, 16, v0
	v_add3_u32 v28, v44, v28, s4
	ds_read2_b32 v[52:53], v7 offset0:231 offset1:239
	v_and_or_b32 v35, v28, s1, v0
	s_waitcnt lgkmcnt(3)
	v_bfe_u32 v0, v46, 16, 1
	v_add3_u32 v0, v46, v0, s4
	s_waitcnt lgkmcnt(2)
	v_bfe_u32 v28, v48, 16, 1
	v_lshrrev_b32_e32 v0, 16, v0
	v_add3_u32 v28, v48, v28, s4
	v_and_or_b32 v36, v28, s1, v0
	s_waitcnt lgkmcnt(1)
	v_bfe_u32 v0, v50, 16, 1
	v_add3_u32 v0, v50, v0, s4
	s_waitcnt lgkmcnt(0)
	v_bfe_u32 v28, v52, 16, 1
	v_lshrrev_b32_e32 v0, 16, v0
	v_add3_u32 v28, v52, v28, s4
	v_and_or_b32 v37, v28, s1, v0
	v_or_b32_e32 v0, s0, v5
	v_lshlrev_b32_e32 v0, 11, v0
	v_lshl_add_u64 v[54:55], v[38:39], 0, v[0:1]
	v_bfe_u32 v0, v29, 16, 1
	v_add3_u32 v0, v29, v0, s4
	v_bfe_u32 v28, v41, 16, 1
	v_lshrrev_b32_e32 v0, 16, v0
	v_add3_u32 v28, v41, v28, s4
	global_store_dwordx4 v[54:55], v[34:37], off
	s_nop 1
	v_and_or_b32 v34, v28, s1, v0
	v_bfe_u32 v0, v43, 16, 1
	v_add3_u32 v0, v43, v0, s4
	v_bfe_u32 v28, v45, 16, 1
	v_lshrrev_b32_e32 v0, 16, v0
	v_add3_u32 v28, v45, v28, s4
	v_and_or_b32 v35, v28, s1, v0
	v_bfe_u32 v0, v47, 16, 1
	v_add3_u32 v0, v47, v0, s4
	v_bfe_u32 v28, v49, 16, 1
	v_lshrrev_b32_e32 v0, 16, v0
	v_add3_u32 v28, v49, v28, s4
	v_and_or_b32 v36, v28, s1, v0
	v_bfe_u32 v0, v51, 16, 1
	v_add3_u32 v0, v51, v0, s4
	v_bfe_u32 v28, v53, 16, 1
	v_lshrrev_b32_e32 v0, 16, v0
	v_add3_u32 v28, v53, v28, s4
	v_and_or_b32 v37, v28, s1, v0
	v_or_b32_e32 v0, s0, v30
	v_lshlrev_b32_e32 v0, 11, v0
	ds_read2_b32 v[28:29], v7 offset0:16 offset1:24
	v_lshl_add_u64 v[40:41], v[38:39], 0, v[0:1]
	global_store_dwordx4 v[40:41], v[34:37], off
	ds_read2_b32 v[40:41], v7 offset0:49 offset1:57
	ds_read2_b32 v[42:43], v7 offset0:82 offset1:90
	ds_read2_b32 v[44:45], v7 offset0:115 offset1:123
	s_waitcnt lgkmcnt(3)
	v_bfe_u32 v0, v28, 16, 1
	v_add3_u32 v0, v28, v0, s4
	s_waitcnt lgkmcnt(2)
	v_bfe_u32 v28, v40, 16, 1
	ds_read2_b32 v[46:47], v7 offset0:148 offset1:156
	v_lshrrev_b32_e32 v0, 16, v0
	v_add3_u32 v28, v40, v28, s4
	ds_read2_b32 v[48:49], v7 offset0:181 offset1:189
	v_and_or_b32 v34, v28, s1, v0
	s_waitcnt lgkmcnt(3)
	v_bfe_u32 v0, v42, 16, 1
	v_add3_u32 v0, v42, v0, s4
	s_waitcnt lgkmcnt(2)
	v_bfe_u32 v28, v44, 16, 1
	ds_read2_b32 v[50:51], v7 offset0:214 offset1:222
	v_lshrrev_b32_e32 v0, 16, v0
	v_add3_u32 v28, v44, v28, s4
	ds_read2_b32 v[52:53], v7 offset0:247 offset1:255
	v_and_or_b32 v35, v28, s1, v0
	s_waitcnt lgkmcnt(3)
	v_bfe_u32 v0, v46, 16, 1
	v_add3_u32 v0, v46, v0, s4
	s_waitcnt lgkmcnt(2)
	v_bfe_u32 v28, v48, 16, 1
	v_lshrrev_b32_e32 v0, 16, v0
	v_add3_u32 v28, v48, v28, s4
	v_and_or_b32 v36, v28, s1, v0
	s_waitcnt lgkmcnt(1)
	v_bfe_u32 v0, v50, 16, 1
	v_add3_u32 v0, v50, v0, s4
	s_waitcnt lgkmcnt(0)
	v_bfe_u32 v28, v52, 16, 1
	v_lshrrev_b32_e32 v0, 16, v0
	v_add3_u32 v28, v52, v28, s4
	v_and_or_b32 v37, v28, s1, v0
	v_or_b32_e32 v0, s0, v31
	v_lshlrev_b32_e32 v0, 11, v0
	v_lshl_add_u64 v[54:55], v[38:39], 0, v[0:1]
	v_bfe_u32 v0, v29, 16, 1
	v_add3_u32 v0, v29, v0, s4
	v_bfe_u32 v28, v41, 16, 1
	v_lshrrev_b32_e32 v0, 16, v0
	v_add3_u32 v28, v41, v28, s4
	global_store_dwordx4 v[54:55], v[34:37], off
	s_nop 1
	v_and_or_b32 v34, v28, s1, v0
	v_bfe_u32 v0, v43, 16, 1
	v_add3_u32 v0, v43, v0, s4
	v_bfe_u32 v28, v45, 16, 1
	v_lshrrev_b32_e32 v0, 16, v0
	v_add3_u32 v28, v45, v28, s4
	v_and_or_b32 v35, v28, s1, v0
	v_bfe_u32 v0, v47, 16, 1
	v_add3_u32 v0, v47, v0, s4
	v_bfe_u32 v28, v49, 16, 1
	v_lshrrev_b32_e32 v0, 16, v0
	v_add3_u32 v28, v49, v28, s4
	v_and_or_b32 v36, v28, s1, v0
	v_bfe_u32 v0, v51, 16, 1
	v_add3_u32 v0, v51, v0, s4
	v_bfe_u32 v28, v53, 16, 1
	v_lshrrev_b32_e32 v0, 16, v0
	v_add3_u32 v28, v53, v28, s4
	v_and_or_b32 v37, v28, s1, v0
	v_or_b32_e32 v0, s0, v32
	v_lshlrev_b32_e32 v0, 11, v0
	v_lshl_add_u64 v[28:29], v[38:39], 0, v[0:1]
	global_store_dwordx4 v[28:29], v[34:37], off
	s_waitcnt lgkmcnt(0)
	s_mov_b64 s[0:1], 0

; #define LDS_WAIT() asm volatile("s_waitcnt lgkmcnt(0)" ::: "memory")
; __device__ __forceinline__ void p0_transpose_item(const float* W, int K, int N, bf16* WT, int pmode, LAS float* scr, int item, int lane, bool f8 = false) {
;     const int nblk = N / 32, kb = item / nblk, nb = item % nblk, k0 = 64 * kb, n0 = 32 * nb;
;     int r0 = n0;
;     if (pmode == 1) { const int h = n0 / 96, d = n0 % 96; r0 = d < 64 ? h * 64 + d : 1024 + h * 32 + (d - 64); }
;     else if (pmode == 2) { const int h = n0 / 128, d = n0 % 128; r0 = d < 64 ? h * 64 + d : 1024 + h * 64 + (d - 64); }
; #pragma unroll 8
;     for (int i = 0; i < 32; ++i) { const int kk = 2 * i + (lane >> 5); scr[kk * 33 + (lane & 31)] = W[(size_t)(k0 + kk) * N + n0 + (lane & 31)]; }
;     LDS_WAIT(); asm volatile("" ::: "memory");
.LBB0_1145:
	s_lshl_b32 s11, s8, 1
	s_lshl_b32 s10, s7, 1
	v_or_b32_e32 v56, s11, v2
	s_add_i32 s13, s11, 4
	s_add_i32 s12, s10, 4
	s_add_i32 s14, s10, 8
	s_add_i32 s15, s11, 8
	v_add_u32_e32 v0, s0, v56
	v_or_b32_e32 v58, s13, v2
	v_or_b32_e32 v33, s10, v3
	s_add_i32 s16, s10, 12
	s_add_i32 s17, s11, 12
	s_add_i32 s18, s10, 16
	s_add_i32 s20, s10, 20
	s_add_i32 s22, s10, 24
	s_add_i32 s10, s10, 28
	v_or_b32_e32 v57, s12, v3
	v_or_b32_e32 v59, s14, v3
	v_or_b32_e32 v60, s15, v2
	v_lshlrev_b64 v[50:51], 13, v[0:1]
	v_add_u32_e32 v0, s0, v58
	v_mov_b32_e32 v35, v1
	v_mov_b32_e32 v37, v1
	v_mov_b32_e32 v39, v1
	s_add_i32 s19, s11, 16
	v_add_u32_e32 v34, s5, v33
	v_or_b32_e32 v61, s16, v3
	v_or_b32_e32 v62, s17, v2
	v_or_b32_e32 v63, s18, v3
	v_or_b32_e32 v65, s20, v3
	v_or_b32_e32 v67, s22, v3
	v_or_b32_e32 v69, s10, v3
	v_add_u32_e32 v36, s5, v57
	v_add_u32_e32 v38, s5, v59
	v_lshlrev_b64 v[52:53], 13, v[0:1]
	v_add_u32_e32 v0, s0, v60
	v_mov_b32_e32 v41, v1
	v_mov_b32_e32 v43, v1
	v_mov_b32_e32 v45, v1
	v_mov_b32_e32 v47, v1
	v_mov_b32_e32 v49, v1
	s_add_i32 s21, s11, 20
	v_or_b32_e32 v64, s19, v2
	v_lshlrev_b64 v[34:35], 13, v[34:35]
	v_add_u32_e32 v40, s5, v61
	v_add_u32_e32 v42, s5, v63
	v_add_u32_e32 v44, s5, v65
	v_add_u32_e32 v46, s5, v67
	v_add_u32_e32 v48, s5, v69
	v_lshl_add_u64 v[50:51], v[28:29], 0, v[50:51]
	v_lshlrev_b64 v[36:37], 13, v[36:37]
	v_lshlrev_b64 v[38:39], 13, v[38:39]
	v_lshlrev_b64 v[54:55], 13, v[0:1]
	v_add_u32_e32 v0, s0, v62
	s_add_i32 s23, s11, 24
	v_or_b32_e32 v66, s21, v2
	v_lshl_add_u64 v[34:35], v[28:29], 0, v[34:35]
	v_lshlrev_b64 v[40:41], 13, v[40:41]
	v_lshlrev_b64 v[42:43], 13, v[42:43]
	v_lshlrev_b64 v[44:45], 13, v[44:45]
	v_lshlrev_b64 v[46:47], 13, v[46:47]
	v_lshlrev_b64 v[48:49], 13, v[48:49]
	v_lshl_add_u64 v[52:53], v[28:29], 0, v[52:53]
	v_lshl_add_u64 v[36:37], v[28:29], 0, v[36:37]
	v_lshl_add_u64 v[38:39], v[28:29], 0, v[38:39]
	global_load_dword v71, v[50:51], off nt
	global_load_dword v72, v[34:35], off nt
	v_lshlrev_b64 v[50:51], 13, v[0:1]
	v_add_u32_e32 v0, s0, v64
	s_add_i32 s11, s11, 28
	v_or_b32_e32 v68, s23, v2
	v_lshl_add_u64 v[40:41], v[28:29], 0, v[40:41]
	v_lshl_add_u64 v[42:43], v[28:29], 0, v[42:43]
	v_lshl_add_u64 v[44:45], v[28:29], 0, v[44:45]
	v_lshl_add_u64 v[46:47], v[28:29], 0, v[46:47]
	v_lshl_add_u64 v[48:49], v[28:29], 0, v[48:49]
	global_load_dword v73, v[52:53], off nt
	global_load_dword v74, v[36:37], off nt
	global_load_dword v75, v[38:39], off nt
	global_load_dword v76, v[40:41], off nt
	global_load_dword v77, v[42:43], off nt
	global_load_dword v78, v[44:45], off nt
	global_load_dword v79, v[46:47], off nt
	global_load_dword v80, v[48:49], off nt
	v_lshl_add_u64 v[36:37], v[28:29], 0, v[50:51]
	v_lshlrev_b64 v[38:39], 13, v[0:1]
	v_add_u32_e32 v0, s0, v66
	v_or_b32_e32 v70, s11, v2
	v_lshl_add_u64 v[34:35], v[28:29], 0, v[54:55]
	global_load_dword v81, v[36:37], off nt
	global_load_dword v82, v[34:35], off nt
	v_lshlrev_b64 v[36:37], 13, v[0:1]
	v_add_u32_e32 v0, s0, v68
	v_lshl_add_u64 v[34:35], v[28:29], 0, v[38:39]
	v_lshlrev_b64 v[38:39], 13, v[0:1]
	v_add_u32_e32 v0, s0, v70
	v_lshlrev_b64 v[40:41], 13, v[0:1]
	v_lshl_add_u64 v[40:41], v[28:29], 0, v[40:41]
	v_lshl_add_u64 v[36:37], v[28:29], 0, v[36:37]
	v_lshl_add_u64 v[38:39], v[28:29], 0, v[38:39]
	global_load_dword v0, v[40:41], off nt
	global_load_dword v83, v[38:39], off nt
	global_load_dword v84, v[36:37], off nt
	global_load_dword v85, v[34:35], off nt
	s_add_i32 s8, s8, 16
	s_add_i32 s7, s7, 16
	s_add_i32 s9, s9, -16
	v_mad_u64_u32 v[34:35], s[10:11], v56, s33, v[6:7]
	s_cmp_lg_u32 s9, 0
	v_mad_u64_u32 v[36:37], s[10:11], v33, s33, v[6:7]
	v_mad_u64_u32 v[38:39], s[10:11], v58, s33, v[6:7]
	v_mad_u64_u32 v[40:41], s[10:11], v57, s33, v[6:7]
	v_mad_u64_u32 v[42:43], s[10:11], v60, s33, v[6:7]
	v_mad_u64_u32 v[44:45], s[10:11], v59, s33, v[6:7]
	v_mad_u64_u32 v[46:47], s[10:11], v62, s33, v[6:7]
	v_mad_u64_u32 v[48:49], s[10:11], v61, s33, v[6:7]
	v_mad_u64_u32 v[50:51], s[10:11], v64, s33, v[6:7]
	v_mad_u64_u32 v[52:53], s[10:11], v63, s33, v[6:7]
	v_mad_u64_u32 v[54:55], s[10:11], v66, s33, v[6:7]
	v_mad_u64_u32 v[56:57], s[10:11], v65, s33, v[6:7]
	v_mad_u64_u32 v[58:59], s[10:11], v68, s33, v[6:7]
	v_mad_u64_u32 v[60:61], s[10:11], v67, s33, v[6:7]
	v_mad_u64_u32 v[62:63], s[10:11], v70, s33, v[6:7]
	v_mad_u64_u32 v[64:65], s[10:11], v69, s33, v[6:7]
	s_waitcnt vmcnt(15)
	ds_write_b32 v34, v71
	s_waitcnt vmcnt(14)
	ds_write_b32 v36, v72
	s_waitcnt vmcnt(13)
	ds_write_b32 v38, v73
	s_waitcnt vmcnt(12)
	ds_write_b32 v40, v74
	s_waitcnt vmcnt(4)
	ds_write_b32 v42, v82
	ds_write_b32 v44, v75
	ds_write_b32 v46, v81
	ds_write_b32 v48, v76
	s_waitcnt vmcnt(0)
	ds_write_b32 v50, v85
	ds_write_b32 v52, v77
	ds_write_b32 v54, v84
	ds_write_b32 v56, v78
	ds_write_b32 v58, v83
	ds_write_b32 v60, v79
	ds_write_b32 v62, v0
	ds_write_b32 v64, v80
	s_cbranch_scc1 .LBB0_1145
; #define GAS __attribute__((address_space(1)))
; #define LAS __attribute__((address_space(3)))
; #define LDS_WAIT() asm volatile("s_waitcnt lgkmcnt(0)" ::: "memory")
; __device__ __forceinline__ unsigned pk2(float lo, float hi) { return f2bf(lo) | (f2bf(hi) << 16); }
; __device__ __forceinline__ unsigned pk4f8(float a, float b, float c, float d) { int w = 0; w = __builtin_amdgcn_cvt_pk_fp8_f32(a, b, w, false); w = __builtin_amdgcn_cvt_pk_fp8_f32(c, d, w, true); return (unsigned)w; }
; __device__ __forceinline__ void p0_transpose_item(const float* W, int K, int N, bf16* WT, int pmode, LAS float* scr, int item, int lane, bool f8 = false) {
;     ...
;     else if (pmode == 2) { const int h = n0 / 128, d = n0 % 128; r0 = d < 64 ? h * 64 + d : 1024 + h * 64 + (d - 64); }
;     ...
;     const int c = lane & 7;
; #pragma unroll
;     for (int j = 0; j < 4; ++j) { const int n = (lane >> 3) + 8 * j; const LAS float* s = scr + (8 * c) * 33 + n;
;         if (f8) {
;             v2u o; o.x = pk4f8(s[0 * 33] * 32.f, s[1 * 33] * 32.f, s[2 * 33] * 32.f, s[3 * 33] * 32.f); o.y = pk4f8(s[4 * 33] * 32.f, s[5 * 33] * 32.f, s[6 * 33] * 32.f, s[7 * 33] * 32.f);
;             *(GAS v2u*)((unsigned char*)WT + (size_t)(r0 + n) * K + k0 + 8 * c) = o; continue; }
;         v4u o; o.x = pk2(s[0 * 33], s[1 * 33]); o.y = pk2(s[2 * 33], s[3 * 33]); o.z = pk2(s[4 * 33], s[5 * 33]); o.w = pk2(s[6 * 33], s[7 * 33]);
;         *(GAS v4u*)(WT + (size_t)(r0 + n) * K + k0 + 8 * c) = o; }
;     LDS_WAIT(); asm volatile("" ::: "memory");
	s_waitcnt lgkmcnt(0)
	s_and_b32 s4, s4, 0x60
	s_and_b32 s5, s6, 2
	s_add_i32 s7, s4, 0x3c0
	s_lshl_b32 s1, s1, 4
	ds_read2_b32 v[28:29], v7 offset1:8
	s_cmp_eq_u32 s5, 0
	v_readlane_b32 s8, v243, 9
	ds_read2_b32 v[40:41], v7 offset0:33 offset1:41
	s_cselect_b32 s4, s4, s7
	s_and_b32 s1, s1, 0x3c0
	v_readlane_b32 s9, v243, 10
	s_add_i32 s4, s4, s1
	s_mov_b32 s1, s9
	ds_read2_b32 v[42:43], v7 offset0:66 offset1:74
	s_lshl_b32 s8, s0, 1
	v_writelane_b32 v243, s0, 9
	ds_read2_b32 v[44:45], v7 offset0:99 offset1:107
	s_waitcnt lgkmcnt(3)
	v_bfe_u32 v0, v28, 16, 1
	v_writelane_b32 v243, s1, 10
	s_movk_i32 s1, 0x7fff
	v_add3_u32 v0, v28, v0, s1
	s_waitcnt lgkmcnt(2)
	v_bfe_u32 v28, v40, 16, 1
	ds_read2_b32 v[46:47], v7 offset0:132 offset1:140
	v_lshrrev_b32_e32 v0, 16, v0
	v_add3_u32 v28, v40, v28, s1
	s_mov_b32 s0, 0xffff0000
	ds_read2_b32 v[48:49], v7 offset0:165 offset1:173
	v_and_or_b32 v34, v28, s0, v0
	s_waitcnt lgkmcnt(3)
	v_bfe_u32 v0, v42, 16, 1
	v_add3_u32 v0, v42, v0, s1
	s_waitcnt lgkmcnt(2)
	v_bfe_u32 v28, v44, 16, 1
	ds_read2_b32 v[50:51], v7 offset0:198 offset1:206
	v_lshrrev_b32_e32 v0, 16, v0
	v_add3_u32 v28, v44, v28, s1
	ds_read2_b32 v[52:53], v7 offset0:231 offset1:239
	v_and_or_b32 v35, v28, s0, v0
	s_waitcnt lgkmcnt(3)
	v_bfe_u32 v0, v46, 16, 1
	v_add3_u32 v0, v46, v0, s1
	s_waitcnt lgkmcnt(2)
	v_bfe_u32 v28, v48, 16, 1
	v_lshrrev_b32_e32 v0, 16, v0
	v_add3_u32 v28, v48, v28, s1
	v_and_or_b32 v36, v28, s0, v0
	s_waitcnt lgkmcnt(1)
	v_bfe_u32 v0, v50, 16, 1
	v_add3_u32 v0, v50, v0, s1
	s_waitcnt lgkmcnt(0)
	v_bfe_u32 v28, v52, 16, 1
	v_lshrrev_b32_e32 v0, 16, v0
	v_add3_u32 v28, v52, v28, s1
	v_and_or_b32 v37, v28, s0, v0
	v_or_b32_e32 v0, s4, v5
	v_lshl_add_u64 v[38:39], v[10:11], 0, s[8:9]
	v_lshlrev_b32_e32 v0, 9, v0
	v_lshl_add_u64 v[54:55], v[38:39], 0, v[0:1]
	v_bfe_u32 v0, v29, 16, 1
	v_add3_u32 v0, v29, v0, s1
	v_bfe_u32 v28, v41, 16, 1
	v_lshrrev_b32_e32 v0, 16, v0
	v_add3_u32 v28, v41, v28, s1
	global_store_dwordx4 v[54:55], v[34:37], off
	s_nop 1
	v_and_or_b32 v34, v28, s0, v0
	v_bfe_u32 v0, v43, 16, 1
	v_add3_u32 v0, v43, v0, s1
	v_bfe_u32 v28, v45, 16, 1
	v_lshrrev_b32_e32 v0, 16, v0
	v_add3_u32 v28, v45, v28, s1
	v_and_or_b32 v35, v28, s0, v0
	v_bfe_u32 v0, v47, 16, 1
	v_add3_u32 v0, v47, v0, s1
	v_bfe_u32 v28, v49, 16, 1
	v_lshrrev_b32_e32 v0, 16, v0
	v_add3_u32 v28, v49, v28, s1
	v_and_or_b32 v36, v28, s0, v0
	v_bfe_u32 v0, v51, 16, 1
	v_add3_u32 v0, v51, v0, s1
	v_bfe_u32 v28, v53, 16, 1
	v_lshrrev_b32_e32 v0, 16, v0
	v_add3_u32 v28, v53, v28, s1
	v_and_or_b32 v37, v28, s0, v0
	v_or_b32_e32 v0, s4, v30
	v_lshlrev_b32_e32 v0, 9, v0
	ds_read2_b32 v[28:29], v7 offset0:16 offset1:24
	v_lshl_add_u64 v[40:41], v[38:39], 0, v[0:1]
	global_store_dwordx4 v[40:41], v[34:37], off
	ds_read2_b32 v[40:41], v7 offset0:49 offset1:57
	ds_read2_b32 v[42:43], v7 offset0:82 offset1:90
	ds_read2_b32 v[44:45], v7 offset0:115 offset1:123
	s_waitcnt lgkmcnt(3)
	v_bfe_u32 v0, v28, 16, 1
	v_add3_u32 v0, v28, v0, s1
	s_waitcnt lgkmcnt(2)
	v_bfe_u32 v28, v40, 16, 1
	ds_read2_b32 v[46:47], v7 offset0:148 offset1:156
	v_lshrrev_b32_e32 v0, 16, v0
	v_add3_u32 v28, v40, v28, s1
	ds_read2_b32 v[48:49], v7 offset0:181 offset1:189
	v_and_or_b32 v34, v28, s0, v0
	s_waitcnt lgkmcnt(3)
	v_bfe_u32 v0, v42, 16, 1
	v_add3_u32 v0, v42, v0, s1
	s_waitcnt lgkmcnt(2)
	v_bfe_u32 v28, v44, 16, 1
	ds_read2_b32 v[50:51], v7 offset0:214 offset1:222
	v_lshrrev_b32_e32 v0, 16, v0
	v_add3_u32 v28, v44, v28, s1
	ds_read2_b32 v[52:53], v7 offset0:247 offset1:255
	v_and_or_b32 v35, v28, s0, v0
	s_waitcnt lgkmcnt(3)
	v_bfe_u32 v0, v46, 16, 1
	v_add3_u32 v0, v46, v0, s1
	s_waitcnt lgkmcnt(2)
	v_bfe_u32 v28, v48, 16, 1
	v_lshrrev_b32_e32 v0, 16, v0
	v_add3_u32 v28, v48, v28, s1
	v_and_or_b32 v36, v28, s0, v0
	s_waitcnt lgkmcnt(1)
	v_bfe_u32 v0, v50, 16, 1
	v_add3_u32 v0, v50, v0, s1
	s_waitcnt lgkmcnt(0)
	v_bfe_u32 v28, v52, 16, 1
	v_lshrrev_b32_e32 v0, 16, v0
	v_add3_u32 v28, v52, v28, s1
	v_and_or_b32 v37, v28, s0, v0
	v_or_b32_e32 v0, s4, v31
	v_lshlrev_b32_e32 v0, 9, v0
	v_lshl_add_u64 v[54:55], v[38:39], 0, v[0:1]
	v_bfe_u32 v0, v29, 16, 1
	v_add3_u32 v0, v29, v0, s1
	v_bfe_u32 v28, v41, 16, 1
	v_lshrrev_b32_e32 v0, 16, v0
	v_add3_u32 v28, v41, v28, s1
	global_store_dwordx4 v[54:55], v[34:37], off
	s_nop 1
	v_and_or_b32 v34, v28, s0, v0
	v_bfe_u32 v0, v43, 16, 1
	v_add3_u32 v0, v43, v0, s1
	v_bfe_u32 v28, v45, 16, 1
	v_lshrrev_b32_e32 v0, 16, v0
	v_add3_u32 v28, v45, v28, s1
	v_and_or_b32 v35, v28, s0, v0
	v_bfe_u32 v0, v47, 16, 1
	v_add3_u32 v0, v47, v0, s1
	v_bfe_u32 v28, v49, 16, 1
	v_lshrrev_b32_e32 v0, 16, v0
	v_add3_u32 v28, v49, v28, s1
	v_and_or_b32 v36, v28, s0, v0
	v_bfe_u32 v0, v51, 16, 1
	v_add3_u32 v0, v51, v0, s1
	v_bfe_u32 v28, v53, 16, 1
	v_lshrrev_b32_e32 v0, 16, v0
	v_add3_u32 v28, v53, v28, s1
	v_and_or_b32 v37, v28, s0, v0
	v_or_b32_e32 v0, s4, v32
	v_lshlrev_b32_e32 v0, 9, v0
	v_lshl_add_u64 v[28:29], v[38:39], 0, v[0:1]
	global_store_dwordx4 v[28:29], v[34:37], off
	s_waitcnt lgkmcnt(0)

; #define LDS_WAIT() asm volatile("s_waitcnt lgkmcnt(0)" ::: "memory")
; __device__ __forceinline__ void p0_transpose_item(const float* W, int K, int N, bf16* WT, int pmode, LAS float* scr, int item, int lane, bool f8 = false) {
;     const int nblk = N / 32, kb = item / nblk, nb = item % nblk, k0 = 64 * kb, n0 = 32 * nb;
;     int r0 = n0;
;     if (pmode == 1) { const int h = n0 / 96, d = n0 % 96; r0 = d < 64 ? h * 64 + d : 1024 + h * 32 + (d - 64); }
;     else if (pmode == 2) { const int h = n0 / 128, d = n0 % 128; r0 = d < 64 ? h * 64 + d : 1024 + h * 64 + (d - 64); }
; #pragma unroll 8
;     for (int i = 0; i < 32; ++i) { const int kk = 2 * i + (lane >> 5); scr[kk * 33 + (lane & 31)] = W[(size_t)(k0 + kk) * N + n0 + (lane & 31)]; }
;     LDS_WAIT(); asm volatile("" ::: "memory");
.LBB0_1154:
	s_lshl_b32 s9, s1, 1
	s_lshl_b32 s10, s5, 1
	v_or_b32_e32 v0, s9, v3
	v_or_b32_e32 v33, s10, v2
	s_add_i32 s11, s9, 4
	s_add_i32 s12, s10, 4
	s_add_i32 s13, s9, 8
	s_add_i32 s14, s10, 8
	s_add_i32 s15, s9, 12
	s_add_i32 s16, s10, 12
	s_add_i32 s17, s9, 16
	s_add_i32 s18, s10, 16
	s_add_i32 s19, s9, 20
	s_add_i32 s20, s10, 20
	s_add_i32 s21, s9, 24
	s_add_i32 s22, s10, 24
	s_add_i32 s9, s9, 28
	s_add_i32 s10, s10, 28
	v_add_u32_e32 v34, s4, v33
	v_or_b32_e32 v66, s11, v3
	v_or_b32_e32 v67, s12, v2
	v_or_b32_e32 v68, s13, v3
	v_or_b32_e32 v69, s14, v2
	v_or_b32_e32 v70, s15, v3
	v_or_b32_e32 v71, s16, v2
	v_or_b32_e32 v72, s17, v3
	v_or_b32_e32 v73, s18, v2
	v_or_b32_e32 v74, s19, v3
	v_or_b32_e32 v75, s20, v2
	v_or_b32_e32 v76, s21, v3
	v_or_b32_e32 v77, s22, v2
	v_or_b32_e32 v78, s9, v3
	v_or_b32_e32 v79, s10, v2
	v_add_u32_e32 v36, s0, v0
	v_mad_u64_u32 v[34:35], s[10:11], v34, s23, v[28:29]
	v_add_u32_e32 v40, s0, v66
	v_add_u32_e32 v38, s4, v67
	v_add_u32_e32 v44, s0, v68
	v_add_u32_e32 v42, s4, v69
	v_add_u32_e32 v48, s0, v70
	v_add_u32_e32 v46, s4, v71
	v_add_u32_e32 v52, s0, v72
	v_add_u32_e32 v50, s4, v73
	v_add_u32_e32 v56, s0, v74
	v_add_u32_e32 v54, s4, v75
	v_add_u32_e32 v60, s0, v76
	v_add_u32_e32 v58, s4, v77
	v_add_u32_e32 v64, s0, v78
	v_add_u32_e32 v62, s4, v79
	v_mad_u64_u32 v[36:37], s[10:11], v36, s23, v[28:29]
	v_mad_u64_u32 v[38:39], s[10:11], v38, s23, v[28:29]
	v_mad_u64_u32 v[40:41], s[10:11], v40, s23, v[28:29]
	v_mad_u64_u32 v[42:43], s[10:11], v42, s23, v[28:29]
	v_mad_u64_u32 v[44:45], s[10:11], v44, s23, v[28:29]
	v_mad_u64_u32 v[46:47], s[10:11], v46, s23, v[28:29]
	v_mad_u64_u32 v[48:49], s[10:11], v48, s23, v[28:29]
	v_mad_u64_u32 v[50:51], s[10:11], v50, s23, v[28:29]
	v_mad_u64_u32 v[52:53], s[10:11], v52, s23, v[28:29]
	v_mad_u64_u32 v[54:55], s[10:11], v54, s23, v[28:29]
	v_mad_u64_u32 v[56:57], s[10:11], v56, s23, v[28:29]
	v_mad_u64_u32 v[58:59], s[10:11], v58, s23, v[28:29]
	v_mad_u64_u32 v[60:61], s[10:11], v60, s23, v[28:29]
	v_mad_u64_u32 v[62:63], s[10:11], v62, s23, v[28:29]
	v_mad_u64_u32 v[64:65], s[10:11], v64, s23, v[28:29]
	global_load_dword v80, v[34:35], off nt
	global_load_dword v81, v[36:37], off nt
	global_load_dword v82, v[38:39], off nt
	global_load_dword v83, v[40:41], off nt
	global_load_dword v84, v[42:43], off nt
	global_load_dword v85, v[44:45], off nt
	global_load_dword v86, v[46:47], off nt
	global_load_dword v87, v[48:49], off nt
	global_load_dword v88, v[50:51], off nt
	global_load_dword v89, v[52:53], off nt
	global_load_dword v90, v[54:55], off nt
	global_load_dword v91, v[56:57], off nt
	global_load_dword v92, v[58:59], off nt
	global_load_dword v93, v[60:61], off nt
	global_load_dword v94, v[62:63], off nt
	global_load_dword v95, v[64:65], off nt
	s_add_i32 s5, s5, 16
	s_add_i32 s1, s1, 16
	s_add_i32 s8, s8, -16
	v_mad_u64_u32 v[34:35], s[10:11], v33, s33, v[6:7]
	s_cmp_lg_u32 s8, 0
	v_mad_u64_u32 v[36:37], s[10:11], v0, s33, v[6:7]
	v_mad_u64_u32 v[38:39], s[10:11], v67, s33, v[6:7]
	v_mad_u64_u32 v[40:41], s[10:11], v66, s33, v[6:7]
	v_mad_u64_u32 v[42:43], s[10:11], v69, s33, v[6:7]
	v_mad_u64_u32 v[44:45], s[10:11], v68, s33, v[6:7]
	v_mad_u64_u32 v[46:47], s[10:11], v71, s33, v[6:7]
	v_mad_u64_u32 v[48:49], s[10:11], v70, s33, v[6:7]
	v_mad_u64_u32 v[50:51], s[10:11], v73, s33, v[6:7]
	v_mad_u64_u32 v[52:53], s[10:11], v72, s33, v[6:7]
	v_mad_u64_u32 v[54:55], s[10:11], v75, s33, v[6:7]
	v_mad_u64_u32 v[56:57], s[10:11], v74, s33, v[6:7]
	v_mad_u64_u32 v[58:59], s[10:11], v77, s33, v[6:7]
	v_mad_u64_u32 v[60:61], s[10:11], v76, s33, v[6:7]
	v_mad_u64_u32 v[62:63], s[10:11], v79, s33, v[6:7]
	v_mad_u64_u32 v[64:65], s[10:11], v78, s33, v[6:7]
	s_waitcnt vmcnt(15)
	ds_write_b32 v34, v80
	s_waitcnt vmcnt(14)
	ds_write_b32 v36, v81
	s_waitcnt vmcnt(13)
	ds_write_b32 v38, v82
	s_waitcnt vmcnt(12)
	ds_write_b32 v40, v83
	s_waitcnt vmcnt(11)
	ds_write_b32 v42, v84
	s_waitcnt vmcnt(10)
	ds_write_b32 v44, v85
	s_waitcnt vmcnt(9)
	ds_write_b32 v46, v86
	s_waitcnt vmcnt(8)
	ds_write_b32 v48, v87
	s_waitcnt vmcnt(7)
	ds_write_b32 v50, v88
	s_waitcnt vmcnt(6)
	ds_write_b32 v52, v89
	s_waitcnt vmcnt(5)
	ds_write_b32 v54, v90
	s_waitcnt vmcnt(4)
	ds_write_b32 v56, v91
	s_waitcnt vmcnt(3)
	ds_write_b32 v58, v92
	s_waitcnt vmcnt(2)
	ds_write_b32 v60, v93
	s_waitcnt vmcnt(1)
	ds_write_b32 v62, v94
	s_waitcnt vmcnt(0)
	ds_write_b32 v64, v95
	s_cbranch_scc1 .LBB0_1154
; #define GAS __attribute__((address_space(1)))
; #define LAS __attribute__((address_space(3)))
; #define LDS_WAIT() asm volatile("s_waitcnt lgkmcnt(0)" ::: "memory")
; __device__ __forceinline__ unsigned pk2(float lo, float hi) { return f2bf(lo) | (f2bf(hi) << 16); }
; __device__ __forceinline__ unsigned pk4f8(float a, float b, float c, float d) { int w = 0; w = __builtin_amdgcn_cvt_pk_fp8_f32(a, b, w, false); w = __builtin_amdgcn_cvt_pk_fp8_f32(c, d, w, true); return (unsigned)w; }
; __device__ __forceinline__ void p0_transpose_item(const float* W, int K, int N, bf16* WT, int pmode, LAS float* scr, int item, int lane, bool f8 = false) {
;     ...
;     if (pmode == 1) { const int h = n0 / 96, d = n0 % 96; r0 = d < 64 ? h * 64 + d : 1024 + h * 32 + (d - 64); }
;     ...
;     const int c = lane & 7;
; #pragma unroll
;     for (int j = 0; j < 4; ++j) { const int n = (lane >> 3) + 8 * j; const LAS float* s = scr + (8 * c) * 33 + n;
;         if (f8) {
;             v2u o; o.x = pk4f8(s[0 * 33] * 32.f, s[1 * 33] * 32.f, s[2 * 33] * 32.f, s[3 * 33] * 32.f); o.y = pk4f8(s[4 * 33] * 32.f, s[5 * 33] * 32.f, s[6 * 33] * 32.f, s[7 * 33] * 32.f);
;             *(GAS v2u*)((unsigned char*)WT + (size_t)(r0 + n) * K + k0 + 8 * c) = o; continue; }
;         v4u o; o.x = pk2(s[0 * 33], s[1 * 33]); o.y = pk2(s[2 * 33], s[3 * 33]); o.z = pk2(s[4 * 33], s[5 * 33]); o.w = pk2(s[6 * 33], s[7 * 33]);
;         *(GAS v4u*)(WT + (size_t)(r0 + n) * K + k0 + 8 * c) = o; }
;     LDS_WAIT(); asm volatile("" ::: "memory");
	s_waitcnt lgkmcnt(0)
	ds_read2_b32 v[28:29], v7 offset1:8
	v_readlane_b32 s0, v243, 9
	ds_read2_b32 v[40:41], v7 offset0:33 offset1:41
	ds_read2_b32 v[42:43], v7 offset0:66 offset1:74
	v_readlane_b32 s1, v243, 10
	s_mov_b32 s5, s1
	v_writelane_b32 v243, s0, 9
	ds_read2_b32 v[44:45], v7 offset0:99 offset1:107
	s_waitcnt lgkmcnt(3)
	v_bfe_u32 v0, v28, 16, 1
	v_writelane_b32 v243, s1, 10
	s_movk_i32 s1, 0x7fff
	v_add3_u32 v0, v28, v0, s1
	s_waitcnt lgkmcnt(2)
	v_bfe_u32 v28, v40, 16, 1
	ds_read2_b32 v[46:47], v7 offset0:132 offset1:140
	v_lshrrev_b32_e32 v0, 16, v0
	v_add3_u32 v28, v40, v28, s1
	s_mov_b32 s0, 0xffff0000
	ds_read2_b32 v[48:49], v7 offset0:165 offset1:173
	v_and_or_b32 v34, v28, s0, v0
	s_waitcnt lgkmcnt(3)
	v_bfe_u32 v0, v42, 16, 1
	v_add3_u32 v0, v42, v0, s1
	s_waitcnt lgkmcnt(2)
	v_bfe_u32 v28, v44, 16, 1
	ds_read2_b32 v[50:51], v7 offset0:198 offset1:206
	v_lshrrev_b32_e32 v0, 16, v0
	v_add3_u32 v28, v44, v28, s1
	ds_read2_b32 v[52:53], v7 offset0:231 offset1:239
	v_and_or_b32 v35, v28, s0, v0
	s_waitcnt lgkmcnt(3)
	v_bfe_u32 v0, v46, 16, 1
	v_add3_u32 v0, v46, v0, s1
	s_waitcnt lgkmcnt(2)
	v_bfe_u32 v28, v48, 16, 1
	v_lshrrev_b32_e32 v0, 16, v0
	v_add3_u32 v28, v48, v28, s1
	v_and_or_b32 v36, v28, s0, v0
	s_waitcnt lgkmcnt(1)
	v_bfe_u32 v0, v50, 16, 1
	v_add3_u32 v0, v50, v0, s1
	s_waitcnt lgkmcnt(0)
	v_bfe_u32 v28, v52, 16, 1
	v_lshrrev_b32_e32 v0, 16, v0
	v_add3_u32 v28, v52, v28, s1
	s_lshl_b32 s4, s4, 1
	v_and_or_b32 v37, v28, s0, v0
	v_add_u32_e32 v0, s7, v5
	v_lshl_add_u64 v[38:39], v[12:13], 0, s[4:5]
	v_mul_i32_i24_e32 v0, 0x300, v0
	v_lshl_add_u64 v[54:55], v[38:39], 0, v[0:1]
	v_bfe_u32 v0, v29, 16, 1
	v_add3_u32 v0, v29, v0, s1
	v_bfe_u32 v28, v41, 16, 1
	v_lshrrev_b32_e32 v0, 16, v0
	v_add3_u32 v28, v41, v28, s1
	global_store_dwordx4 v[54:55], v[34:37], off
	s_nop 1
	v_and_or_b32 v34, v28, s0, v0
	v_bfe_u32 v0, v43, 16, 1
	v_add3_u32 v0, v43, v0, s1
	v_bfe_u32 v28, v45, 16, 1
	v_lshrrev_b32_e32 v0, 16, v0
	v_add3_u32 v28, v45, v28, s1
	v_and_or_b32 v35, v28, s0, v0
	v_bfe_u32 v0, v47, 16, 1
	v_add3_u32 v0, v47, v0, s1
	v_bfe_u32 v28, v49, 16, 1
	v_lshrrev_b32_e32 v0, 16, v0
	v_add3_u32 v28, v49, v28, s1
	v_and_or_b32 v36, v28, s0, v0
	v_bfe_u32 v0, v51, 16, 1
	v_add3_u32 v0, v51, v0, s1
	v_bfe_u32 v28, v53, 16, 1
	v_lshrrev_b32_e32 v0, 16, v0
	v_add3_u32 v28, v53, v28, s1
	v_and_or_b32 v37, v28, s0, v0
	v_add_u32_e32 v0, s7, v30
	v_mul_i32_i24_e32 v0, 0x300, v0
	ds_read2_b32 v[28:29], v7 offset0:16 offset1:24
	v_lshl_add_u64 v[40:41], v[38:39], 0, v[0:1]
	global_store_dwordx4 v[40:41], v[34:37], off
	ds_read2_b32 v[40:41], v7 offset0:49 offset1:57
	ds_read2_b32 v[42:43], v7 offset0:82 offset1:90
	ds_read2_b32 v[44:45], v7 offset0:115 offset1:123
	s_waitcnt lgkmcnt(3)
	v_bfe_u32 v0, v28, 16, 1
	v_add3_u32 v0, v28, v0, s1
	s_waitcnt lgkmcnt(2)
	v_bfe_u32 v28, v40, 16, 1
	ds_read2_b32 v[46:47], v7 offset0:148 offset1:156
	v_lshrrev_b32_e32 v0, 16, v0
	v_add3_u32 v28, v40, v28, s1
	ds_read2_b32 v[48:49], v7 offset0:181 offset1:189
	v_and_or_b32 v34, v28, s0, v0
	s_waitcnt lgkmcnt(3)
	v_bfe_u32 v0, v42, 16, 1
	v_add3_u32 v0, v42, v0, s1
	s_waitcnt lgkmcnt(2)
	v_bfe_u32 v28, v44, 16, 1
	ds_read2_b32 v[50:51], v7 offset0:214 offset1:222
	v_lshrrev_b32_e32 v0, 16, v0
	v_add3_u32 v28, v44, v28, s1
	ds_read2_b32 v[52:53], v7 offset0:247 offset1:255
	v_and_or_b32 v35, v28, s0, v0
	s_waitcnt lgkmcnt(3)
	v_bfe_u32 v0, v46, 16, 1
	v_add3_u32 v0, v46, v0, s1
	s_waitcnt lgkmcnt(2)
	v_bfe_u32 v28, v48, 16, 1
	v_lshrrev_b32_e32 v0, 16, v0
	v_add3_u32 v28, v48, v28, s1
	v_and_or_b32 v36, v28, s0, v0
	s_waitcnt lgkmcnt(1)
	v_bfe_u32 v0, v50, 16, 1
	v_add3_u32 v0, v50, v0, s1
	s_waitcnt lgkmcnt(0)
	v_bfe_u32 v28, v52, 16, 1
	v_lshrrev_b32_e32 v0, 16, v0
	v_add3_u32 v28, v52, v28, s1
	v_and_or_b32 v37, v28, s0, v0
	v_add_u32_e32 v0, s7, v31
	v_mul_i32_i24_e32 v0, 0x300, v0
	v_lshl_add_u64 v[54:55], v[38:39], 0, v[0:1]
	v_bfe_u32 v0, v29, 16, 1
	v_add3_u32 v0, v29, v0, s1
	v_bfe_u32 v28, v41, 16, 1
	v_lshrrev_b32_e32 v0, 16, v0
	v_add3_u32 v28, v41, v28, s1
	global_store_dwordx4 v[54:55], v[34:37], off
	s_nop 1
	v_and_or_b32 v34, v28, s0, v0
	v_bfe_u32 v0, v43, 16, 1
	v_add3_u32 v0, v43, v0, s1
	v_bfe_u32 v28, v45, 16, 1
	v_lshrrev_b32_e32 v0, 16, v0
	v_add3_u32 v28, v45, v28, s1
	v_and_or_b32 v35, v28, s0, v0
	v_bfe_u32 v0, v47, 16, 1
	v_add3_u32 v0, v47, v0, s1
	v_bfe_u32 v28, v49, 16, 1
	v_lshrrev_b32_e32 v0, 16, v0
	v_add3_u32 v28, v49, v28, s1
	v_and_or_b32 v36, v28, s0, v0
	v_bfe_u32 v0, v51, 16, 1
	v_add3_u32 v0, v51, v0, s1
	v_bfe_u32 v28, v53, 16, 1
	v_lshrrev_b32_e32 v0, 16, v0
	v_add3_u32 v28, v53, v28, s1
	v_and_or_b32 v37, v28, s0, v0
	v_add_u32_e32 v0, s7, v32
	v_mul_i32_i24_e32 v0, 0x300, v0
	v_lshl_add_u64 v[28:29], v[38:39], 0, v[0:1]
	global_store_dwordx4 v[28:29], v[34:37], off
	s_waitcnt lgkmcnt(0)

; #define LDS_WAIT() asm volatile("s_waitcnt lgkmcnt(0)" ::: "memory")
; __device__ __forceinline__ void p0_transpose_item(const float* W, int K, int N, bf16* WT, int pmode, LAS float* scr, int item, int lane, bool f8 = false) {
;     const int nblk = N / 32, kb = item / nblk, nb = item % nblk, k0 = 64 * kb, n0 = 32 * nb;
;     int r0 = n0;
;     if (pmode == 1) { const int h = n0 / 96, d = n0 % 96; r0 = d < 64 ? h * 64 + d : 1024 + h * 32 + (d - 64); }
;     else if (pmode == 2) { const int h = n0 / 128, d = n0 % 128; r0 = d < 64 ? h * 64 + d : 1024 + h * 64 + (d - 64); }
; #pragma unroll 8
;     for (int i = 0; i < 32; ++i) { const int kk = 2 * i + (lane >> 5); scr[kk * 33 + (lane & 31)] = W[(size_t)(k0 + kk) * N + n0 + (lane & 31)]; }
;     LDS_WAIT(); asm volatile("" ::: "memory");
.LBB0_1159:
	s_lshl_b32 s9, s5, 1
	s_lshl_b32 s10, s7, 1
	v_or_b32_e32 v0, s9, v3
	v_or_b32_e32 v33, s10, v2
	s_add_i32 s11, s9, 4
	s_add_i32 s12, s10, 4
	s_add_i32 s13, s9, 8
	s_add_i32 s14, s10, 8
	s_add_i32 s15, s9, 12
	s_add_i32 s16, s10, 12
	s_add_i32 s17, s9, 16
	s_add_i32 s18, s10, 16
	s_add_i32 s19, s9, 20
	s_add_i32 s20, s10, 20
	s_add_i32 s21, s9, 24
	s_add_i32 s22, s10, 24
	s_add_i32 s9, s9, 28
	s_add_i32 s10, s10, 28
	v_add_u32_e32 v34, s0, v33
	v_or_b32_e32 v66, s11, v3
	v_or_b32_e32 v67, s12, v2
	v_or_b32_e32 v68, s13, v3
	v_or_b32_e32 v69, s14, v2
	v_or_b32_e32 v70, s15, v3
	v_or_b32_e32 v71, s16, v2
	v_or_b32_e32 v72, s17, v3
	v_or_b32_e32 v73, s18, v2
	v_or_b32_e32 v74, s19, v3
	v_or_b32_e32 v75, s20, v2
	v_or_b32_e32 v76, s21, v3
	v_or_b32_e32 v77, s22, v2
	v_or_b32_e32 v78, s9, v3
	v_or_b32_e32 v79, s10, v2
	v_add_u32_e32 v36, s4, v0
	v_mad_u64_u32 v[34:35], s[10:11], v34, s23, v[28:29]
	v_add_u32_e32 v40, s4, v66
	v_add_u32_e32 v38, s0, v67
	v_add_u32_e32 v44, s4, v68
	v_add_u32_e32 v42, s0, v69
	v_add_u32_e32 v48, s4, v70
	v_add_u32_e32 v46, s0, v71
	v_add_u32_e32 v52, s4, v72
	v_add_u32_e32 v50, s0, v73
	v_add_u32_e32 v56, s4, v74
	v_add_u32_e32 v54, s0, v75
	v_add_u32_e32 v60, s4, v76
	v_add_u32_e32 v58, s0, v77
	v_add_u32_e32 v64, s4, v78
	v_add_u32_e32 v62, s0, v79
	v_mad_u64_u32 v[36:37], s[10:11], v36, s23, v[28:29]
	v_mad_u64_u32 v[38:39], s[10:11], v38, s23, v[28:29]
	v_mad_u64_u32 v[40:41], s[10:11], v40, s23, v[28:29]
	v_mad_u64_u32 v[42:43], s[10:11], v42, s23, v[28:29]
	v_mad_u64_u32 v[44:45], s[10:11], v44, s23, v[28:29]
	v_mad_u64_u32 v[46:47], s[10:11], v46, s23, v[28:29]
	v_mad_u64_u32 v[48:49], s[10:11], v48, s23, v[28:29]
	v_mad_u64_u32 v[50:51], s[10:11], v50, s23, v[28:29]
	v_mad_u64_u32 v[52:53], s[10:11], v52, s23, v[28:29]
	v_mad_u64_u32 v[54:55], s[10:11], v54, s23, v[28:29]
	v_mad_u64_u32 v[56:57], s[10:11], v56, s23, v[28:29]
	v_mad_u64_u32 v[58:59], s[10:11], v58, s23, v[28:29]
	v_mad_u64_u32 v[60:61], s[10:11], v60, s23, v[28:29]
	v_mad_u64_u32 v[62:63], s[10:11], v62, s23, v[28:29]
	v_mad_u64_u32 v[64:65], s[10:11], v64, s23, v[28:29]
	global_load_dword v80, v[34:35], off nt
	global_load_dword v81, v[36:37], off nt
	global_load_dword v82, v[38:39], off nt
	global_load_dword v83, v[40:41], off nt
	global_load_dword v84, v[42:43], off nt
	global_load_dword v85, v[44:45], off nt
	global_load_dword v86, v[46:47], off nt
	global_load_dword v87, v[48:49], off nt
	global_load_dword v88, v[50:51], off nt
	global_load_dword v89, v[52:53], off nt
	global_load_dword v90, v[54:55], off nt
	global_load_dword v91, v[56:57], off nt
	global_load_dword v92, v[58:59], off nt
	global_load_dword v93, v[60:61], off nt
	global_load_dword v94, v[62:63], off nt
	global_load_dword v95, v[64:65], off nt
	s_add_i32 s7, s7, 16
	s_add_i32 s5, s5, 16
	s_add_i32 s8, s8, -16
	v_mad_u64_u32 v[34:35], s[10:11], v33, s33, v[6:7]
	s_cmp_lg_u32 s8, 0
	v_mad_u64_u32 v[36:37], s[10:11], v0, s33, v[6:7]
	v_mad_u64_u32 v[38:39], s[10:11], v67, s33, v[6:7]
	v_mad_u64_u32 v[40:41], s[10:11], v66, s33, v[6:7]
	v_mad_u64_u32 v[42:43], s[10:11], v69, s33, v[6:7]
	v_mad_u64_u32 v[44:45], s[10:11], v68, s33, v[6:7]
	v_mad_u64_u32 v[46:47], s[10:11], v71, s33, v[6:7]
	v_mad_u64_u32 v[48:49], s[10:11], v70, s33, v[6:7]
	v_mad_u64_u32 v[50:51], s[10:11], v73, s33, v[6:7]
	v_mad_u64_u32 v[52:53], s[10:11], v72, s33, v[6:7]
	v_mad_u64_u32 v[54:55], s[10:11], v75, s33, v[6:7]
	v_mad_u64_u32 v[56:57], s[10:11], v74, s33, v[6:7]
	v_mad_u64_u32 v[58:59], s[10:11], v77, s33, v[6:7]
	v_mad_u64_u32 v[60:61], s[10:11], v76, s33, v[6:7]
	v_mad_u64_u32 v[62:63], s[10:11], v79, s33, v[6:7]
	v_mad_u64_u32 v[64:65], s[10:11], v78, s33, v[6:7]
	s_waitcnt vmcnt(15)
	ds_write_b32 v34, v80
	s_waitcnt vmcnt(14)
	ds_write_b32 v36, v81
	s_waitcnt vmcnt(13)
	ds_write_b32 v38, v82
	s_waitcnt vmcnt(12)
	ds_write_b32 v40, v83
	s_waitcnt vmcnt(11)
	ds_write_b32 v42, v84
	s_waitcnt vmcnt(10)
	ds_write_b32 v44, v85
	s_waitcnt vmcnt(9)
	ds_write_b32 v46, v86
	s_waitcnt vmcnt(8)
	ds_write_b32 v48, v87
	s_waitcnt vmcnt(7)
	ds_write_b32 v50, v88
	s_waitcnt vmcnt(6)
	ds_write_b32 v52, v89
	s_waitcnt vmcnt(5)
	ds_write_b32 v54, v90
	s_waitcnt vmcnt(4)
	ds_write_b32 v56, v91
	s_waitcnt vmcnt(3)
	ds_write_b32 v58, v92
	s_waitcnt vmcnt(2)
	ds_write_b32 v60, v93
	s_waitcnt vmcnt(1)
	ds_write_b32 v62, v94
	s_waitcnt vmcnt(0)
	ds_write_b32 v64, v95
	s_cbranch_scc1 .LBB0_1159
; #define GAS __attribute__((address_space(1)))
; #define LAS __attribute__((address_space(3)))
; #define LDS_WAIT() asm volatile("s_waitcnt lgkmcnt(0)" ::: "memory")
; __device__ __forceinline__ unsigned pk2(float lo, float hi) { return f2bf(lo) | (f2bf(hi) << 16); }
; __device__ __forceinline__ unsigned pk4f8(float a, float b, float c, float d) { int w = 0; w = __builtin_amdgcn_cvt_pk_fp8_f32(a, b, w, false); w = __builtin_amdgcn_cvt_pk_fp8_f32(c, d, w, true); return (unsigned)w; }
; __device__ __forceinline__ void p0_transpose_item(const float* W, int K, int N, bf16* WT, int pmode, LAS float* scr, int item, int lane, bool f8 = false) {
;     ...
;     const int c = lane & 7;
; #pragma unroll
;     for (int j = 0; j < 4; ++j) { const int n = (lane >> 3) + 8 * j; const LAS float* s = scr + (8 * c) * 33 + n;
;         if (f8) {
;             v2u o; o.x = pk4f8(s[0 * 33] * 32.f, s[1 * 33] * 32.f, s[2 * 33] * 32.f, s[3 * 33] * 32.f); o.y = pk4f8(s[4 * 33] * 32.f, s[5 * 33] * 32.f, s[6 * 33] * 32.f, s[7 * 33] * 32.f);
;             *(GAS v2u*)((unsigned char*)WT + (size_t)(r0 + n) * K + k0 + 8 * c) = o; continue; }
;         v4u o; o.x = pk2(s[0 * 33], s[1 * 33]); o.y = pk2(s[2 * 33], s[3 * 33]); o.z = pk2(s[4 * 33], s[5 * 33]); o.w = pk2(s[6 * 33], s[7 * 33]);
;         *(GAS v4u*)(WT + (size_t)(r0 + n) * K + k0 + 8 * c) = o; }
;     LDS_WAIT(); asm volatile("" ::: "memory");
	s_waitcnt lgkmcnt(0)
	ds_read2_b32 v[28:29], v7 offset1:8
	ds_read2_b32 v[40:41], v7 offset0:33 offset1:41
	v_readlane_b32 s4, v243, 9
	v_readlane_b32 s5, v243, 10
	ds_read2_b32 v[42:43], v7 offset0:66 offset1:74
	s_mov_b32 s9, s5
	v_writelane_b32 v243, s4, 9
	ds_read2_b32 v[44:45], v7 offset0:99 offset1:107
	s_waitcnt lgkmcnt(3)
	v_bfe_u32 v0, v28, 16, 1
	v_writelane_b32 v243, s5, 10
	s_movk_i32 s4, 0x7fff
	v_add3_u32 v0, v28, v0, s4
	s_waitcnt lgkmcnt(2)
	v_bfe_u32 v28, v40, 16, 1
	ds_read2_b32 v[46:47], v7 offset0:132 offset1:140
	s_lshl_b32 s8, s0, 1
	v_lshrrev_b32_e32 v0, 16, v0
	v_add3_u32 v28, v40, v28, s4
	s_mov_b32 s0, 0xffff0000
	ds_read2_b32 v[48:49], v7 offset0:165 offset1:173
	v_and_or_b32 v34, v28, s0, v0
	s_waitcnt lgkmcnt(3)
	v_bfe_u32 v0, v42, 16, 1
	v_add3_u32 v0, v42, v0, s4
	s_waitcnt lgkmcnt(2)
	v_bfe_u32 v28, v44, 16, 1
	ds_read2_b32 v[50:51], v7 offset0:198 offset1:206
	v_lshrrev_b32_e32 v0, 16, v0
	v_add3_u32 v28, v44, v28, s4
	ds_read2_b32 v[52:53], v7 offset0:231 offset1:239
	v_and_or_b32 v35, v28, s0, v0
	s_waitcnt lgkmcnt(3)
	v_bfe_u32 v0, v46, 16, 1
	v_add3_u32 v0, v46, v0, s4
	s_waitcnt lgkmcnt(2)
	v_bfe_u32 v28, v48, 16, 1
	v_lshrrev_b32_e32 v0, 16, v0
	v_add3_u32 v28, v48, v28, s4
	v_and_or_b32 v36, v28, s0, v0
	s_waitcnt lgkmcnt(1)
	v_bfe_u32 v0, v50, 16, 1
	v_add3_u32 v0, v50, v0, s4
	s_waitcnt lgkmcnt(0)
	v_bfe_u32 v28, v52, 16, 1
	s_and_b32 s1, 0xffff, s1
	v_lshrrev_b32_e32 v0, 16, v0
	v_add3_u32 v28, v52, v28, s4
	v_and_or_b32 v37, v28, s0, v0
	v_or_b32_e32 v0, s1, v5
	v_lshl_add_u64 v[38:39], v[14:15], 0, s[8:9]
	v_lshlrev_b32_e32 v0, 11, v0
	v_lshl_add_u64 v[54:55], v[38:39], 0, v[0:1]
	v_bfe_u32 v0, v29, 16, 1
	v_add3_u32 v0, v29, v0, s4
	v_bfe_u32 v28, v41, 16, 1
	v_lshrrev_b32_e32 v0, 16, v0
	v_add3_u32 v28, v41, v28, s4
	global_store_dwordx4 v[54:55], v[34:37], off
	s_nop 1
	v_and_or_b32 v34, v28, s0, v0
	v_bfe_u32 v0, v43, 16, 1
	v_add3_u32 v0, v43, v0, s4
	v_bfe_u32 v28, v45, 16, 1
	v_lshrrev_b32_e32 v0, 16, v0
	v_add3_u32 v28, v45, v28, s4
	v_and_or_b32 v35, v28, s0, v0
	v_bfe_u32 v0, v47, 16, 1
	v_add3_u32 v0, v47, v0, s4
	v_bfe_u32 v28, v49, 16, 1
	v_lshrrev_b32_e32 v0, 16, v0
	v_add3_u32 v28, v49, v28, s4
	v_and_or_b32 v36, v28, s0, v0
	v_bfe_u32 v0, v51, 16, 1
	v_add3_u32 v0, v51, v0, s4
	v_bfe_u32 v28, v53, 16, 1
	v_lshrrev_b32_e32 v0, 16, v0
	v_add3_u32 v28, v53, v28, s4
	v_and_or_b32 v37, v28, s0, v0
	v_or_b32_e32 v0, s1, v30
	v_lshlrev_b32_e32 v0, 11, v0
	ds_read2_b32 v[28:29], v7 offset0:16 offset1:24
	v_lshl_add_u64 v[40:41], v[38:39], 0, v[0:1]
	global_store_dwordx4 v[40:41], v[34:37], off
	ds_read2_b32 v[40:41], v7 offset0:49 offset1:57
	ds_read2_b32 v[42:43], v7 offset0:82 offset1:90
	ds_read2_b32 v[44:45], v7 offset0:115 offset1:123
	s_waitcnt lgkmcnt(3)
	v_bfe_u32 v0, v28, 16, 1
	v_add3_u32 v0, v28, v0, s4
	s_waitcnt lgkmcnt(2)
	v_bfe_u32 v28, v40, 16, 1
	ds_read2_b32 v[46:47], v7 offset0:148 offset1:156
	v_lshrrev_b32_e32 v0, 16, v0
	v_add3_u32 v28, v40, v28, s4
	ds_read2_b32 v[48:49], v7 offset0:181 offset1:189
	v_and_or_b32 v34, v28, s0, v0
	s_waitcnt lgkmcnt(3)
	v_bfe_u32 v0, v42, 16, 1
	v_add3_u32 v0, v42, v0, s4
	s_waitcnt lgkmcnt(2)
	v_bfe_u32 v28, v44, 16, 1
	ds_read2_b32 v[50:51], v7 offset0:214 offset1:222
	v_lshrrev_b32_e32 v0, 16, v0
	v_add3_u32 v28, v44, v28, s4
	ds_read2_b32 v[52:53], v7 offset0:247 offset1:255
	v_and_or_b32 v35, v28, s0, v0
	s_waitcnt lgkmcnt(3)
	v_bfe_u32 v0, v46, 16, 1
	v_add3_u32 v0, v46, v0, s4
	s_waitcnt lgkmcnt(2)
	v_bfe_u32 v28, v48, 16, 1
	v_lshrrev_b32_e32 v0, 16, v0
	v_add3_u32 v28, v48, v28, s4
	v_and_or_b32 v36, v28, s0, v0
	s_waitcnt lgkmcnt(1)
	v_bfe_u32 v0, v50, 16, 1
	v_add3_u32 v0, v50, v0, s4
	s_waitcnt lgkmcnt(0)
	v_bfe_u32 v28, v52, 16, 1
	v_lshrrev_b32_e32 v0, 16, v0
	v_add3_u32 v28, v52, v28, s4
	v_and_or_b32 v37, v28, s0, v0
	v_or_b32_e32 v0, s1, v31
	v_lshlrev_b32_e32 v0, 11, v0
	v_lshl_add_u64 v[54:55], v[38:39], 0, v[0:1]
	v_bfe_u32 v0, v29, 16, 1
	v_add3_u32 v0, v29, v0, s4
	v_bfe_u32 v28, v41, 16, 1
	v_lshrrev_b32_e32 v0, 16, v0
	v_add3_u32 v28, v41, v28, s4
	global_store_dwordx4 v[54:55], v[34:37], off
	s_nop 1
	v_and_or_b32 v34, v28, s0, v0
	v_bfe_u32 v0, v43, 16, 1
	v_add3_u32 v0, v43, v0, s4
	v_bfe_u32 v28, v45, 16, 1
	v_lshrrev_b32_e32 v0, 16, v0
	v_add3_u32 v28, v45, v28, s4
	v_and_or_b32 v35, v28, s0, v0
	v_bfe_u32 v0, v47, 16, 1
	v_add3_u32 v0, v47, v0, s4
	v_bfe_u32 v28, v49, 16, 1
	v_lshrrev_b32_e32 v0, 16, v0
	v_add3_u32 v28, v49, v28, s4
	v_and_or_b32 v36, v28, s0, v0
	v_bfe_u32 v0, v51, 16, 1
	v_add3_u32 v0, v51, v0, s4
	v_bfe_u32 v28, v53, 16, 1
	v_lshrrev_b32_e32 v0, 16, v0
	v_add3_u32 v28, v53, v28, s4
	v_and_or_b32 v37, v28, s0, v0
	v_or_b32_e32 v0, s1, v32
	v_lshlrev_b32_e32 v0, 11, v0
	v_lshl_add_u64 v[28:29], v[38:39], 0, v[0:1]
	global_store_dwordx4 v[28:29], v[34:37], off
	s_waitcnt lgkmcnt(0)

; #define LDS_WAIT() asm volatile("s_waitcnt lgkmcnt(0)" ::: "memory")
; __device__ __forceinline__ void p0_transpose_item(const float* W, int K, int N, bf16* WT, int pmode, LAS float* scr, int item, int lane, bool f8 = false) {
;     const int nblk = N / 32, kb = item / nblk, nb = item % nblk, k0 = 64 * kb, n0 = 32 * nb;
;     int r0 = n0;
;     if (pmode == 1) { const int h = n0 / 96, d = n0 % 96; r0 = d < 64 ? h * 64 + d : 1024 + h * 32 + (d - 64); }
;     else if (pmode == 2) { const int h = n0 / 128, d = n0 % 128; r0 = d < 64 ? h * 64 + d : 1024 + h * 64 + (d - 64); }
; #pragma unroll 8
;     for (int i = 0; i < 32; ++i) { const int kk = 2 * i + (lane >> 5); scr[kk * 33 + (lane & 31)] = W[(size_t)(k0 + kk) * N + n0 + (lane & 31)]; }
;     LDS_WAIT(); asm volatile("" ::: "memory");
.LBB0_1164:
	s_lshl_b32 s10, s7, 1
	s_lshl_b32 s9, s4, 1
	v_or_b32_e32 v56, s10, v2
	s_add_i32 s12, s10, 4
	s_add_i32 s11, s9, 4
	s_add_i32 s13, s9, 8
	s_add_i32 s14, s10, 8
	v_add_u32_e32 v0, s1, v56
	v_or_b32_e32 v58, s12, v2
	v_or_b32_e32 v33, s9, v3
	s_add_i32 s15, s9, 12
	s_add_i32 s16, s10, 12
	s_add_i32 s17, s9, 16
	s_add_i32 s19, s9, 20
	s_add_i32 s21, s9, 24
	s_add_i32 s9, s9, 28
	v_or_b32_e32 v57, s11, v3
	v_or_b32_e32 v59, s13, v3
	v_or_b32_e32 v60, s14, v2
	v_lshlrev_b64 v[50:51], 12, v[0:1]
	v_add_u32_e32 v0, s1, v58
	v_mov_b32_e32 v35, v1
	v_mov_b32_e32 v37, v1
	v_mov_b32_e32 v39, v1
	s_add_i32 s18, s10, 16
	v_add_u32_e32 v34, s5, v33
	v_or_b32_e32 v61, s15, v3
	v_or_b32_e32 v62, s16, v2
	v_or_b32_e32 v63, s17, v3
	v_or_b32_e32 v65, s19, v3
	v_or_b32_e32 v67, s21, v3
	v_or_b32_e32 v69, s9, v3
	v_add_u32_e32 v36, s5, v57
	v_add_u32_e32 v38, s5, v59
	v_lshlrev_b64 v[52:53], 12, v[0:1]
	v_add_u32_e32 v0, s1, v60
	v_mov_b32_e32 v41, v1
	v_mov_b32_e32 v43, v1
	v_mov_b32_e32 v45, v1
	v_mov_b32_e32 v47, v1
	v_mov_b32_e32 v49, v1
	s_add_i32 s20, s10, 20
	v_or_b32_e32 v64, s18, v2
	v_lshlrev_b64 v[34:35], 12, v[34:35]
	v_add_u32_e32 v40, s5, v61
	v_add_u32_e32 v42, s5, v63
	v_add_u32_e32 v44, s5, v65
	v_add_u32_e32 v46, s5, v67
	v_add_u32_e32 v48, s5, v69
	v_lshl_add_u64 v[50:51], v[28:29], 0, v[50:51]
	v_lshlrev_b64 v[36:37], 12, v[36:37]
	v_lshlrev_b64 v[38:39], 12, v[38:39]
	v_lshlrev_b64 v[54:55], 12, v[0:1]
	v_add_u32_e32 v0, s1, v62
	s_add_i32 s22, s10, 24
	v_or_b32_e32 v66, s20, v2
	v_lshl_add_u64 v[34:35], v[28:29], 0, v[34:35]
	v_lshlrev_b64 v[40:41], 12, v[40:41]
	v_lshlrev_b64 v[42:43], 12, v[42:43]
	v_lshlrev_b64 v[44:45], 12, v[44:45]
	v_lshlrev_b64 v[46:47], 12, v[46:47]
	v_lshlrev_b64 v[48:49], 12, v[48:49]
	v_lshl_add_u64 v[52:53], v[28:29], 0, v[52:53]
	v_lshl_add_u64 v[36:37], v[28:29], 0, v[36:37]
	v_lshl_add_u64 v[38:39], v[28:29], 0, v[38:39]
	global_load_dword v71, v[50:51], off nt
	global_load_dword v72, v[34:35], off nt
	v_lshlrev_b64 v[50:51], 12, v[0:1]
	v_add_u32_e32 v0, s1, v64
	s_add_i32 s10, s10, 28
	v_or_b32_e32 v68, s22, v2
	v_lshl_add_u64 v[40:41], v[28:29], 0, v[40:41]
	v_lshl_add_u64 v[42:43], v[28:29], 0, v[42:43]
	v_lshl_add_u64 v[44:45], v[28:29], 0, v[44:45]
	v_lshl_add_u64 v[46:47], v[28:29], 0, v[46:47]
	v_lshl_add_u64 v[48:49], v[28:29], 0, v[48:49]
	global_load_dword v73, v[52:53], off nt
	global_load_dword v74, v[36:37], off nt
	global_load_dword v75, v[38:39], off nt
	global_load_dword v76, v[40:41], off nt
	global_load_dword v77, v[42:43], off nt
	global_load_dword v78, v[44:45], off nt
	global_load_dword v79, v[46:47], off nt
	global_load_dword v80, v[48:49], off nt
	v_lshl_add_u64 v[36:37], v[28:29], 0, v[50:51]
	v_lshlrev_b64 v[38:39], 12, v[0:1]
	v_add_u32_e32 v0, s1, v66
	v_or_b32_e32 v70, s10, v2
	v_lshl_add_u64 v[34:35], v[28:29], 0, v[54:55]
	global_load_dword v81, v[36:37], off nt
	global_load_dword v82, v[34:35], off nt
	v_lshlrev_b64 v[36:37], 12, v[0:1]
	v_add_u32_e32 v0, s1, v68
	v_lshl_add_u64 v[34:35], v[28:29], 0, v[38:39]
	v_lshlrev_b64 v[38:39], 12, v[0:1]
	v_add_u32_e32 v0, s1, v70
	v_lshlrev_b64 v[40:41], 12, v[0:1]
	v_lshl_add_u64 v[40:41], v[28:29], 0, v[40:41]
	v_lshl_add_u64 v[36:37], v[28:29], 0, v[36:37]
	v_lshl_add_u64 v[38:39], v[28:29], 0, v[38:39]
	global_load_dword v0, v[40:41], off nt
	global_load_dword v83, v[38:39], off nt
	global_load_dword v84, v[36:37], off nt
	global_load_dword v85, v[34:35], off nt
	s_add_i32 s7, s7, 16
	s_add_i32 s4, s4, 16
	s_add_i32 s8, s8, -16
	v_mad_u64_u32 v[34:35], s[10:11], v56, s33, v[6:7]
	s_cmp_lg_u32 s8, 0
	v_mad_u64_u32 v[36:37], s[10:11], v33, s33, v[6:7]
	v_mad_u64_u32 v[38:39], s[10:11], v58, s33, v[6:7]
	v_mad_u64_u32 v[40:41], s[10:11], v57, s33, v[6:7]
	v_mad_u64_u32 v[42:43], s[10:11], v60, s33, v[6:7]
	v_mad_u64_u32 v[44:45], s[10:11], v59, s33, v[6:7]
	v_mad_u64_u32 v[46:47], s[10:11], v62, s33, v[6:7]
	v_mad_u64_u32 v[48:49], s[10:11], v61, s33, v[6:7]
	v_mad_u64_u32 v[50:51], s[10:11], v64, s33, v[6:7]
	v_mad_u64_u32 v[52:53], s[10:11], v63, s33, v[6:7]
	v_mad_u64_u32 v[54:55], s[10:11], v66, s33, v[6:7]
	v_mad_u64_u32 v[56:57], s[10:11], v65, s33, v[6:7]
	v_mad_u64_u32 v[58:59], s[10:11], v68, s33, v[6:7]
	v_mad_u64_u32 v[60:61], s[10:11], v67, s33, v[6:7]
	v_mad_u64_u32 v[62:63], s[10:11], v70, s33, v[6:7]
	v_mad_u64_u32 v[64:65], s[10:11], v69, s33, v[6:7]
	s_waitcnt vmcnt(15)
	ds_write_b32 v34, v71
	s_waitcnt vmcnt(14)
	ds_write_b32 v36, v72
	s_waitcnt vmcnt(13)
	ds_write_b32 v38, v73
	s_waitcnt vmcnt(12)
	ds_write_b32 v40, v74
	s_waitcnt vmcnt(4)
	ds_write_b32 v42, v82
	ds_write_b32 v44, v75
	ds_write_b32 v46, v81
	ds_write_b32 v48, v76
	s_waitcnt vmcnt(0)
	ds_write_b32 v50, v85
	ds_write_b32 v52, v77
	ds_write_b32 v54, v84
	ds_write_b32 v56, v78
	ds_write_b32 v58, v83
	ds_write_b32 v60, v79
	ds_write_b32 v62, v0
	ds_write_b32 v64, v80
	s_cbranch_scc1 .LBB0_1164
; #define GAS __attribute__((address_space(1)))
; #define LAS __attribute__((address_space(3)))
; #define LDS_WAIT() asm volatile("s_waitcnt lgkmcnt(0)" ::: "memory")
; __device__ __forceinline__ unsigned pk2(float lo, float hi) { return f2bf(lo) | (f2bf(hi) << 16); }
; __device__ __forceinline__ unsigned pk4f8(float a, float b, float c, float d) { int w = 0; w = __builtin_amdgcn_cvt_pk_fp8_f32(a, b, w, false); w = __builtin_amdgcn_cvt_pk_fp8_f32(c, d, w, true); return (unsigned)w; }
; __device__ __forceinline__ void p0_transpose_item(const float* W, int K, int N, bf16* WT, int pmode, LAS float* scr, int item, int lane, bool f8 = false) {
;     ...
;     const int c = lane & 7;
; #pragma unroll
;     for (int j = 0; j < 4; ++j) { const int n = (lane >> 3) + 8 * j; const LAS float* s = scr + (8 * c) * 33 + n;
;         if (f8) {
;             v2u o; o.x = pk4f8(s[0 * 33] * 32.f, s[1 * 33] * 32.f, s[2 * 33] * 32.f, s[3 * 33] * 32.f); o.y = pk4f8(s[4 * 33] * 32.f, s[5 * 33] * 32.f, s[6 * 33] * 32.f, s[7 * 33] * 32.f);
;             *(GAS v2u*)((unsigned char*)WT + (size_t)(r0 + n) * K + k0 + 8 * c) = o; continue; }
;         v4u o; o.x = pk2(s[0 * 33], s[1 * 33]); o.y = pk2(s[2 * 33], s[3 * 33]); o.z = pk2(s[4 * 33], s[5 * 33]); o.w = pk2(s[6 * 33], s[7 * 33]);
;         *(GAS v4u*)(WT + (size_t)(r0 + n) * K + k0 + 8 * c) = o; }
;     LDS_WAIT(); asm volatile("" ::: "memory");
	s_waitcnt lgkmcnt(0)
	ds_read2_b32 v[28:29], v7 offset1:8
	ds_read2_b32 v[40:41], v7 offset0:33 offset1:41
	ds_read2_b32 v[42:43], v7 offset0:66 offset1:74
	v_readlane_b32 s4, v243, 9
	v_readlane_b32 s5, v243, 10
	s_lshl_b32 s4, s1, 1
	ds_read2_b32 v[44:45], v7 offset0:99 offset1:107
	s_mov_b32 s1, s5
	v_lshl_add_u64 v[38:39], v[16:17], 0, s[4:5]
	s_waitcnt lgkmcnt(3)
	v_bfe_u32 v0, v28, 16, 1
	s_movk_i32 s4, 0x7fff
	v_writelane_b32 v243, s0, 9
	v_add3_u32 v0, v28, v0, s4
	s_waitcnt lgkmcnt(2)
	v_bfe_u32 v28, v40, 16, 1
	ds_read2_b32 v[46:47], v7 offset0:132 offset1:140
	v_writelane_b32 v243, s1, 10
	v_lshrrev_b32_e32 v0, 16, v0
	v_add3_u32 v28, v40, v28, s4
	s_mov_b32 s1, 0xffff0000
	ds_read2_b32 v[48:49], v7 offset0:165 offset1:173
	v_and_or_b32 v34, v28, s1, v0
	s_waitcnt lgkmcnt(3)
	v_bfe_u32 v0, v42, 16, 1
	v_add3_u32 v0, v42, v0, s4
	s_waitcnt lgkmcnt(2)
	v_bfe_u32 v28, v44, 16, 1
	ds_read2_b32 v[50:51], v7 offset0:198 offset1:206
	v_lshrrev_b32_e32 v0, 16, v0
	v_add3_u32 v28, v44, v28, s4
	ds_read2_b32 v[52:53], v7 offset0:231 offset1:239
	v_and_or_b32 v35, v28, s1, v0
	s_waitcnt lgkmcnt(3)
	v_bfe_u32 v0, v46, 16, 1
	v_add3_u32 v0, v46, v0, s4
	s_waitcnt lgkmcnt(2)
	v_bfe_u32 v28, v48, 16, 1
	v_lshrrev_b32_e32 v0, 16, v0
	v_add3_u32 v28, v48, v28, s4
	v_and_or_b32 v36, v28, s1, v0
	s_waitcnt lgkmcnt(1)
	v_bfe_u32 v0, v50, 16, 1
	v_add3_u32 v0, v50, v0, s4
	s_waitcnt lgkmcnt(0)
	v_bfe_u32 v28, v52, 16, 1
	v_lshrrev_b32_e32 v0, 16, v0
	v_add3_u32 v28, v52, v28, s4
	v_and_or_b32 v37, v28, s1, v0
	v_or_b32_e32 v0, s0, v5
	v_lshlrev_b32_e32 v0, 13, v0
	v_lshl_add_u64 v[54:55], v[38:39], 0, v[0:1]
	v_bfe_u32 v0, v29, 16, 1
	v_add3_u32 v0, v29, v0, s4
	v_bfe_u32 v28, v41, 16, 1
	v_lshrrev_b32_e32 v0, 16, v0
	v_add3_u32 v28, v41, v28, s4
	global_store_dwordx4 v[54:55], v[34:37], off
	s_nop 1
	v_and_or_b32 v34, v28, s1, v0
	v_bfe_u32 v0, v43, 16, 1
	v_add3_u32 v0, v43, v0, s4
	v_bfe_u32 v28, v45, 16, 1
	v_lshrrev_b32_e32 v0, 16, v0
	v_add3_u32 v28, v45, v28, s4
	v_and_or_b32 v35, v28, s1, v0
	v_bfe_u32 v0, v47, 16, 1
	v_add3_u32 v0, v47, v0, s4
	v_bfe_u32 v28, v49, 16, 1
	v_lshrrev_b32_e32 v0, 16, v0
	v_add3_u32 v28, v49, v28, s4
	v_and_or_b32 v36, v28, s1, v0
	v_bfe_u32 v0, v51, 16, 1
	v_add3_u32 v0, v51, v0, s4
	v_bfe_u32 v28, v53, 16, 1
	v_lshrrev_b32_e32 v0, 16, v0
	v_add3_u32 v28, v53, v28, s4
	v_and_or_b32 v37, v28, s1, v0
	v_or_b32_e32 v0, s0, v30
	v_lshlrev_b32_e32 v0, 13, v0
	ds_read2_b32 v[28:29], v7 offset0:16 offset1:24
	v_lshl_add_u64 v[40:41], v[38:39], 0, v[0:1]
	global_store_dwordx4 v[40:41], v[34:37], off
	ds_read2_b32 v[40:41], v7 offset0:49 offset1:57
	ds_read2_b32 v[42:43], v7 offset0:82 offset1:90
	ds_read2_b32 v[44:45], v7 offset0:115 offset1:123
	s_waitcnt lgkmcnt(3)
	v_bfe_u32 v0, v28, 16, 1
	v_add3_u32 v0, v28, v0, s4
	s_waitcnt lgkmcnt(2)
	v_bfe_u32 v28, v40, 16, 1
	ds_read2_b32 v[46:47], v7 offset0:148 offset1:156
	v_lshrrev_b32_e32 v0, 16, v0
	v_add3_u32 v28, v40, v28, s4
	ds_read2_b32 v[48:49], v7 offset0:181 offset1:189
	v_and_or_b32 v34, v28, s1, v0
	s_waitcnt lgkmcnt(3)
	v_bfe_u32 v0, v42, 16, 1
	v_add3_u32 v0, v42, v0, s4
	s_waitcnt lgkmcnt(2)
	v_bfe_u32 v28, v44, 16, 1
	ds_read2_b32 v[50:51], v7 offset0:214 offset1:222
	v_lshrrev_b32_e32 v0, 16, v0
	v_add3_u32 v28, v44, v28, s4
	ds_read2_b32 v[52:53], v7 offset0:247 offset1:255
	v_and_or_b32 v35, v28, s1, v0
	s_waitcnt lgkmcnt(3)
	v_bfe_u32 v0, v46, 16, 1
	v_add3_u32 v0, v46, v0, s4
	s_waitcnt lgkmcnt(2)
	v_bfe_u32 v28, v48, 16, 1
	v_lshrrev_b32_e32 v0, 16, v0
	v_add3_u32 v28, v48, v28, s4
	v_and_or_b32 v36, v28, s1, v0
	s_waitcnt lgkmcnt(1)
	v_bfe_u32 v0, v50, 16, 1
	v_add3_u32 v0, v50, v0, s4
	s_waitcnt lgkmcnt(0)
	v_bfe_u32 v28, v52, 16, 1
	v_lshrrev_b32_e32 v0, 16, v0
	v_add3_u32 v28, v52, v28, s4
	v_and_or_b32 v37, v28, s1, v0
	v_or_b32_e32 v0, s0, v31
	v_lshlrev_b32_e32 v0, 13, v0
	v_lshl_add_u64 v[54:55], v[38:39], 0, v[0:1]
	v_bfe_u32 v0, v29, 16, 1
	v_add3_u32 v0, v29, v0, s4
	v_bfe_u32 v28, v41, 16, 1
	v_lshrrev_b32_e32 v0, 16, v0
	v_add3_u32 v28, v41, v28, s4
	global_store_dwordx4 v[54:55], v[34:37], off
	s_nop 1
	v_and_or_b32 v34, v28, s1, v0
	v_bfe_u32 v0, v43, 16, 1
	v_add3_u32 v0, v43, v0, s4
	v_bfe_u32 v28, v45, 16, 1
	v_lshrrev_b32_e32 v0, 16, v0
	v_add3_u32 v28, v45, v28, s4
	v_and_or_b32 v35, v28, s1, v0
	v_bfe_u32 v0, v47, 16, 1
	v_add3_u32 v0, v47, v0, s4
	v_bfe_u32 v28, v49, 16, 1
	v_lshrrev_b32_e32 v0, 16, v0
	v_add3_u32 v28, v49, v28, s4
	v_and_or_b32 v36, v28, s1, v0
	v_bfe_u32 v0, v51, 16, 1
	v_add3_u32 v0, v51, v0, s4
	v_bfe_u32 v28, v53, 16, 1
	v_lshrrev_b32_e32 v0, 16, v0
	v_add3_u32 v28, v53, v28, s4
	v_and_or_b32 v37, v28, s1, v0
	v_or_b32_e32 v0, s0, v32
	v_lshlrev_b32_e32 v0, 13, v0
	v_lshl_add_u64 v[28:29], v[38:39], 0, v[0:1]
	global_store_dwordx4 v[28:29], v[34:37], off
	s_waitcnt lgkmcnt(0)

; #define LDS_WAIT() asm volatile("s_waitcnt lgkmcnt(0)" ::: "memory")
; __device__ __forceinline__ void p0_transpose_item(const float* W, int K, int N, bf16* WT, int pmode, LAS float* scr, int item, int lane, bool f8 = false) {
;     const int nblk = N / 32, kb = item / nblk, nb = item % nblk, k0 = 64 * kb, n0 = 32 * nb;
;     int r0 = n0;
;     if (pmode == 1) { const int h = n0 / 96, d = n0 % 96; r0 = d < 64 ? h * 64 + d : 1024 + h * 32 + (d - 64); }
;     else if (pmode == 2) { const int h = n0 / 128, d = n0 % 128; r0 = d < 64 ? h * 64 + d : 1024 + h * 64 + (d - 64); }
; #pragma unroll 8
;     for (int i = 0; i < 32; ++i) { const int kk = 2 * i + (lane >> 5); scr[kk * 33 + (lane & 31)] = W[(size_t)(k0 + kk) * N + n0 + (lane & 31)]; }
;     LDS_WAIT(); asm volatile("" ::: "memory");
.LBB0_1169:
	s_lshl_b32 s10, s7, 1
	s_lshl_b32 s9, s4, 1
	v_or_b32_e32 v56, s10, v2
	s_add_i32 s12, s10, 4
	s_add_i32 s11, s9, 4
	s_add_i32 s13, s9, 8
	s_add_i32 s14, s10, 8
	v_add_u32_e32 v0, s1, v56
	v_or_b32_e32 v58, s12, v2
	v_or_b32_e32 v33, s9, v3
	s_add_i32 s15, s9, 12
	s_add_i32 s16, s10, 12
	s_add_i32 s17, s9, 16
	s_add_i32 s19, s9, 20
	s_add_i32 s21, s9, 24
	s_add_i32 s9, s9, 28
	v_or_b32_e32 v57, s11, v3
	v_or_b32_e32 v59, s13, v3
	v_or_b32_e32 v60, s14, v2
	v_lshlrev_b64 v[50:51], 12, v[0:1]
	v_add_u32_e32 v0, s1, v58
	v_mov_b32_e32 v35, v1
	v_mov_b32_e32 v37, v1
	v_mov_b32_e32 v39, v1
	s_add_i32 s18, s10, 16
	v_add_u32_e32 v34, s5, v33
	v_or_b32_e32 v61, s15, v3
	v_or_b32_e32 v62, s16, v2
	v_or_b32_e32 v63, s17, v3
	v_or_b32_e32 v65, s19, v3
	v_or_b32_e32 v67, s21, v3
	v_or_b32_e32 v69, s9, v3
	v_add_u32_e32 v36, s5, v57
	v_add_u32_e32 v38, s5, v59
	v_lshlrev_b64 v[52:53], 12, v[0:1]
	v_add_u32_e32 v0, s1, v60
	v_mov_b32_e32 v41, v1
	v_mov_b32_e32 v43, v1
	v_mov_b32_e32 v45, v1
	v_mov_b32_e32 v47, v1
	v_mov_b32_e32 v49, v1
	s_add_i32 s20, s10, 20
	v_or_b32_e32 v64, s18, v2
	v_lshlrev_b64 v[34:35], 12, v[34:35]
	v_add_u32_e32 v40, s5, v61
	v_add_u32_e32 v42, s5, v63
	v_add_u32_e32 v44, s5, v65
	v_add_u32_e32 v46, s5, v67
	v_add_u32_e32 v48, s5, v69
	v_lshl_add_u64 v[50:51], v[28:29], 0, v[50:51]
	v_lshlrev_b64 v[36:37], 12, v[36:37]
	v_lshlrev_b64 v[38:39], 12, v[38:39]
	v_lshlrev_b64 v[54:55], 12, v[0:1]
	v_add_u32_e32 v0, s1, v62
	s_add_i32 s22, s10, 24
	v_or_b32_e32 v66, s20, v2
	v_lshl_add_u64 v[34:35], v[28:29], 0, v[34:35]
	v_lshlrev_b64 v[40:41], 12, v[40:41]
	v_lshlrev_b64 v[42:43], 12, v[42:43]
	v_lshlrev_b64 v[44:45], 12, v[44:45]
	v_lshlrev_b64 v[46:47], 12, v[46:47]
	v_lshlrev_b64 v[48:49], 12, v[48:49]
	v_lshl_add_u64 v[52:53], v[28:29], 0, v[52:53]
	v_lshl_add_u64 v[36:37], v[28:29], 0, v[36:37]
	v_lshl_add_u64 v[38:39], v[28:29], 0, v[38:39]
	global_load_dword v71, v[50:51], off nt
	global_load_dword v72, v[34:35], off nt
	v_lshlrev_b64 v[50:51], 12, v[0:1]
	v_add_u32_e32 v0, s1, v64
	s_add_i32 s10, s10, 28
	v_or_b32_e32 v68, s22, v2
	v_lshl_add_u64 v[40:41], v[28:29], 0, v[40:41]
	v_lshl_add_u64 v[42:43], v[28:29], 0, v[42:43]
	v_lshl_add_u64 v[44:45], v[28:29], 0, v[44:45]
	v_lshl_add_u64 v[46:47], v[28:29], 0, v[46:47]
	v_lshl_add_u64 v[48:49], v[28:29], 0, v[48:49]
	global_load_dword v73, v[52:53], off nt
	global_load_dword v74, v[36:37], off nt
	global_load_dword v75, v[38:39], off nt
	global_load_dword v76, v[40:41], off nt
	global_load_dword v77, v[42:43], off nt
	global_load_dword v78, v[44:45], off nt
	global_load_dword v79, v[46:47], off nt
	global_load_dword v80, v[48:49], off nt
	v_lshl_add_u64 v[36:37], v[28:29], 0, v[50:51]
	v_lshlrev_b64 v[38:39], 12, v[0:1]
	v_add_u32_e32 v0, s1, v66
	v_or_b32_e32 v70, s10, v2
	v_lshl_add_u64 v[34:35], v[28:29], 0, v[54:55]
	global_load_dword v81, v[36:37], off nt
	global_load_dword v82, v[34:35], off nt
	v_lshlrev_b64 v[36:37], 12, v[0:1]
	v_add_u32_e32 v0, s1, v68
	v_lshl_add_u64 v[34:35], v[28:29], 0, v[38:39]
	v_lshlrev_b64 v[38:39], 12, v[0:1]
	v_add_u32_e32 v0, s1, v70
	v_lshlrev_b64 v[40:41], 12, v[0:1]
	v_lshl_add_u64 v[40:41], v[28:29], 0, v[40:41]
	v_lshl_add_u64 v[36:37], v[28:29], 0, v[36:37]
	v_lshl_add_u64 v[38:39], v[28:29], 0, v[38:39]
	global_load_dword v0, v[40:41], off nt
	global_load_dword v83, v[38:39], off nt
	global_load_dword v84, v[36:37], off nt
	global_load_dword v85, v[34:35], off nt
	s_add_i32 s7, s7, 16
	s_add_i32 s4, s4, 16
	s_add_i32 s8, s8, -16
	v_mad_u64_u32 v[34:35], s[10:11], v56, s33, v[6:7]
	s_cmp_lg_u32 s8, 0
	v_mad_u64_u32 v[36:37], s[10:11], v33, s33, v[6:7]
	v_mad_u64_u32 v[38:39], s[10:11], v58, s33, v[6:7]
	v_mad_u64_u32 v[40:41], s[10:11], v57, s33, v[6:7]
	v_mad_u64_u32 v[42:43], s[10:11], v60, s33, v[6:7]
	v_mad_u64_u32 v[44:45], s[10:11], v59, s33, v[6:7]
	v_mad_u64_u32 v[46:47], s[10:11], v62, s33, v[6:7]
	v_mad_u64_u32 v[48:49], s[10:11], v61, s33, v[6:7]
	v_mad_u64_u32 v[50:51], s[10:11], v64, s33, v[6:7]
	v_mad_u64_u32 v[52:53], s[10:11], v63, s33, v[6:7]
	v_mad_u64_u32 v[54:55], s[10:11], v66, s33, v[6:7]
	v_mad_u64_u32 v[56:57], s[10:11], v65, s33, v[6:7]
	v_mad_u64_u32 v[58:59], s[10:11], v68, s33, v[6:7]
	v_mad_u64_u32 v[60:61], s[10:11], v67, s33, v[6:7]
	v_mad_u64_u32 v[62:63], s[10:11], v70, s33, v[6:7]
	v_mad_u64_u32 v[64:65], s[10:11], v69, s33, v[6:7]
	s_waitcnt vmcnt(15)
	ds_write_b32 v34, v71
	s_waitcnt vmcnt(14)
	ds_write_b32 v36, v72
	s_waitcnt vmcnt(13)
	ds_write_b32 v38, v73
	s_waitcnt vmcnt(12)
	ds_write_b32 v40, v74
	s_waitcnt vmcnt(4)
	ds_write_b32 v42, v82
	ds_write_b32 v44, v75
	ds_write_b32 v46, v81
	ds_write_b32 v48, v76
	s_waitcnt vmcnt(0)
	ds_write_b32 v50, v85
	ds_write_b32 v52, v77
	ds_write_b32 v54, v84
	ds_write_b32 v56, v78
	ds_write_b32 v58, v83
	ds_write_b32 v60, v79
	ds_write_b32 v62, v0
	ds_write_b32 v64, v80
	s_cbranch_scc1 .LBB0_1169
; #define GAS __attribute__((address_space(1)))
; #define LAS __attribute__((address_space(3)))
; #define LDS_WAIT() asm volatile("s_waitcnt lgkmcnt(0)" ::: "memory")
; __device__ __forceinline__ unsigned pk2(float lo, float hi) { return f2bf(lo) | (f2bf(hi) << 16); }
; __device__ __forceinline__ unsigned pk4f8(float a, float b, float c, float d) { int w = 0; w = __builtin_amdgcn_cvt_pk_fp8_f32(a, b, w, false); w = __builtin_amdgcn_cvt_pk_fp8_f32(c, d, w, true); return (unsigned)w; }
; __device__ __forceinline__ void p0_transpose_item(const float* W, int K, int N, bf16* WT, int pmode, LAS float* scr, int item, int lane, bool f8 = false) {
;     ...
;     const int c = lane & 7;
; #pragma unroll
;     for (int j = 0; j < 4; ++j) { const int n = (lane >> 3) + 8 * j; const LAS float* s = scr + (8 * c) * 33 + n;
;         if (f8) {
;             v2u o; o.x = pk4f8(s[0 * 33] * 32.f, s[1 * 33] * 32.f, s[2 * 33] * 32.f, s[3 * 33] * 32.f); o.y = pk4f8(s[4 * 33] * 32.f, s[5 * 33] * 32.f, s[6 * 33] * 32.f, s[7 * 33] * 32.f);
;             *(GAS v2u*)((unsigned char*)WT + (size_t)(r0 + n) * K + k0 + 8 * c) = o; continue; }
;         v4u o; o.x = pk2(s[0 * 33], s[1 * 33]); o.y = pk2(s[2 * 33], s[3 * 33]); o.z = pk2(s[4 * 33], s[5 * 33]); o.w = pk2(s[6 * 33], s[7 * 33]);
;         *(GAS v4u*)(WT + (size_t)(r0 + n) * K + k0 + 8 * c) = o; }
;     LDS_WAIT(); asm volatile("" ::: "memory");
	s_waitcnt lgkmcnt(0)
	ds_read2_b32 v[28:29], v7 offset1:8
	ds_read2_b32 v[40:41], v7 offset0:33 offset1:41
	ds_read2_b32 v[42:43], v7 offset0:66 offset1:74
	v_readlane_b32 s4, v243, 9
	v_readlane_b32 s5, v243, 10
	s_lshl_b32 s4, s1, 1
	ds_read2_b32 v[44:45], v7 offset0:99 offset1:107
	s_mov_b32 s1, s5
	v_lshl_add_u64 v[38:39], v[18:19], 0, s[4:5]
	s_waitcnt lgkmcnt(3)
	v_bfe_u32 v0, v28, 16, 1
	s_movk_i32 s4, 0x7fff
	v_writelane_b32 v243, s0, 9
	v_add3_u32 v0, v28, v0, s4
	s_waitcnt lgkmcnt(2)
	v_bfe_u32 v28, v40, 16, 1
	ds_read2_b32 v[46:47], v7 offset0:132 offset1:140
	v_writelane_b32 v243, s1, 10
	v_lshrrev_b32_e32 v0, 16, v0
	v_add3_u32 v28, v40, v28, s4
	s_mov_b32 s1, 0xffff0000
	ds_read2_b32 v[48:49], v7 offset0:165 offset1:173
	v_and_or_b32 v34, v28, s1, v0
	s_waitcnt lgkmcnt(3)
	v_bfe_u32 v0, v42, 16, 1
	v_add3_u32 v0, v42, v0, s4
	s_waitcnt lgkmcnt(2)
	v_bfe_u32 v28, v44, 16, 1
	ds_read2_b32 v[50:51], v7 offset0:198 offset1:206
	v_lshrrev_b32_e32 v0, 16, v0
	v_add3_u32 v28, v44, v28, s4
	ds_read2_b32 v[52:53], v7 offset0:231 offset1:239
	v_and_or_b32 v35, v28, s1, v0
	s_waitcnt lgkmcnt(3)
	v_bfe_u32 v0, v46, 16, 1
	v_add3_u32 v0, v46, v0, s4
	s_waitcnt lgkmcnt(2)
	v_bfe_u32 v28, v48, 16, 1
	v_lshrrev_b32_e32 v0, 16, v0
	v_add3_u32 v28, v48, v28, s4
	v_and_or_b32 v36, v28, s1, v0
	s_waitcnt lgkmcnt(1)
	v_bfe_u32 v0, v50, 16, 1
	v_add3_u32 v0, v50, v0, s4
	s_waitcnt lgkmcnt(0)
	v_bfe_u32 v28, v52, 16, 1
	v_lshrrev_b32_e32 v0, 16, v0
	v_add3_u32 v28, v52, v28, s4
	v_and_or_b32 v37, v28, s1, v0
	v_or_b32_e32 v0, s0, v5
	v_lshlrev_b32_e32 v0, 13, v0
	v_lshl_add_u64 v[54:55], v[38:39], 0, v[0:1]
	v_bfe_u32 v0, v29, 16, 1
	v_add3_u32 v0, v29, v0, s4
	v_bfe_u32 v28, v41, 16, 1
	v_lshrrev_b32_e32 v0, 16, v0
	v_add3_u32 v28, v41, v28, s4
	global_store_dwordx4 v[54:55], v[34:37], off
	s_nop 1
	v_and_or_b32 v34, v28, s1, v0
	v_bfe_u32 v0, v43, 16, 1
	v_add3_u32 v0, v43, v0, s4
	v_bfe_u32 v28, v45, 16, 1
	v_lshrrev_b32_e32 v0, 16, v0
	v_add3_u32 v28, v45, v28, s4
	v_and_or_b32 v35, v28, s1, v0
	v_bfe_u32 v0, v47, 16, 1
	v_add3_u32 v0, v47, v0, s4
	v_bfe_u32 v28, v49, 16, 1
	v_lshrrev_b32_e32 v0, 16, v0
	v_add3_u32 v28, v49, v28, s4
	v_and_or_b32 v36, v28, s1, v0
	v_bfe_u32 v0, v51, 16, 1
	v_add3_u32 v0, v51, v0, s4
	v_bfe_u32 v28, v53, 16, 1
	v_lshrrev_b32_e32 v0, 16, v0
	v_add3_u32 v28, v53, v28, s4
	v_and_or_b32 v37, v28, s1, v0
	v_or_b32_e32 v0, s0, v30
	v_lshlrev_b32_e32 v0, 13, v0
	ds_read2_b32 v[28:29], v7 offset0:16 offset1:24
	v_lshl_add_u64 v[40:41], v[38:39], 0, v[0:1]
	global_store_dwordx4 v[40:41], v[34:37], off
	ds_read2_b32 v[40:41], v7 offset0:49 offset1:57
	ds_read2_b32 v[42:43], v7 offset0:82 offset1:90
	ds_read2_b32 v[44:45], v7 offset0:115 offset1:123
	s_waitcnt lgkmcnt(3)
	v_bfe_u32 v0, v28, 16, 1
	v_add3_u32 v0, v28, v0, s4
	s_waitcnt lgkmcnt(2)
	v_bfe_u32 v28, v40, 16, 1
	ds_read2_b32 v[46:47], v7 offset0:148 offset1:156
	v_lshrrev_b32_e32 v0, 16, v0
	v_add3_u32 v28, v40, v28, s4
	ds_read2_b32 v[48:49], v7 offset0:181 offset1:189
	v_and_or_b32 v34, v28, s1, v0
	s_waitcnt lgkmcnt(3)
	v_bfe_u32 v0, v42, 16, 1
	v_add3_u32 v0, v42, v0, s4
	s_waitcnt lgkmcnt(2)
	v_bfe_u32 v28, v44, 16, 1
	ds_read2_b32 v[50:51], v7 offset0:214 offset1:222
	v_lshrrev_b32_e32 v0, 16, v0
	v_add3_u32 v28, v44, v28, s4
	ds_read2_b32 v[52:53], v7 offset0:247 offset1:255
	v_and_or_b32 v35, v28, s1, v0
	s_waitcnt lgkmcnt(3)
	v_bfe_u32 v0, v46, 16, 1
	v_add3_u32 v0, v46, v0, s4
	s_waitcnt lgkmcnt(2)
	v_bfe_u32 v28, v48, 16, 1
	v_lshrrev_b32_e32 v0, 16, v0
	v_add3_u32 v28, v48, v28, s4
	v_and_or_b32 v36, v28, s1, v0
	s_waitcnt lgkmcnt(1)
	v_bfe_u32 v0, v50, 16, 1
	v_add3_u32 v0, v50, v0, s4
	s_waitcnt lgkmcnt(0)
	v_bfe_u32 v28, v52, 16, 1
	v_lshrrev_b32_e32 v0, 16, v0
	v_add3_u32 v28, v52, v28, s4
	v_and_or_b32 v37, v28, s1, v0
	v_or_b32_e32 v0, s0, v31
	v_lshlrev_b32_e32 v0, 13, v0
	v_lshl_add_u64 v[54:55], v[38:39], 0, v[0:1]
	v_bfe_u32 v0, v29, 16, 1
	v_add3_u32 v0, v29, v0, s4
	v_bfe_u32 v28, v41, 16, 1
	v_lshrrev_b32_e32 v0, 16, v0
	v_add3_u32 v28, v41, v28, s4
	global_store_dwordx4 v[54:55], v[34:37], off
	s_nop 1
	v_and_or_b32 v34, v28, s1, v0
	v_bfe_u32 v0, v43, 16, 1
	v_add3_u32 v0, v43, v0, s4
	v_bfe_u32 v28, v45, 16, 1
	v_lshrrev_b32_e32 v0, 16, v0
	v_add3_u32 v28, v45, v28, s4
	v_and_or_b32 v35, v28, s1, v0
	v_bfe_u32 v0, v47, 16, 1
	v_add3_u32 v0, v47, v0, s4
	v_bfe_u32 v28, v49, 16, 1
	v_lshrrev_b32_e32 v0, 16, v0
	v_add3_u32 v28, v49, v28, s4
	v_and_or_b32 v36, v28, s1, v0
	v_bfe_u32 v0, v51, 16, 1
	v_add3_u32 v0, v51, v0, s4
	v_bfe_u32 v28, v53, 16, 1
	v_lshrrev_b32_e32 v0, 16, v0
	v_add3_u32 v28, v53, v28, s4
	v_and_or_b32 v37, v28, s1, v0
	v_or_b32_e32 v0, s0, v32
	v_lshlrev_b32_e32 v0, 13, v0
	v_lshl_add_u64 v[28:29], v[38:39], 0, v[0:1]
	global_store_dwordx4 v[28:29], v[34:37], off
	s_waitcnt lgkmcnt(0)

; __device__ __forceinline__ void p0_transpose_item(const float* W, int K, int N, bf16* WT, int pmode, LAS float* scr, int item, int lane, bool f8 = false) {
;     ...
; #pragma unroll 8
;     for (int i = 0; i < 32; ++i) { const int kk = 2 * i + (lane >> 5); scr[kk * 33 + (lane & 31)] = W[(size_t)(k0 + kk) * N + n0 + (lane & 31)]; }
.LBB0_1174:
	s_lshl_b32 s10, s7, 1
	s_lshl_b32 s9, s4, 1
	v_or_b32_e32 v56, s10, v2
	s_add_i32 s12, s10, 4
	s_add_i32 s11, s9, 4
	s_add_i32 s13, s9, 8
	s_add_i32 s14, s10, 8
	v_add_u32_e32 v0, s1, v56
	v_or_b32_e32 v58, s12, v2
	v_or_b32_e32 v33, s9, v3
	s_add_i32 s15, s9, 12
	s_add_i32 s16, s10, 12
	s_add_i32 s17, s9, 16
	s_add_i32 s19, s9, 20
	s_add_i32 s21, s9, 24
	s_add_i32 s9, s9, 28
	v_or_b32_e32 v57, s11, v3
	v_or_b32_e32 v59, s13, v3
	v_or_b32_e32 v60, s14, v2
	v_lshlrev_b64 v[50:51], 14, v[0:1]
	v_add_u32_e32 v0, s1, v58
	v_mov_b32_e32 v35, v1
	v_mov_b32_e32 v37, v1
	v_mov_b32_e32 v39, v1
	s_add_i32 s18, s10, 16
	v_add_u32_e32 v34, s5, v33
	v_or_b32_e32 v61, s15, v3
	v_or_b32_e32 v62, s16, v2
	v_or_b32_e32 v63, s17, v3
	v_or_b32_e32 v65, s19, v3
	v_or_b32_e32 v67, s21, v3
	v_or_b32_e32 v69, s9, v3
	v_add_u32_e32 v36, s5, v57
	v_add_u32_e32 v38, s5, v59
	v_lshlrev_b64 v[52:53], 14, v[0:1]
	v_add_u32_e32 v0, s1, v60
	v_mov_b32_e32 v41, v1
	v_mov_b32_e32 v43, v1
	v_mov_b32_e32 v45, v1
	v_mov_b32_e32 v47, v1
	v_mov_b32_e32 v49, v1
	s_add_i32 s20, s10, 20
	v_or_b32_e32 v64, s18, v2
	v_lshlrev_b64 v[34:35], 14, v[34:35]
	v_add_u32_e32 v40, s5, v61
	v_add_u32_e32 v42, s5, v63
	v_add_u32_e32 v44, s5, v65
	v_add_u32_e32 v46, s5, v67
	v_add_u32_e32 v48, s5, v69
	v_lshl_add_u64 v[50:51], v[28:29], 0, v[50:51]
	v_lshlrev_b64 v[36:37], 14, v[36:37]
	v_lshlrev_b64 v[38:39], 14, v[38:39]
	v_lshlrev_b64 v[54:55], 14, v[0:1]
	v_add_u32_e32 v0, s1, v62
	s_add_i32 s22, s10, 24
	v_or_b32_e32 v66, s20, v2
	v_lshl_add_u64 v[34:35], v[28:29], 0, v[34:35]
	v_lshlrev_b64 v[40:41], 14, v[40:41]
	v_lshlrev_b64 v[42:43], 14, v[42:43]
	v_lshlrev_b64 v[44:45], 14, v[44:45]
	v_lshlrev_b64 v[46:47], 14, v[46:47]
	v_lshlrev_b64 v[48:49], 14, v[48:49]
	v_lshl_add_u64 v[52:53], v[28:29], 0, v[52:53]
	v_lshl_add_u64 v[36:37], v[28:29], 0, v[36:37]
	v_lshl_add_u64 v[38:39], v[28:29], 0, v[38:39]
	global_load_dword v71, v[50:51], off nt
	global_load_dword v72, v[34:35], off nt
	v_lshlrev_b64 v[50:51], 14, v[0:1]
	v_add_u32_e32 v0, s1, v64
	s_add_i32 s10, s10, 28
	v_or_b32_e32 v68, s22, v2
	v_lshl_add_u64 v[40:41], v[28:29], 0, v[40:41]
	v_lshl_add_u64 v[42:43], v[28:29], 0, v[42:43]
	v_lshl_add_u64 v[44:45], v[28:29], 0, v[44:45]
	v_lshl_add_u64 v[46:47], v[28:29], 0, v[46:47]
	v_lshl_add_u64 v[48:49], v[28:29], 0, v[48:49]
	global_load_dword v73, v[52:53], off nt
	global_load_dword v74, v[36:37], off nt
	global_load_dword v75, v[38:39], off nt
	global_load_dword v76, v[40:41], off nt
	global_load_dword v77, v[42:43], off nt
	global_load_dword v78, v[44:45], off nt
	global_load_dword v79, v[46:47], off nt
	global_load_dword v80, v[48:49], off nt
	v_lshl_add_u64 v[36:37], v[28:29], 0, v[50:51]
	v_lshlrev_b64 v[38:39], 14, v[0:1]
	v_add_u32_e32 v0, s1, v66
	v_or_b32_e32 v70, s10, v2
	v_lshl_add_u64 v[34:35], v[28:29], 0, v[54:55]
	global_load_dword v81, v[36:37], off nt
	global_load_dword v82, v[34:35], off nt
	v_lshlrev_b64 v[36:37], 14, v[0:1]
	v_add_u32_e32 v0, s1, v68
	v_lshl_add_u64 v[34:35], v[28:29], 0, v[38:39]
	v_lshlrev_b64 v[38:39], 14, v[0:1]
	v_add_u32_e32 v0, s1, v70
	v_lshlrev_b64 v[40:41], 14, v[0:1]
	v_lshl_add_u64 v[40:41], v[28:29], 0, v[40:41]
	v_lshl_add_u64 v[36:37], v[28:29], 0, v[36:37]
	v_lshl_add_u64 v[38:39], v[28:29], 0, v[38:39]
	global_load_dword v0, v[40:41], off nt
	global_load_dword v83, v[38:39], off nt
	global_load_dword v84, v[36:37], off nt
	global_load_dword v85, v[34:35], off nt
	s_add_i32 s7, s7, 16
	s_add_i32 s4, s4, 16
	s_add_i32 s8, s8, -16
	v_mad_u64_u32 v[34:35], s[10:11], v56, s33, v[6:7]
	s_cmp_lg_u32 s8, 0
	v_mad_u64_u32 v[36:37], s[10:11], v33, s33, v[6:7]
	v_mad_u64_u32 v[38:39], s[10:11], v58, s33, v[6:7]
	v_mad_u64_u32 v[40:41], s[10:11], v57, s33, v[6:7]
	v_mad_u64_u32 v[42:43], s[10:11], v60, s33, v[6:7]
	v_mad_u64_u32 v[44:45], s[10:11], v59, s33, v[6:7]
	v_mad_u64_u32 v[46:47], s[10:11], v62, s33, v[6:7]
	v_mad_u64_u32 v[48:49], s[10:11], v61, s33, v[6:7]
	v_mad_u64_u32 v[50:51], s[10:11], v64, s33, v[6:7]
	v_mad_u64_u32 v[52:53], s[10:11], v63, s33, v[6:7]
	v_mad_u64_u32 v[54:55], s[10:11], v66, s33, v[6:7]
	v_mad_u64_u32 v[56:57], s[10:11], v65, s33, v[6:7]
	v_mad_u64_u32 v[58:59], s[10:11], v68, s33, v[6:7]
	v_mad_u64_u32 v[60:61], s[10:11], v67, s33, v[6:7]
	v_mad_u64_u32 v[62:63], s[10:11], v70, s33, v[6:7]
	v_mad_u64_u32 v[64:65], s[10:11], v69, s33, v[6:7]
	s_waitcnt vmcnt(15)
	ds_write_b32 v34, v71
	s_waitcnt vmcnt(14)
	ds_write_b32 v36, v72
	s_waitcnt vmcnt(13)
	ds_write_b32 v38, v73
	s_waitcnt vmcnt(12)
	ds_write_b32 v40, v74
	s_waitcnt vmcnt(4)
	ds_write_b32 v42, v82
	ds_write_b32 v44, v75
	ds_write_b32 v46, v81
	ds_write_b32 v48, v76
	s_waitcnt vmcnt(0)
	ds_write_b32 v50, v85
	ds_write_b32 v52, v77
	ds_write_b32 v54, v84
	ds_write_b32 v56, v78
	ds_write_b32 v58, v83
	ds_write_b32 v60, v79
	ds_write_b32 v62, v0
	ds_write_b32 v64, v80
	s_cbranch_scc1 .LBB0_1174
; #define GAS __attribute__((address_space(1)))
; #define LAS __attribute__((address_space(3)))
; __device__ __forceinline__ unsigned pk2(float lo, float hi) { return f2bf(lo) | (f2bf(hi) << 16); }
; __device__ __forceinline__ unsigned pk4f8(float a, float b, float c, float d) { int w = 0; w = __builtin_amdgcn_cvt_pk_fp8_f32(a, b, w, false); w = __builtin_amdgcn_cvt_pk_fp8_f32(c, d, w, true); return (unsigned)w; }
; __device__ __forceinline__ void p0_transpose_item(const float* W, int K, int N, bf16* WT, int pmode, LAS float* scr, int item, int lane, bool f8 = false) {
;     ...
;     const int c = lane & 7;
; #pragma unroll
;     for (int j = 0; j < 4; ++j) { const int n = (lane >> 3) + 8 * j; const LAS float* s = scr + (8 * c) * 33 + n;
;         if (f8) {
;             v2u o; o.x = pk4f8(s[0 * 33] * 32.f, s[1 * 33] * 32.f, s[2 * 33] * 32.f, s[3 * 33] * 32.f); o.y = pk4f8(s[4 * 33] * 32.f, s[5 * 33] * 32.f, s[6 * 33] * 32.f, s[7 * 33] * 32.f);
;             *(GAS v2u*)((unsigned char*)WT + (size_t)(r0 + n) * K + k0 + 8 * c) = o; continue; }
;         v4u o; o.x = pk2(s[0 * 33], s[1 * 33]); o.y = pk2(s[2 * 33], s[3 * 33]); o.z = pk2(s[4 * 33], s[5 * 33]); o.w = pk2(s[6 * 33], s[7 * 33]);
;         *(GAS v4u*)(WT + (size_t)(r0 + n) * K + k0 + 8 * c) = o; }
	s_waitcnt lgkmcnt(0)
	ds_read2_b32 v[28:29], v7 offset1:8
	ds_read2_b32 v[40:41], v7 offset0:33 offset1:41
	ds_read2_b32 v[42:43], v7 offset0:66 offset1:74
	v_readlane_b32 s4, v243, 9
	v_readlane_b32 s5, v243, 10
	s_lshl_b32 s4, s1, 1
	ds_read2_b32 v[44:45], v7 offset0:99 offset1:107
	s_mov_b32 s1, s5
	v_lshl_add_u64 v[38:39], v[20:21], 0, s[4:5]
	s_waitcnt lgkmcnt(3)
	v_bfe_u32 v0, v28, 16, 1
	s_movk_i32 s4, 0x7fff
	v_writelane_b32 v243, s0, 9
	v_add3_u32 v0, v28, v0, s4
	s_waitcnt lgkmcnt(2)
	v_bfe_u32 v28, v40, 16, 1
	ds_read2_b32 v[46:47], v7 offset0:132 offset1:140
	v_writelane_b32 v243, s1, 10
	v_lshrrev_b32_e32 v0, 16, v0
	v_add3_u32 v28, v40, v28, s4
	s_mov_b32 s1, 0xffff0000
	ds_read2_b32 v[48:49], v7 offset0:165 offset1:173
	v_and_or_b32 v34, v28, s1, v0
	s_waitcnt lgkmcnt(3)
	v_bfe_u32 v0, v42, 16, 1
	v_add3_u32 v0, v42, v0, s4
	s_waitcnt lgkmcnt(2)
	v_bfe_u32 v28, v44, 16, 1
	ds_read2_b32 v[50:51], v7 offset0:198 offset1:206
	v_lshrrev_b32_e32 v0, 16, v0
	v_add3_u32 v28, v44, v28, s4
	ds_read2_b32 v[52:53], v7 offset0:231 offset1:239
	v_and_or_b32 v35, v28, s1, v0
	s_waitcnt lgkmcnt(3)
	v_bfe_u32 v0, v46, 16, 1
	v_add3_u32 v0, v46, v0, s4
	s_waitcnt lgkmcnt(2)
	v_bfe_u32 v28, v48, 16, 1
	v_lshrrev_b32_e32 v0, 16, v0
	v_add3_u32 v28, v48, v28, s4
	v_and_or_b32 v36, v28, s1, v0
	s_waitcnt lgkmcnt(1)
	v_bfe_u32 v0, v50, 16, 1
	v_add3_u32 v0, v50, v0, s4
	s_waitcnt lgkmcnt(0)
	v_bfe_u32 v28, v52, 16, 1
	v_lshrrev_b32_e32 v0, 16, v0
	v_add3_u32 v28, v52, v28, s4
	v_and_or_b32 v37, v28, s1, v0
	v_or_b32_e32 v0, s0, v5
	v_lshlrev_b32_e32 v0, 11, v0
	v_lshl_add_u64 v[54:55], v[38:39], 0, v[0:1]
	v_bfe_u32 v0, v29, 16, 1
	v_add3_u32 v0, v29, v0, s4
	v_bfe_u32 v28, v41, 16, 1
	v_lshrrev_b32_e32 v0, 16, v0
	v_add3_u32 v28, v41, v28, s4
	global_store_dwordx4 v[54:55], v[34:37], off
	s_nop 1
	v_and_or_b32 v34, v28, s1, v0
	v_bfe_u32 v0, v43, 16, 1
	v_add3_u32 v0, v43, v0, s4
	v_bfe_u32 v28, v45, 16, 1
	v_lshrrev_b32_e32 v0, 16, v0
	v_add3_u32 v28, v45, v28, s4
	v_and_or_b32 v35, v28, s1, v0
	v_bfe_u32 v0, v47, 16, 1
	v_add3_u32 v0, v47, v0, s4
	v_bfe_u32 v28, v49, 16, 1
	v_lshrrev_b32_e32 v0, 16, v0
	v_add3_u32 v28, v49, v28, s4
	v_and_or_b32 v36, v28, s1, v0
	v_bfe_u32 v0, v51, 16, 1
	v_add3_u32 v0, v51, v0, s4
	v_bfe_u32 v28, v53, 16, 1
	v_lshrrev_b32_e32 v0, 16, v0
	v_add3_u32 v28, v53, v28, s4
	v_and_or_b32 v37, v28, s1, v0
	v_or_b32_e32 v0, s0, v30
	v_lshlrev_b32_e32 v0, 11, v0
	ds_read2_b32 v[28:29], v7 offset0:16 offset1:24
	v_lshl_add_u64 v[40:41], v[38:39], 0, v[0:1]
	global_store_dwordx4 v[40:41], v[34:37], off
	ds_read2_b32 v[40:41], v7 offset0:49 offset1:57
	ds_read2_b32 v[42:43], v7 offset0:82 offset1:90
	ds_read2_b32 v[44:45], v7 offset0:115 offset1:123
	s_waitcnt lgkmcnt(3)
	v_bfe_u32 v0, v28, 16, 1
	v_add3_u32 v0, v28, v0, s4
	s_waitcnt lgkmcnt(2)
	v_bfe_u32 v28, v40, 16, 1
	ds_read2_b32 v[46:47], v7 offset0:148 offset1:156
	v_lshrrev_b32_e32 v0, 16, v0
	v_add3_u32 v28, v40, v28, s4
	ds_read2_b32 v[48:49], v7 offset0:181 offset1:189
	v_and_or_b32 v34, v28, s1, v0
	s_waitcnt lgkmcnt(3)
	v_bfe_u32 v0, v42, 16, 1
	v_add3_u32 v0, v42, v0, s4
	s_waitcnt lgkmcnt(2)
	v_bfe_u32 v28, v44, 16, 1
	ds_read2_b32 v[50:51], v7 offset0:214 offset1:222
	v_lshrrev_b32_e32 v0, 16, v0
	v_add3_u32 v28, v44, v28, s4
	ds_read2_b32 v[52:53], v7 offset0:247 offset1:255
	v_and_or_b32 v35, v28, s1, v0
	s_waitcnt lgkmcnt(3)
	v_bfe_u32 v0, v46, 16, 1
	v_add3_u32 v0, v46, v0, s4
	s_waitcnt lgkmcnt(2)
	v_bfe_u32 v28, v48, 16, 1
	v_lshrrev_b32_e32 v0, 16, v0
	v_add3_u32 v28, v48, v28, s4
	v_and_or_b32 v36, v28, s1, v0
	s_waitcnt lgkmcnt(1)
	v_bfe_u32 v0, v50, 16, 1
	v_add3_u32 v0, v50, v0, s4
	s_waitcnt lgkmcnt(0)
	v_bfe_u32 v28, v52, 16, 1
	v_lshrrev_b32_e32 v0, 16, v0
	v_add3_u32 v28, v52, v28, s4
	v_and_or_b32 v37, v28, s1, v0
	v_or_b32_e32 v0, s0, v31
	v_lshlrev_b32_e32 v0, 11, v0
	v_lshl_add_u64 v[54:55], v[38:39], 0, v[0:1]
	v_bfe_u32 v0, v29, 16, 1
	v_add3_u32 v0, v29, v0, s4
	v_bfe_u32 v28, v41, 16, 1
	v_lshrrev_b32_e32 v0, 16, v0
	v_add3_u32 v28, v41, v28, s4
	global_store_dwordx4 v[54:55], v[34:37], off
	s_nop 1
	v_and_or_b32 v34, v28, s1, v0
	v_bfe_u32 v0, v43, 16, 1
	v_add3_u32 v0, v43, v0, s4
	v_bfe_u32 v28, v45, 16, 1
	v_lshrrev_b32_e32 v0, 16, v0
	v_add3_u32 v28, v45, v28, s4
	v_and_or_b32 v35, v28, s1, v0
	v_bfe_u32 v0, v47, 16, 1
	v_add3_u32 v0, v47, v0, s4
	v_bfe_u32 v28, v49, 16, 1
	v_lshrrev_b32_e32 v0, 16, v0
	v_add3_u32 v28, v49, v28, s4
	v_and_or_b32 v36, v28, s1, v0
	v_bfe_u32 v0, v51, 16, 1
	v_add3_u32 v0, v51, v0, s4
	v_bfe_u32 v28, v53, 16, 1
	v_lshrrev_b32_e32 v0, 16, v0
	v_add3_u32 v28, v53, v28, s4
	v_and_or_b32 v37, v28, s1, v0
	v_or_b32_e32 v0, s0, v32
	v_lshlrev_b32_e32 v0, 11, v0
	v_lshl_add_u64 v[28:29], v[38:39], 0, v[0:1]
	global_store_dwordx4 v[28:29], v[34:37], off
	s_waitcnt lgkmcnt(0)

; __device__ __forceinline__ void p0_transpose_item(const float* W, int K, int N, bf16* WT, int pmode, LAS float* scr, int item, int lane, bool f8 = false) {
;     ...
; #pragma unroll 8
;     for (int i = 0; i < 32; ++i) { const int kk = 2 * i + (lane >> 5); scr[kk * 33 + (lane & 31)] = W[(size_t)(k0 + kk) * N + n0 + (lane & 31)]; }
.LBB0_1179:
	s_lshl_b32 s10, s7, 1
	s_lshl_b32 s9, s4, 1
	v_or_b32_e32 v56, s10, v2
	s_add_i32 s12, s10, 4
	s_add_i32 s11, s9, 4
	s_add_i32 s13, s9, 8
	s_add_i32 s14, s10, 8
	v_add_u32_e32 v0, s1, v56
	v_or_b32_e32 v58, s12, v2
	v_or_b32_e32 v33, s9, v3
	s_add_i32 s15, s9, 12
	s_add_i32 s16, s10, 12
	s_add_i32 s17, s9, 16
	s_add_i32 s19, s9, 20
	s_add_i32 s21, s9, 24
	s_add_i32 s9, s9, 28
	v_or_b32_e32 v57, s11, v3
	v_or_b32_e32 v59, s13, v3
	v_or_b32_e32 v60, s14, v2
	v_lshlrev_b64 v[50:51], 14, v[0:1]
	v_add_u32_e32 v0, s1, v58
	v_mov_b32_e32 v35, v1
	v_mov_b32_e32 v37, v1
	v_mov_b32_e32 v39, v1
	s_add_i32 s18, s10, 16
	v_add_u32_e32 v34, s5, v33
	v_or_b32_e32 v61, s15, v3
	v_or_b32_e32 v62, s16, v2
	v_or_b32_e32 v63, s17, v3
	v_or_b32_e32 v65, s19, v3
	v_or_b32_e32 v67, s21, v3
	v_or_b32_e32 v69, s9, v3
	v_add_u32_e32 v36, s5, v57
	v_add_u32_e32 v38, s5, v59
	v_lshlrev_b64 v[52:53], 14, v[0:1]
	v_add_u32_e32 v0, s1, v60
	v_mov_b32_e32 v41, v1
	v_mov_b32_e32 v43, v1
	v_mov_b32_e32 v45, v1
	v_mov_b32_e32 v47, v1
	v_mov_b32_e32 v49, v1
	s_add_i32 s20, s10, 20
	v_or_b32_e32 v64, s18, v2
	v_lshlrev_b64 v[34:35], 14, v[34:35]
	v_add_u32_e32 v40, s5, v61
	v_add_u32_e32 v42, s5, v63
	v_add_u32_e32 v44, s5, v65
	v_add_u32_e32 v46, s5, v67
	v_add_u32_e32 v48, s5, v69
	v_lshl_add_u64 v[50:51], v[28:29], 0, v[50:51]
	v_lshlrev_b64 v[36:37], 14, v[36:37]
	v_lshlrev_b64 v[38:39], 14, v[38:39]
	v_lshlrev_b64 v[54:55], 14, v[0:1]
	v_add_u32_e32 v0, s1, v62
	s_add_i32 s22, s10, 24
	v_or_b32_e32 v66, s20, v2
	v_lshl_add_u64 v[34:35], v[28:29], 0, v[34:35]
	v_lshlrev_b64 v[40:41], 14, v[40:41]
	v_lshlrev_b64 v[42:43], 14, v[42:43]
	v_lshlrev_b64 v[44:45], 14, v[44:45]
	v_lshlrev_b64 v[46:47], 14, v[46:47]
	v_lshlrev_b64 v[48:49], 14, v[48:49]
	v_lshl_add_u64 v[52:53], v[28:29], 0, v[52:53]
	v_lshl_add_u64 v[36:37], v[28:29], 0, v[36:37]
	v_lshl_add_u64 v[38:39], v[28:29], 0, v[38:39]
	global_load_dword v71, v[50:51], off nt
	global_load_dword v72, v[34:35], off nt
	v_lshlrev_b64 v[50:51], 14, v[0:1]
	v_add_u32_e32 v0, s1, v64
	s_add_i32 s10, s10, 28
	v_or_b32_e32 v68, s22, v2
	v_lshl_add_u64 v[40:41], v[28:29], 0, v[40:41]
	v_lshl_add_u64 v[42:43], v[28:29], 0, v[42:43]
	v_lshl_add_u64 v[44:45], v[28:29], 0, v[44:45]
	v_lshl_add_u64 v[46:47], v[28:29], 0, v[46:47]
	v_lshl_add_u64 v[48:49], v[28:29], 0, v[48:49]
	global_load_dword v73, v[52:53], off nt
	global_load_dword v74, v[36:37], off nt
	global_load_dword v75, v[38:39], off nt
	global_load_dword v76, v[40:41], off nt
	global_load_dword v77, v[42:43], off nt
	global_load_dword v78, v[44:45], off nt
	global_load_dword v79, v[46:47], off nt
	global_load_dword v80, v[48:49], off nt
	v_lshl_add_u64 v[36:37], v[28:29], 0, v[50:51]
	v_lshlrev_b64 v[38:39], 14, v[0:1]
	v_add_u32_e32 v0, s1, v66
	v_or_b32_e32 v70, s10, v2
	v_lshl_add_u64 v[34:35], v[28:29], 0, v[54:55]
	global_load_dword v81, v[36:37], off nt
	global_load_dword v82, v[34:35], off nt
	v_lshlrev_b64 v[36:37], 14, v[0:1]
	v_add_u32_e32 v0, s1, v68
	v_lshl_add_u64 v[34:35], v[28:29], 0, v[38:39]
	v_lshlrev_b64 v[38:39], 14, v[0:1]
	v_add_u32_e32 v0, s1, v70
	v_lshlrev_b64 v[40:41], 14, v[0:1]
	v_lshl_add_u64 v[40:41], v[28:29], 0, v[40:41]
	v_lshl_add_u64 v[36:37], v[28:29], 0, v[36:37]
	v_lshl_add_u64 v[38:39], v[28:29], 0, v[38:39]
	global_load_dword v0, v[40:41], off nt
	global_load_dword v83, v[38:39], off nt
	global_load_dword v84, v[36:37], off nt
	global_load_dword v85, v[34:35], off nt
	s_add_i32 s7, s7, 16
	s_add_i32 s4, s4, 16
	s_add_i32 s8, s8, -16
	v_mad_u64_u32 v[34:35], s[10:11], v56, s33, v[6:7]
	s_cmp_lg_u32 s8, 0
	v_mad_u64_u32 v[36:37], s[10:11], v33, s33, v[6:7]
	v_mad_u64_u32 v[38:39], s[10:11], v58, s33, v[6:7]
	v_mad_u64_u32 v[40:41], s[10:11], v57, s33, v[6:7]
	v_mad_u64_u32 v[42:43], s[10:11], v60, s33, v[6:7]
	v_mad_u64_u32 v[44:45], s[10:11], v59, s33, v[6:7]
	v_mad_u64_u32 v[46:47], s[10:11], v62, s33, v[6:7]
	v_mad_u64_u32 v[48:49], s[10:11], v61, s33, v[6:7]
	v_mad_u64_u32 v[50:51], s[10:11], v64, s33, v[6:7]
	v_mad_u64_u32 v[52:53], s[10:11], v63, s33, v[6:7]
	v_mad_u64_u32 v[54:55], s[10:11], v66, s33, v[6:7]
	v_mad_u64_u32 v[56:57], s[10:11], v65, s33, v[6:7]
	v_mad_u64_u32 v[58:59], s[10:11], v68, s33, v[6:7]
	v_mad_u64_u32 v[60:61], s[10:11], v67, s33, v[6:7]
	v_mad_u64_u32 v[62:63], s[10:11], v70, s33, v[6:7]
	v_mad_u64_u32 v[64:65], s[10:11], v69, s33, v[6:7]
	s_waitcnt vmcnt(15)
	ds_write_b32 v34, v71
	s_waitcnt vmcnt(14)
	ds_write_b32 v36, v72
	s_waitcnt vmcnt(13)
	ds_write_b32 v38, v73
	s_waitcnt vmcnt(12)
	ds_write_b32 v40, v74
	s_waitcnt vmcnt(4)
	ds_write_b32 v42, v82
	ds_write_b32 v44, v75
	ds_write_b32 v46, v81
	ds_write_b32 v48, v76
	s_waitcnt vmcnt(0)
	ds_write_b32 v50, v85
	ds_write_b32 v52, v77
	ds_write_b32 v54, v84
	ds_write_b32 v56, v78
	ds_write_b32 v58, v83
	ds_write_b32 v60, v79
	ds_write_b32 v62, v0
	ds_write_b32 v64, v80
	s_cbranch_scc1 .LBB0_1179
; #define GAS __attribute__((address_space(1)))
; #define LAS __attribute__((address_space(3)))
; __device__ __forceinline__ unsigned pk2(float lo, float hi) { return f2bf(lo) | (f2bf(hi) << 16); }
; __device__ __forceinline__ unsigned pk4f8(float a, float b, float c, float d) { int w = 0; w = __builtin_amdgcn_cvt_pk_fp8_f32(a, b, w, false); w = __builtin_amdgcn_cvt_pk_fp8_f32(c, d, w, true); return (unsigned)w; }
; __device__ __forceinline__ void p0_transpose_item(const float* W, int K, int N, bf16* WT, int pmode, LAS float* scr, int item, int lane, bool f8 = false) {
;     ...
;     const int c = lane & 7;
; #pragma unroll
;     for (int j = 0; j < 4; ++j) { const int n = (lane >> 3) + 8 * j; const LAS float* s = scr + (8 * c) * 33 + n;
;         if (f8) {
;             v2u o; o.x = pk4f8(s[0 * 33] * 32.f, s[1 * 33] * 32.f, s[2 * 33] * 32.f, s[3 * 33] * 32.f); o.y = pk4f8(s[4 * 33] * 32.f, s[5 * 33] * 32.f, s[6 * 33] * 32.f, s[7 * 33] * 32.f);
;             *(GAS v2u*)((unsigned char*)WT + (size_t)(r0 + n) * K + k0 + 8 * c) = o; continue; }
;         v4u o; o.x = pk2(s[0 * 33], s[1 * 33]); o.y = pk2(s[2 * 33], s[3 * 33]); o.z = pk2(s[4 * 33], s[5 * 33]); o.w = pk2(s[6 * 33], s[7 * 33]);
;         *(GAS v4u*)(WT + (size_t)(r0 + n) * K + k0 + 8 * c) = o; }
	s_waitcnt lgkmcnt(0)
	ds_read2_b32 v[28:29], v7 offset1:8
	ds_read2_b32 v[40:41], v7 offset0:33 offset1:41
	ds_read2_b32 v[42:43], v7 offset0:66 offset1:74
	v_readlane_b32 s4, v243, 9
	v_readlane_b32 s5, v243, 10
	s_lshl_b32 s4, s1, 1
	ds_read2_b32 v[44:45], v7 offset0:99 offset1:107
	s_mov_b32 s1, s5
	v_lshl_add_u64 v[38:39], v[22:23], 0, s[4:5]
	s_waitcnt lgkmcnt(3)
	v_bfe_u32 v0, v28, 16, 1
	s_movk_i32 s4, 0x7fff
	v_writelane_b32 v243, s0, 9
	v_add3_u32 v0, v28, v0, s4
	s_waitcnt lgkmcnt(2)
	v_bfe_u32 v28, v40, 16, 1
	ds_read2_b32 v[46:47], v7 offset0:132 offset1:140
	v_writelane_b32 v243, s1, 10
	v_lshrrev_b32_e32 v0, 16, v0
	v_add3_u32 v28, v40, v28, s4
	s_mov_b32 s1, 0xffff0000
	ds_read2_b32 v[48:49], v7 offset0:165 offset1:173
	v_and_or_b32 v34, v28, s1, v0
	s_waitcnt lgkmcnt(3)
	v_bfe_u32 v0, v42, 16, 1
	v_add3_u32 v0, v42, v0, s4
	s_waitcnt lgkmcnt(2)
	v_bfe_u32 v28, v44, 16, 1
	ds_read2_b32 v[50:51], v7 offset0:198 offset1:206
	v_lshrrev_b32_e32 v0, 16, v0
	v_add3_u32 v28, v44, v28, s4
	ds_read2_b32 v[52:53], v7 offset0:231 offset1:239
	v_and_or_b32 v35, v28, s1, v0
	s_waitcnt lgkmcnt(3)
	v_bfe_u32 v0, v46, 16, 1
	v_add3_u32 v0, v46, v0, s4
	s_waitcnt lgkmcnt(2)
	v_bfe_u32 v28, v48, 16, 1
	v_lshrrev_b32_e32 v0, 16, v0
	v_add3_u32 v28, v48, v28, s4
	v_and_or_b32 v36, v28, s1, v0
	s_waitcnt lgkmcnt(1)
	v_bfe_u32 v0, v50, 16, 1
	v_add3_u32 v0, v50, v0, s4
	s_waitcnt lgkmcnt(0)
	v_bfe_u32 v28, v52, 16, 1
	v_lshrrev_b32_e32 v0, 16, v0
	v_add3_u32 v28, v52, v28, s4
	v_and_or_b32 v37, v28, s1, v0
	v_or_b32_e32 v0, s0, v5
	v_lshlrev_b32_e32 v0, 11, v0
	v_lshl_add_u64 v[54:55], v[38:39], 0, v[0:1]
	v_bfe_u32 v0, v29, 16, 1
	v_add3_u32 v0, v29, v0, s4
	v_bfe_u32 v28, v41, 16, 1
	v_lshrrev_b32_e32 v0, 16, v0
	v_add3_u32 v28, v41, v28, s4
	global_store_dwordx4 v[54:55], v[34:37], off
	s_nop 1
	v_and_or_b32 v34, v28, s1, v0
	v_bfe_u32 v0, v43, 16, 1
	v_add3_u32 v0, v43, v0, s4
	v_bfe_u32 v28, v45, 16, 1
	v_lshrrev_b32_e32 v0, 16, v0
	v_add3_u32 v28, v45, v28, s4
	v_and_or_b32 v35, v28, s1, v0
	v_bfe_u32 v0, v47, 16, 1
	v_add3_u32 v0, v47, v0, s4
	v_bfe_u32 v28, v49, 16, 1
	v_lshrrev_b32_e32 v0, 16, v0
	v_add3_u32 v28, v49, v28, s4
	v_and_or_b32 v36, v28, s1, v0
	v_bfe_u32 v0, v51, 16, 1
	v_add3_u32 v0, v51, v0, s4
	v_bfe_u32 v28, v53, 16, 1
	v_lshrrev_b32_e32 v0, 16, v0
	v_add3_u32 v28, v53, v28, s4
	v_and_or_b32 v37, v28, s1, v0
	v_or_b32_e32 v0, s0, v30
	v_lshlrev_b32_e32 v0, 11, v0
	ds_read2_b32 v[28:29], v7 offset0:16 offset1:24
	v_lshl_add_u64 v[40:41], v[38:39], 0, v[0:1]
	global_store_dwordx4 v[40:41], v[34:37], off
	ds_read2_b32 v[40:41], v7 offset0:49 offset1:57
	ds_read2_b32 v[42:43], v7 offset0:82 offset1:90
	ds_read2_b32 v[44:45], v7 offset0:115 offset1:123
	s_waitcnt lgkmcnt(3)
	v_bfe_u32 v0, v28, 16, 1
	v_add3_u32 v0, v28, v0, s4
	s_waitcnt lgkmcnt(2)
	v_bfe_u32 v28, v40, 16, 1
	ds_read2_b32 v[46:47], v7 offset0:148 offset1:156
	v_lshrrev_b32_e32 v0, 16, v0
	v_add3_u32 v28, v40, v28, s4
	ds_read2_b32 v[48:49], v7 offset0:181 offset1:189
	v_and_or_b32 v34, v28, s1, v0
	s_waitcnt lgkmcnt(3)
	v_bfe_u32 v0, v42, 16, 1
	v_add3_u32 v0, v42, v0, s4
	s_waitcnt lgkmcnt(2)
	v_bfe_u32 v28, v44, 16, 1
	ds_read2_b32 v[50:51], v7 offset0:214 offset1:222
	v_lshrrev_b32_e32 v0, 16, v0
	v_add3_u32 v28, v44, v28, s4
	ds_read2_b32 v[52:53], v7 offset0:247 offset1:255
	v_and_or_b32 v35, v28, s1, v0
	s_waitcnt lgkmcnt(3)
	v_bfe_u32 v0, v46, 16, 1
	v_add3_u32 v0, v46, v0, s4
	s_waitcnt lgkmcnt(2)
	v_bfe_u32 v28, v48, 16, 1
	v_lshrrev_b32_e32 v0, 16, v0
	v_add3_u32 v28, v48, v28, s4
	v_and_or_b32 v36, v28, s1, v0
	s_waitcnt lgkmcnt(1)
	v_bfe_u32 v0, v50, 16, 1
	v_add3_u32 v0, v50, v0, s4
	s_waitcnt lgkmcnt(0)
	v_bfe_u32 v28, v52, 16, 1
	v_lshrrev_b32_e32 v0, 16, v0
	v_add3_u32 v28, v52, v28, s4
	v_and_or_b32 v37, v28, s1, v0
	v_or_b32_e32 v0, s0, v31
	v_lshlrev_b32_e32 v0, 11, v0
	v_lshl_add_u64 v[54:55], v[38:39], 0, v[0:1]
	v_bfe_u32 v0, v29, 16, 1
	v_add3_u32 v0, v29, v0, s4
	v_bfe_u32 v28, v41, 16, 1
	v_lshrrev_b32_e32 v0, 16, v0
	v_add3_u32 v28, v41, v28, s4
	global_store_dwordx4 v[54:55], v[34:37], off
	s_nop 1
	v_and_or_b32 v34, v28, s1, v0
	v_bfe_u32 v0, v43, 16, 1
	v_add3_u32 v0, v43, v0, s4
	v_bfe_u32 v28, v45, 16, 1
	v_lshrrev_b32_e32 v0, 16, v0
	v_add3_u32 v28, v45, v28, s4
	v_and_or_b32 v35, v28, s1, v0
	v_bfe_u32 v0, v47, 16, 1
	v_add3_u32 v0, v47, v0, s4
	v_bfe_u32 v28, v49, 16, 1
	v_lshrrev_b32_e32 v0, 16, v0
	v_add3_u32 v28, v49, v28, s4
	v_and_or_b32 v36, v28, s1, v0
	v_bfe_u32 v0, v51, 16, 1
	v_add3_u32 v0, v51, v0, s4
	v_bfe_u32 v28, v53, 16, 1
	v_lshrrev_b32_e32 v0, 16, v0
	v_add3_u32 v28, v53, v28, s4
	v_and_or_b32 v37, v28, s1, v0
	v_or_b32_e32 v0, s0, v32
	v_lshlrev_b32_e32 v0, 11, v0
	v_lshl_add_u64 v[28:29], v[38:39], 0, v[0:1]
	global_store_dwordx4 v[28:29], v[34:37], off
	s_waitcnt lgkmcnt(0)

; __device__ __forceinline__ void p0_transpose_item(const float* W, int K, int N, bf16* WT, int pmode, LAS float* scr, int item, int lane, bool f8 = false) {
;     ...
; #pragma unroll 8
;     for (int i = 0; i < 32; ++i) { const int kk = 2 * i + (lane >> 5); scr[kk * 33 + (lane & 31)] = W[(size_t)(k0 + kk) * N + n0 + (lane & 31)]; }
.LBB0_1184:
	s_lshl_b32 s10, s7, 1
	s_lshl_b32 s9, s4, 1
	v_or_b32_e32 v56, s10, v2
	s_add_i32 s12, s10, 4
	s_add_i32 s11, s9, 4
	s_add_i32 s13, s9, 8
	s_add_i32 s14, s10, 8
	v_add_u32_e32 v0, s1, v56
	v_or_b32_e32 v58, s12, v2
	v_or_b32_e32 v33, s9, v3
	s_add_i32 s15, s9, 12
	s_add_i32 s16, s10, 12
	s_add_i32 s17, s9, 16
	s_add_i32 s19, s9, 20
	s_add_i32 s21, s9, 24
	s_add_i32 s9, s9, 28
	v_or_b32_e32 v57, s11, v3
	v_or_b32_e32 v59, s13, v3
	v_or_b32_e32 v60, s14, v2
	v_lshlrev_b64 v[50:51], 12, v[0:1]
	v_add_u32_e32 v0, s1, v58
	v_mov_b32_e32 v35, v1
	v_mov_b32_e32 v37, v1
	v_mov_b32_e32 v39, v1
	s_add_i32 s18, s10, 16
	v_add_u32_e32 v34, s5, v33
	v_or_b32_e32 v61, s15, v3
	v_or_b32_e32 v62, s16, v2
	v_or_b32_e32 v63, s17, v3
	v_or_b32_e32 v65, s19, v3
	v_or_b32_e32 v67, s21, v3
	v_or_b32_e32 v69, s9, v3
	v_add_u32_e32 v36, s5, v57
	v_add_u32_e32 v38, s5, v59
	v_lshlrev_b64 v[52:53], 12, v[0:1]
	v_add_u32_e32 v0, s1, v60
	v_mov_b32_e32 v41, v1
	v_mov_b32_e32 v43, v1
	v_mov_b32_e32 v45, v1
	v_mov_b32_e32 v47, v1
	v_mov_b32_e32 v49, v1
	s_add_i32 s20, s10, 20
	v_or_b32_e32 v64, s18, v2
	v_lshlrev_b64 v[34:35], 12, v[34:35]
	v_add_u32_e32 v40, s5, v61
	v_add_u32_e32 v42, s5, v63
	v_add_u32_e32 v44, s5, v65
	v_add_u32_e32 v46, s5, v67
	v_add_u32_e32 v48, s5, v69
	v_lshl_add_u64 v[50:51], v[28:29], 0, v[50:51]
	v_lshlrev_b64 v[36:37], 12, v[36:37]
	v_lshlrev_b64 v[38:39], 12, v[38:39]
	v_lshlrev_b64 v[54:55], 12, v[0:1]
	v_add_u32_e32 v0, s1, v62
	s_add_i32 s22, s10, 24
	v_or_b32_e32 v66, s20, v2
	v_lshl_add_u64 v[34:35], v[28:29], 0, v[34:35]
	v_lshlrev_b64 v[40:41], 12, v[40:41]
	v_lshlrev_b64 v[42:43], 12, v[42:43]
	v_lshlrev_b64 v[44:45], 12, v[44:45]
	v_lshlrev_b64 v[46:47], 12, v[46:47]
	v_lshlrev_b64 v[48:49], 12, v[48:49]
	v_lshl_add_u64 v[52:53], v[28:29], 0, v[52:53]
	v_lshl_add_u64 v[36:37], v[28:29], 0, v[36:37]
	v_lshl_add_u64 v[38:39], v[28:29], 0, v[38:39]
	global_load_dword v71, v[50:51], off nt
	global_load_dword v72, v[34:35], off nt
	v_lshlrev_b64 v[50:51], 12, v[0:1]
	v_add_u32_e32 v0, s1, v64
	s_add_i32 s10, s10, 28
	v_or_b32_e32 v68, s22, v2
	v_lshl_add_u64 v[40:41], v[28:29], 0, v[40:41]
	v_lshl_add_u64 v[42:43], v[28:29], 0, v[42:43]
	v_lshl_add_u64 v[44:45], v[28:29], 0, v[44:45]
	v_lshl_add_u64 v[46:47], v[28:29], 0, v[46:47]
	v_lshl_add_u64 v[48:49], v[28:29], 0, v[48:49]
	global_load_dword v73, v[52:53], off nt
	global_load_dword v74, v[36:37], off nt
	global_load_dword v75, v[38:39], off nt
	global_load_dword v76, v[40:41], off nt
	global_load_dword v77, v[42:43], off nt
	global_load_dword v78, v[44:45], off nt
	global_load_dword v79, v[46:47], off nt
	global_load_dword v80, v[48:49], off nt
	v_lshl_add_u64 v[36:37], v[28:29], 0, v[50:51]
	v_lshlrev_b64 v[38:39], 12, v[0:1]
	v_add_u32_e32 v0, s1, v66
	v_or_b32_e32 v70, s10, v2
	v_lshl_add_u64 v[34:35], v[28:29], 0, v[54:55]
	global_load_dword v81, v[36:37], off nt
	global_load_dword v82, v[34:35], off nt
	v_lshlrev_b64 v[36:37], 12, v[0:1]
	v_add_u32_e32 v0, s1, v68
	v_lshl_add_u64 v[34:35], v[28:29], 0, v[38:39]
	v_lshlrev_b64 v[38:39], 12, v[0:1]
	v_add_u32_e32 v0, s1, v70
	v_lshlrev_b64 v[40:41], 12, v[0:1]
	v_lshl_add_u64 v[40:41], v[28:29], 0, v[40:41]
	v_lshl_add_u64 v[36:37], v[28:29], 0, v[36:37]
	v_lshl_add_u64 v[38:39], v[28:29], 0, v[38:39]
	global_load_dword v0, v[40:41], off nt
	global_load_dword v83, v[38:39], off nt
	global_load_dword v84, v[36:37], off nt
	global_load_dword v85, v[34:35], off nt
	s_add_i32 s7, s7, 16
	s_add_i32 s4, s4, 16
	s_add_i32 s8, s8, -16
	v_mad_u64_u32 v[34:35], s[10:11], v56, s33, v[6:7]
	s_cmp_lg_u32 s8, 0
	v_mad_u64_u32 v[36:37], s[10:11], v33, s33, v[6:7]
	v_mad_u64_u32 v[38:39], s[10:11], v58, s33, v[6:7]
	v_mad_u64_u32 v[40:41], s[10:11], v57, s33, v[6:7]
	v_mad_u64_u32 v[42:43], s[10:11], v60, s33, v[6:7]
	v_mad_u64_u32 v[44:45], s[10:11], v59, s33, v[6:7]
	v_mad_u64_u32 v[46:47], s[10:11], v62, s33, v[6:7]
	v_mad_u64_u32 v[48:49], s[10:11], v61, s33, v[6:7]
	v_mad_u64_u32 v[50:51], s[10:11], v64, s33, v[6:7]
	v_mad_u64_u32 v[52:53], s[10:11], v63, s33, v[6:7]
	v_mad_u64_u32 v[54:55], s[10:11], v66, s33, v[6:7]
	v_mad_u64_u32 v[56:57], s[10:11], v65, s33, v[6:7]
	v_mad_u64_u32 v[58:59], s[10:11], v68, s33, v[6:7]
	v_mad_u64_u32 v[60:61], s[10:11], v67, s33, v[6:7]
	v_mad_u64_u32 v[62:63], s[10:11], v70, s33, v[6:7]
	v_mad_u64_u32 v[64:65], s[10:11], v69, s33, v[6:7]
	s_waitcnt vmcnt(15)
	ds_write_b32 v34, v71
	s_waitcnt vmcnt(14)
	ds_write_b32 v36, v72
	s_waitcnt vmcnt(13)
	ds_write_b32 v38, v73
	s_waitcnt vmcnt(12)
	ds_write_b32 v40, v74
	s_waitcnt vmcnt(4)
	ds_write_b32 v42, v82
	ds_write_b32 v44, v75
	ds_write_b32 v46, v81
	ds_write_b32 v48, v76
	s_waitcnt vmcnt(0)
	ds_write_b32 v50, v85
	ds_write_b32 v52, v77
	ds_write_b32 v54, v84
	ds_write_b32 v56, v78
	ds_write_b32 v58, v83
	ds_write_b32 v60, v79
	ds_write_b32 v62, v0
	ds_write_b32 v64, v80
	s_cbranch_scc1 .LBB0_1184
; #define GAS __attribute__((address_space(1)))
; #define LAS __attribute__((address_space(3)))
; __device__ __forceinline__ unsigned pk2(float lo, float hi) { return f2bf(lo) | (f2bf(hi) << 16); }
; __device__ __forceinline__ unsigned pk4f8(float a, float b, float c, float d) { int w = 0; w = __builtin_amdgcn_cvt_pk_fp8_f32(a, b, w, false); w = __builtin_amdgcn_cvt_pk_fp8_f32(c, d, w, true); return (unsigned)w; }
; __device__ __forceinline__ void p0_transpose_item(const float* W, int K, int N, bf16* WT, int pmode, LAS float* scr, int item, int lane, bool f8 = false) {
;     ...
;     const int c = lane & 7;
; #pragma unroll
;     for (int j = 0; j < 4; ++j) { const int n = (lane >> 3) + 8 * j; const LAS float* s = scr + (8 * c) * 33 + n;
;         if (f8) {
;             v2u o; o.x = pk4f8(s[0 * 33] * 32.f, s[1 * 33] * 32.f, s[2 * 33] * 32.f, s[3 * 33] * 32.f); o.y = pk4f8(s[4 * 33] * 32.f, s[5 * 33] * 32.f, s[6 * 33] * 32.f, s[7 * 33] * 32.f);
;             *(GAS v2u*)((unsigned char*)WT + (size_t)(r0 + n) * K + k0 + 8 * c) = o; continue; }
;         v4u o; o.x = pk2(s[0 * 33], s[1 * 33]); o.y = pk2(s[2 * 33], s[3 * 33]); o.z = pk2(s[4 * 33], s[5 * 33]); o.w = pk2(s[6 * 33], s[7 * 33]);
;         *(GAS v4u*)(WT + (size_t)(r0 + n) * K + k0 + 8 * c) = o; }
	s_waitcnt lgkmcnt(0)
	ds_read2_b32 v[28:29], v7 offset1:8
	ds_read2_b32 v[40:41], v7 offset0:33 offset1:41
	ds_read2_b32 v[42:43], v7 offset0:66 offset1:74
	v_readlane_b32 s4, v243, 9
	v_readlane_b32 s5, v243, 10
	s_lshl_b32 s4, s1, 1
	ds_read2_b32 v[44:45], v7 offset0:99 offset1:107
	s_mov_b32 s1, s5
	v_lshl_add_u64 v[38:39], v[24:25], 0, s[4:5]
	s_waitcnt lgkmcnt(3)
	v_bfe_u32 v0, v28, 16, 1
	s_movk_i32 s4, 0x7fff
	v_writelane_b32 v243, s0, 9
	v_add3_u32 v0, v28, v0, s4
	s_waitcnt lgkmcnt(2)
	v_bfe_u32 v28, v40, 16, 1
	ds_read2_b32 v[46:47], v7 offset0:132 offset1:140
	v_writelane_b32 v243, s1, 10
	v_lshrrev_b32_e32 v0, 16, v0
	v_add3_u32 v28, v40, v28, s4
	s_mov_b32 s1, 0xffff0000
	ds_read2_b32 v[48:49], v7 offset0:165 offset1:173
	v_and_or_b32 v34, v28, s1, v0
	s_waitcnt lgkmcnt(3)
	v_bfe_u32 v0, v42, 16, 1
	v_add3_u32 v0, v42, v0, s4
	s_waitcnt lgkmcnt(2)
	v_bfe_u32 v28, v44, 16, 1
	ds_read2_b32 v[50:51], v7 offset0:198 offset1:206
	v_lshrrev_b32_e32 v0, 16, v0
	v_add3_u32 v28, v44, v28, s4
	ds_read2_b32 v[52:53], v7 offset0:231 offset1:239
	v_and_or_b32 v35, v28, s1, v0
	s_waitcnt lgkmcnt(3)
	v_bfe_u32 v0, v46, 16, 1
	v_add3_u32 v0, v46, v0, s4
	s_waitcnt lgkmcnt(2)
	v_bfe_u32 v28, v48, 16, 1
	v_lshrrev_b32_e32 v0, 16, v0
	v_add3_u32 v28, v48, v28, s4
	v_and_or_b32 v36, v28, s1, v0
	s_waitcnt lgkmcnt(1)
	v_bfe_u32 v0, v50, 16, 1
	v_add3_u32 v0, v50, v0, s4
	s_waitcnt lgkmcnt(0)
	v_bfe_u32 v28, v52, 16, 1
	v_lshrrev_b32_e32 v0, 16, v0
	v_add3_u32 v28, v52, v28, s4
	v_and_or_b32 v37, v28, s1, v0
	v_or_b32_e32 v0, s0, v5
	v_lshlrev_b32_e32 v0, 11, v0
	v_lshl_add_u64 v[54:55], v[38:39], 0, v[0:1]
	v_bfe_u32 v0, v29, 16, 1
	v_add3_u32 v0, v29, v0, s4
	v_bfe_u32 v28, v41, 16, 1
	v_lshrrev_b32_e32 v0, 16, v0
	v_add3_u32 v28, v41, v28, s4
	global_store_dwordx4 v[54:55], v[34:37], off
	s_nop 1
	v_and_or_b32 v34, v28, s1, v0
	v_bfe_u32 v0, v43, 16, 1
	v_add3_u32 v0, v43, v0, s4
	v_bfe_u32 v28, v45, 16, 1
	v_lshrrev_b32_e32 v0, 16, v0
	v_add3_u32 v28, v45, v28, s4
	v_and_or_b32 v35, v28, s1, v0
	v_bfe_u32 v0, v47, 16, 1
	v_add3_u32 v0, v47, v0, s4
	v_bfe_u32 v28, v49, 16, 1
	v_lshrrev_b32_e32 v0, 16, v0
	v_add3_u32 v28, v49, v28, s4
	v_and_or_b32 v36, v28, s1, v0
	v_bfe_u32 v0, v51, 16, 1
	v_add3_u32 v0, v51, v0, s4
	v_bfe_u32 v28, v53, 16, 1
	v_lshrrev_b32_e32 v0, 16, v0
	v_add3_u32 v28, v53, v28, s4
	v_and_or_b32 v37, v28, s1, v0
	v_or_b32_e32 v0, s0, v30
	v_lshlrev_b32_e32 v0, 11, v0
	ds_read2_b32 v[28:29], v7 offset0:16 offset1:24
	v_lshl_add_u64 v[40:41], v[38:39], 0, v[0:1]
	global_store_dwordx4 v[40:41], v[34:37], off
	ds_read2_b32 v[40:41], v7 offset0:49 offset1:57
	ds_read2_b32 v[42:43], v7 offset0:82 offset1:90
	ds_read2_b32 v[44:45], v7 offset0:115 offset1:123
	s_waitcnt lgkmcnt(3)
	v_bfe_u32 v0, v28, 16, 1
	v_add3_u32 v0, v28, v0, s4
	s_waitcnt lgkmcnt(2)
	v_bfe_u32 v28, v40, 16, 1
	ds_read2_b32 v[46:47], v7 offset0:148 offset1:156
	v_lshrrev_b32_e32 v0, 16, v0
	v_add3_u32 v28, v40, v28, s4
	ds_read2_b32 v[48:49], v7 offset0:181 offset1:189
	v_and_or_b32 v34, v28, s1, v0
	s_waitcnt lgkmcnt(3)
	v_bfe_u32 v0, v42, 16, 1
	v_add3_u32 v0, v42, v0, s4
	s_waitcnt lgkmcnt(2)
	v_bfe_u32 v28, v44, 16, 1
	ds_read2_b32 v[50:51], v7 offset0:214 offset1:222
	v_lshrrev_b32_e32 v0, 16, v0
	v_add3_u32 v28, v44, v28, s4
	ds_read2_b32 v[52:53], v7 offset0:247 offset1:255
	v_and_or_b32 v35, v28, s1, v0
	s_waitcnt lgkmcnt(3)
	v_bfe_u32 v0, v46, 16, 1
	v_add3_u32 v0, v46, v0, s4
	s_waitcnt lgkmcnt(2)
	v_bfe_u32 v28, v48, 16, 1
	v_lshrrev_b32_e32 v0, 16, v0
	v_add3_u32 v28, v48, v28, s4
	v_and_or_b32 v36, v28, s1, v0
	s_waitcnt lgkmcnt(1)
	v_bfe_u32 v0, v50, 16, 1
	v_add3_u32 v0, v50, v0, s4
	s_waitcnt lgkmcnt(0)
	v_bfe_u32 v28, v52, 16, 1
	v_lshrrev_b32_e32 v0, 16, v0
	v_add3_u32 v28, v52, v28, s4
	v_and_or_b32 v37, v28, s1, v0
	v_or_b32_e32 v0, s0, v31
	v_lshlrev_b32_e32 v0, 11, v0
	v_lshl_add_u64 v[54:55], v[38:39], 0, v[0:1]
	v_bfe_u32 v0, v29, 16, 1
	v_add3_u32 v0, v29, v0, s4
	v_bfe_u32 v28, v41, 16, 1
	v_lshrrev_b32_e32 v0, 16, v0
	v_add3_u32 v28, v41, v28, s4
	global_store_dwordx4 v[54:55], v[34:37], off
	s_nop 1
	v_and_or_b32 v34, v28, s1, v0
	v_bfe_u32 v0, v43, 16, 1
	v_add3_u32 v0, v43, v0, s4
	v_bfe_u32 v28, v45, 16, 1
	v_lshrrev_b32_e32 v0, 16, v0
	v_add3_u32 v28, v45, v28, s4
	v_and_or_b32 v35, v28, s1, v0
	v_bfe_u32 v0, v47, 16, 1
	v_add3_u32 v0, v47, v0, s4
	v_bfe_u32 v28, v49, 16, 1
	v_lshrrev_b32_e32 v0, 16, v0
	v_add3_u32 v28, v49, v28, s4
	v_and_or_b32 v36, v28, s1, v0
	v_bfe_u32 v0, v51, 16, 1
	v_add3_u32 v0, v51, v0, s4
	v_bfe_u32 v28, v53, 16, 1
	v_lshrrev_b32_e32 v0, 16, v0
	v_add3_u32 v28, v53, v28, s4
	v_and_or_b32 v37, v28, s1, v0
	v_or_b32_e32 v0, s0, v32
	v_lshlrev_b32_e32 v0, 11, v0
	v_lshl_add_u64 v[28:29], v[38:39], 0, v[0:1]
	global_store_dwordx4 v[28:29], v[34:37], off
	s_waitcnt lgkmcnt(0)

; __device__ __forceinline__ void p0_transpose_item(const float* W, int K, int N, bf16* WT, int pmode, LAS float* scr, int item, int lane, bool f8 = false) {
;     ...
; #pragma unroll 8
;     for (int i = 0; i < 32; ++i) { const int kk = 2 * i + (lane >> 5); scr[kk * 33 + (lane & 31)] = W[(size_t)(k0 + kk) * N + n0 + (lane & 31)]; }
.LBB0_1189:
	s_lshl_b32 s9, s5, 1
	s_lshl_b32 s10, s7, 1
	v_or_b32_e32 v0, s9, v3
	v_or_b32_e32 v33, s10, v2
	s_add_i32 s11, s9, 4
	s_add_i32 s12, s10, 4
	s_add_i32 s13, s9, 8
	s_add_i32 s14, s10, 8
	s_add_i32 s15, s9, 12
	s_add_i32 s16, s10, 12
	s_add_i32 s17, s9, 16
	s_add_i32 s18, s10, 16
	s_add_i32 s19, s9, 20
	s_add_i32 s20, s10, 20
	s_add_i32 s21, s9, 24
	s_add_i32 s22, s10, 24
	s_add_i32 s9, s9, 28
	s_add_i32 s10, s10, 28
	v_add_u32_e32 v34, s4, v33
	v_or_b32_e32 v66, s11, v3
	v_or_b32_e32 v67, s12, v2
	v_or_b32_e32 v68, s13, v3
	v_or_b32_e32 v69, s14, v2
	v_or_b32_e32 v70, s15, v3
	v_or_b32_e32 v71, s16, v2
	v_or_b32_e32 v72, s17, v3
	v_or_b32_e32 v73, s18, v2
	v_or_b32_e32 v74, s19, v3
	v_or_b32_e32 v75, s20, v2
	v_or_b32_e32 v76, s21, v3
	v_or_b32_e32 v77, s22, v2
	v_or_b32_e32 v78, s9, v3
	v_or_b32_e32 v79, s10, v2
	v_add_u32_e32 v36, s1, v0
	v_mad_i64_i32 v[34:35], s[10:11], v34, s23, v[28:29]
	v_add_u32_e32 v40, s1, v66
	v_add_u32_e32 v38, s4, v67
	v_add_u32_e32 v44, s1, v68
	v_add_u32_e32 v42, s4, v69
	v_add_u32_e32 v48, s1, v70
	v_add_u32_e32 v46, s4, v71
	v_add_u32_e32 v52, s1, v72
	v_add_u32_e32 v50, s4, v73
	v_add_u32_e32 v56, s1, v74
	v_add_u32_e32 v54, s4, v75
	v_add_u32_e32 v60, s1, v76
	v_add_u32_e32 v58, s4, v77
	v_add_u32_e32 v64, s1, v78
	v_add_u32_e32 v62, s4, v79
	v_mad_i64_i32 v[36:37], s[10:11], v36, s23, v[28:29]
	v_mad_i64_i32 v[38:39], s[10:11], v38, s23, v[28:29]
	v_mad_i64_i32 v[40:41], s[10:11], v40, s23, v[28:29]
	v_mad_i64_i32 v[42:43], s[10:11], v42, s23, v[28:29]
	v_mad_i64_i32 v[44:45], s[10:11], v44, s23, v[28:29]
	v_mad_i64_i32 v[46:47], s[10:11], v46, s23, v[28:29]
	v_mad_i64_i32 v[48:49], s[10:11], v48, s23, v[28:29]
	v_mad_i64_i32 v[50:51], s[10:11], v50, s23, v[28:29]
	v_mad_i64_i32 v[52:53], s[10:11], v52, s23, v[28:29]
	v_mad_i64_i32 v[54:55], s[10:11], v54, s23, v[28:29]
	v_mad_i64_i32 v[56:57], s[10:11], v56, s23, v[28:29]
	v_mad_i64_i32 v[58:59], s[10:11], v58, s23, v[28:29]
	v_mad_i64_i32 v[60:61], s[10:11], v60, s23, v[28:29]
	v_mad_i64_i32 v[62:63], s[10:11], v62, s23, v[28:29]
	v_mad_i64_i32 v[64:65], s[10:11], v64, s23, v[28:29]
	global_load_dword v80, v[34:35], off nt
	global_load_dword v81, v[36:37], off nt
	global_load_dword v82, v[38:39], off nt
	global_load_dword v83, v[40:41], off nt
	global_load_dword v84, v[42:43], off nt
	global_load_dword v85, v[44:45], off nt
	global_load_dword v86, v[46:47], off nt
	global_load_dword v87, v[48:49], off nt
	global_load_dword v88, v[50:51], off nt
	global_load_dword v89, v[52:53], off nt
	global_load_dword v90, v[54:55], off nt
	global_load_dword v91, v[56:57], off nt
	global_load_dword v92, v[58:59], off nt
	global_load_dword v93, v[60:61], off nt
	global_load_dword v94, v[62:63], off nt
	global_load_dword v95, v[64:65], off nt
	s_add_i32 s7, s7, 16
	s_add_i32 s5, s5, 16
	s_add_i32 s8, s8, -16
	v_mad_u64_u32 v[34:35], s[10:11], v33, s33, v[6:7]
	s_cmp_lg_u32 s8, 0
	v_mad_u64_u32 v[36:37], s[10:11], v0, s33, v[6:7]
	v_mad_u64_u32 v[38:39], s[10:11], v67, s33, v[6:7]
	v_mad_u64_u32 v[40:41], s[10:11], v66, s33, v[6:7]
	v_mad_u64_u32 v[42:43], s[10:11], v69, s33, v[6:7]
	v_mad_u64_u32 v[44:45], s[10:11], v68, s33, v[6:7]
	v_mad_u64_u32 v[46:47], s[10:11], v71, s33, v[6:7]
	v_mad_u64_u32 v[48:49], s[10:11], v70, s33, v[6:7]
	v_mad_u64_u32 v[50:51], s[10:11], v73, s33, v[6:7]
	v_mad_u64_u32 v[52:53], s[10:11], v72, s33, v[6:7]
	v_mad_u64_u32 v[54:55], s[10:11], v75, s33, v[6:7]
	v_mad_u64_u32 v[56:57], s[10:11], v74, s33, v[6:7]
	v_mad_u64_u32 v[58:59], s[10:11], v77, s33, v[6:7]
	v_mad_u64_u32 v[60:61], s[10:11], v76, s33, v[6:7]
	v_mad_u64_u32 v[62:63], s[10:11], v79, s33, v[6:7]
	v_mad_u64_u32 v[64:65], s[10:11], v78, s33, v[6:7]
	s_waitcnt vmcnt(15)
	ds_write_b32 v34, v80
	s_waitcnt vmcnt(14)
	ds_write_b32 v36, v81
	s_waitcnt vmcnt(13)
	ds_write_b32 v38, v82
	s_waitcnt vmcnt(12)
	ds_write_b32 v40, v83
	s_waitcnt vmcnt(11)
	ds_write_b32 v42, v84
	s_waitcnt vmcnt(10)
	ds_write_b32 v44, v85
	s_waitcnt vmcnt(9)
	ds_write_b32 v46, v86
	s_waitcnt vmcnt(8)
	ds_write_b32 v48, v87
	s_waitcnt vmcnt(7)
	ds_write_b32 v50, v88
	s_waitcnt vmcnt(6)
	ds_write_b32 v52, v89
	s_waitcnt vmcnt(5)
	ds_write_b32 v54, v90
	s_waitcnt vmcnt(4)
	ds_write_b32 v56, v91
	s_waitcnt vmcnt(3)
	ds_write_b32 v58, v92
	s_waitcnt vmcnt(2)
	ds_write_b32 v60, v93
	s_waitcnt vmcnt(1)
	ds_write_b32 v62, v94
	s_waitcnt vmcnt(0)
	ds_write_b32 v64, v95
	s_cbranch_scc1 .LBB0_1189
; #define GAS __attribute__((address_space(1)))
; #define LAS __attribute__((address_space(3)))
; __device__ __forceinline__ unsigned pk4f8(float a, float b, float c, float d) { int w = 0; w = __builtin_amdgcn_cvt_pk_fp8_f32(a, b, w, false); w = __builtin_amdgcn_cvt_pk_fp8_f32(c, d, w, true); return (unsigned)w; }
; __device__ __forceinline__ void p0_transpose_item(const float* W, int K, int N, bf16* WT, int pmode, LAS float* scr, int item, int lane, bool f8 = false) {
;     ...
;     const int c = lane & 7;
; #pragma unroll
;     for (int j = 0; j < 4; ++j) { const int n = (lane >> 3) + 8 * j; const LAS float* s = scr + (8 * c) * 33 + n;
;         if (f8) {
;             v2u o; o.x = pk4f8(s[0 * 33] * 32.f, s[1 * 33] * 32.f, s[2 * 33] * 32.f, s[3 * 33] * 32.f); o.y = pk4f8(s[4 * 33] * 32.f, s[5 * 33] * 32.f, s[6 * 33] * 32.f, s[7 * 33] * 32.f);
;             *(GAS v2u*)((unsigned char*)WT + (size_t)(r0 + n) * K + k0 + 8 * c) = o; continue; }
	s_waitcnt lgkmcnt(0)
	ds_read2_b32 v[28:29], v7 offset1:8
	ds_read2_b32 v[34:35], v7 offset0:33 offset1:41
	ds_read2_b32 v[36:37], v7 offset0:66 offset1:74
	ds_read2_b32 v[40:41], v7 offset0:99 offset1:107
	ds_read2_b32 v[42:43], v7 offset0:132 offset1:140
	ds_read2_b32 v[44:45], v7 offset0:165 offset1:173
	v_mov_b32_e32 v46, v1
	s_waitcnt lgkmcnt(5)
	v_mul_f32_e32 v0, 0x42000000, v28
	s_waitcnt lgkmcnt(4)
	v_mul_f32_e32 v28, 0x42000000, v34
	ds_read2_b32 v[48:49], v7 offset0:198 offset1:206
	ds_read2_b32 v[50:51], v7 offset0:231 offset1:239
	v_cvt_pk_fp8_f32 v46, v0, v28
	s_waitcnt lgkmcnt(3)
	v_mul_f32_e32 v0, 0x42000000, v42
	s_waitcnt lgkmcnt(2)
	v_mul_f32_e32 v28, 0x42000000, v44
	v_mov_b32_e32 v47, v1
	v_cvt_pk_fp8_f32 v47, v0, v28
	s_waitcnt lgkmcnt(1)
	v_mul_f32_e32 v0, 0x42000000, v48
	s_waitcnt lgkmcnt(0)
	v_mul_f32_e32 v28, 0x42000000, v50
	v_mul_f32_e32 v33, 0x42000000, v36
	v_cvt_pk_fp8_f32 v47, v0, v28 op_sel:[0,0,1]
	v_mul_f32_e32 v0, 0x42000000, v29
	v_mul_f32_e32 v29, 0x42000000, v35
	v_mov_b32_e32 v28, v1
	v_cvt_pk_fp8_f32 v28, v0, v29
	v_mul_f32_e32 v0, 0x42000000, v43
	v_mul_f32_e32 v35, 0x42000000, v45
	v_mov_b32_e32 v29, v1
	v_cvt_pk_fp8_f32 v29, v0, v35
	v_mul_f32_e32 v34, 0x42000000, v40
	v_cvt_pk_fp8_f32 v46, v33, v34 op_sel:[0,0,1]
	v_mul_f32_e32 v33, 0x42000000, v37
	v_mul_f32_e32 v34, 0x42000000, v41
	v_or_b32_e32 v52, s0, v5
	v_cvt_pk_fp8_f32 v28, v33, v34 op_sel:[0,0,1]
	v_mul_f32_e32 v0, 0x42000000, v49
	v_mul_f32_e32 v33, 0x42000000, v51
	s_ashr_i32 s5, s4, 31
	v_ashrrev_i32_e32 v53, 31, v52
	v_cvt_pk_fp8_f32 v29, v0, v33 op_sel:[0,0,1]
	v_or_b32_e32 v34, s0, v30
	v_lshl_add_u64 v[38:39], v[26:27], 0, s[4:5]
	v_lshlrev_b64 v[52:53], 10, v[52:53]
	v_ashrrev_i32_e32 v35, 31, v34
	v_lshl_add_u64 v[52:53], v[38:39], 0, v[52:53]
	v_lshlrev_b64 v[34:35], 10, v[34:35]
	global_store_dwordx2 v[52:53], v[46:47], off
	v_lshl_add_u64 v[34:35], v[38:39], 0, v[34:35]
	ds_read2_b32 v[36:37], v7 offset0:16 offset1:24
	ds_read2_b32 v[40:41], v7 offset0:49 offset1:57
	ds_read2_b32 v[42:43], v7 offset0:82 offset1:90
	global_store_dwordx2 v[34:35], v[28:29], off
	ds_read2_b32 v[28:29], v7 offset0:115 offset1:123
	ds_read2_b32 v[34:35], v7 offset0:148 offset1:156
	ds_read2_b32 v[44:45], v7 offset0:181 offset1:189
	s_waitcnt lgkmcnt(5)
	v_mul_f32_e32 v0, 0x42000000, v36
	s_waitcnt lgkmcnt(4)
	v_mul_f32_e32 v33, 0x42000000, v40
	v_mov_b32_e32 v46, v1
	ds_read2_b32 v[48:49], v7 offset0:214 offset1:222
	ds_read2_b32 v[50:51], v7 offset0:247 offset1:255
	v_cvt_pk_fp8_f32 v46, v0, v33
	s_waitcnt lgkmcnt(3)
	v_mul_f32_e32 v0, 0x42000000, v34
	s_waitcnt lgkmcnt(2)
	v_mul_f32_e32 v33, 0x42000000, v44
	v_mov_b32_e32 v47, v1
	v_cvt_pk_fp8_f32 v47, v0, v33
	v_mul_f32_e32 v36, 0x42000000, v42
	v_mul_f32_e32 v28, 0x42000000, v28
	v_cvt_pk_fp8_f32 v46, v36, v28 op_sel:[0,0,1]
	s_waitcnt lgkmcnt(1)
	v_mul_f32_e32 v0, 0x42000000, v48
	s_waitcnt lgkmcnt(0)
	v_mul_f32_e32 v28, 0x42000000, v50
	v_cvt_pk_fp8_f32 v47, v0, v28 op_sel:[0,0,1]
	v_mul_f32_e32 v0, 0x42000000, v37
	v_mul_f32_e32 v33, 0x42000000, v41
	v_mov_b32_e32 v28, v1
	v_mul_f32_e32 v36, 0x42000000, v29
	v_cvt_pk_fp8_f32 v28, v0, v33
	v_mul_f32_e32 v0, 0x42000000, v35
	v_mul_f32_e32 v33, 0x42000000, v45
	v_mov_b32_e32 v29, v1
	v_cvt_pk_fp8_f32 v29, v0, v33
	v_mul_f32_e32 v34, 0x42000000, v43
	v_mul_f32_e32 v0, 0x42000000, v49
	v_mul_f32_e32 v33, 0x42000000, v51
	v_or_b32_e32 v52, s0, v31
	v_cvt_pk_fp8_f32 v28, v34, v36 op_sel:[0,0,1]
	v_cvt_pk_fp8_f32 v29, v0, v33 op_sel:[0,0,1]
	v_or_b32_e32 v34, s0, v32
	v_ashrrev_i32_e32 v53, 31, v52
	v_ashrrev_i32_e32 v35, 31, v34
	v_lshlrev_b64 v[52:53], 10, v[52:53]
	v_lshlrev_b64 v[34:35], 10, v[34:35]
	v_lshl_add_u64 v[52:53], v[38:39], 0, v[52:53]
	v_lshl_add_u64 v[34:35], v[38:39], 0, v[34:35]
	global_store_dwordx2 v[52:53], v[46:47], off
	global_store_dwordx2 v[34:35], v[28:29], off
	s_waitcnt lgkmcnt(0)
	s_branch .LBB0_1130

; #define GAS __attribute__((address_space(1)))
; #define ARG(k) (ldarg<k>())
; __device__ __forceinline__ float silu_f(float v) { return v / (1.f + __expf(-v)); }
; __device__ __forceinline__ void p0_prologue(Frame& F) {
;     ...
;         for (int it = F.vcu * 3 + (F.wave - 5); it < 2 * 24 * ADA_KS; it += F.G * 3) {
;             const int l = it / (24 * ADA_KS), rem = it % (24 * ADA_KS), cg = rem / ADA_KS, ks = rem % ADA_KS;
;             const float* W = ARG(4) + (size_t)l * DM * 6144 + cg * 256 + 4 * F.lane;
;             f32x4 a0 = {0.f, 0.f, 0.f, 0.f}, a1 = a0, a2 = a0;
;             const int kbeg = ks * (DM / ADA_KS);
; #pragma unroll 8
;             for (int k = kbeg; k < kbeg + DM / ADA_KS; ++k) {
;                 const f32x4 w = *(const GAS f32x4*)(W + (size_t)k * 6144);
;                 const float s0 = silu_f(c[k]), s1 = silu_f(c[DM + k]), s2 = silu_f(cctx[k]);
;                 a0 += w * s0; a1 += w * s1; a2 += w * s2;
;             }
.LBB0_1196:
	s_mov_b32 s5, 0xfffdc000
	v_add_co_u32_e64 v38, s[42:43], s5, v56
	s_mov_b32 s5, 0xfffe2000
	v_add_co_u32_e64 v40, s[44:45], s5, v56
	s_mov_b32 s5, 0xfffe8000
	v_add_co_u32_e64 v42, s[46:47], s5, v56
	s_mov_b32 s5, 0xfffee000
	s_add_u32 s4, s73, s64
	v_add_co_u32_e64 v64, s[48:49], s5, v56
	s_mov_b32 s5, 0xffff4000
	v_add_co_u32_e64 v62, s[50:51], s5, v56
	s_addc_u32 s5, s74, s65
	global_load_dwordx4 v[18:21], v1, s[4:5]
	global_load_dwordx4 v[14:17], v189, s[4:5]
	global_load_dwordx4 v[2:5], v1, s[4:5] offset:16
	s_add_u32 s4, s4, 0x1000
	s_addc_u32 s5, s5, 0
	v_add_co_u32_e32 v6, vcc, 0xfffd6000, v56
	global_load_dwordx4 v[10:13], v1, s[4:5] offset:16
	s_add_u32 s4, s71, s64
	v_addc_co_u32_e32 v7, vcc, -1, v57, vcc
	s_addc_u32 s5, s72, s65
	global_load_dwordx4 v[50:53], v[6:7], off nt
	global_load_dwordx4 v[22:25], v1, s[4:5]
	s_nop 0
	global_load_dwordx4 v[6:9], v1, s[4:5] offset:16
	s_add_u32 s64, s64, 32
	s_addc_u32 s65, s65, 0
	s_cmpk_eq_i32 s64, 0x100
	s_waitcnt vmcnt(6)
	v_mul_f32_e32 v39, 0xbfb8aa3b, v18
	v_mul_f32_e32 v43, 0xbfb8aa3b, v19
	s_waitcnt vmcnt(4)
	v_mul_f32_e32 v60, 0xbfb8aa3b, v5
	v_exp_f32_e32 v39, v39
	v_mul_f32_e32 v48, 0xbfb8aa3b, v17
	v_exp_f32_e32 v43, v43
	v_exp_f32_e32 v60, v60
	v_exp_f32_e32 v48, v48
	v_mul_f32_e32 v46, 0xbfb8aa3b, v16
	v_mul_f32_e32 v59, 0xbfb8aa3b, v4
	v_exp_f32_e32 v46, v46
	v_exp_f32_e32 v59, v59
	s_waitcnt vmcnt(1)
	v_mul_f32_e32 v68, 0xbfb8aa3b, v23
	v_add_f32_e32 v39, 1.0, v39
	s_waitcnt vmcnt(0)
	v_mul_f32_e32 v72, 0xbfb8aa3b, v6
	v_add_f32_e32 v139, 1.0, v43
	v_exp_f32_e32 v43, v68
	v_add_f32_e32 v68, 1.0, v60
	v_div_scale_f32 v60, s[4:5], v39, v39, v18
	v_add_f32_e32 v75, 1.0, v48
	v_exp_f32_e32 v48, v72
	v_rcp_f32_e32 v103, v60
	v_mul_f32_e32 v41, 0xbfb8aa3b, v14
	v_mul_f32_e32 v69, 0xbfb8aa3b, v24
	v_mul_f32_e32 v77, 0xbfb8aa3b, v9
	v_exp_f32_e32 v41, v41
	v_add_f32_e32 v79, 1.0, v46
	v_exp_f32_e32 v46, v69
	v_add_f32_e32 v69, 1.0, v59
	v_exp_f32_e32 v59, v77
	v_add_f32_e32 v90, 1.0, v48
	v_fma_f32 v48, -v60, v103, 1.0
	v_div_scale_f32 v99, vcc, v18, v39, v18
	v_fmac_f32_e32 v103, v48, v103
	v_add_f32_e32 v41, 1.0, v41
	v_add_f32_e32 v77, 1.0, v59
	v_mul_f32_e32 v59, v99, v103
	v_div_scale_f32 v100, s[4:5], v41, v41, v14
	v_fma_f32 v48, -v60, v59, v99
	v_rcp_f32_e32 v104, v100
	v_fmac_f32_e32 v59, v48, v103
	v_mul_f32_e32 v47, 0xbfb8aa3b, v21
	v_mul_f32_e32 v58, 0xbfb8aa3b, v3
	v_fma_f32 v60, -v60, v59, v99
	v_exp_f32_e32 v47, v47
	v_exp_f32_e32 v58, v58
	v_mul_f32_e32 v61, 0xbfb8aa3b, v10
	v_mul_f32_e32 v67, 0xbfb8aa3b, v22
	v_div_fmas_f32 v59, v60, v103, v59
	v_exp_f32_e32 v61, v61
	v_exp_f32_e32 v67, v67
	v_div_fixup_f32 v18, v59, v39, v18
	v_mul_f32_e32 v45, 0xbfb8aa3b, v20
	v_pk_fma_f32 v[34:35], v[50:51], v[18:19], v[34:35] op_sel_hi:[1,0,1]
	v_pk_fma_f32 v[36:37], v[52:53], v[18:19], v[36:37] op_sel_hi:[1,0,1]
	v_fma_f32 v18, -v100, v104, 1.0
	v_exp_f32_e32 v45, v45
	v_mul_f32_e32 v70, 0xbfb8aa3b, v25
	v_div_scale_f32 v101, s[60:61], v14, v41, v14
	v_fmac_f32_e32 v104, v18, v104
	v_add_f32_e32 v76, 1.0, v47
	v_exp_f32_e32 v47, v70
	v_add_f32_e32 v70, 1.0, v58
	v_div_scale_f32 v116, s[4:5], v79, v79, v16
	v_mul_f32_e32 v60, v101, v104
	v_div_scale_f32 v126, s[4:5], v70, v70, v3
	v_rcp_f32_e32 v94, v116
	v_add_f32_e32 v86, 1.0, v61
	v_add_f32_e32 v61, 1.0, v67
	v_fma_f32 v18, -v100, v60, v101
	v_div_scale_f32 v102, s[4:5], v139, v139, v19
	v_rcp_f32_e32 v84, v126
	v_add_f32_e32 v98, 1.0, v43
	v_div_scale_f32 v43, s[22:23], v61, v61, v22
	v_fmac_f32_e32 v60, v18, v104
	v_mul_f32_e32 v74, 0xbfb8aa3b, v8
	v_add_f32_e32 v82, 1.0, v45
	v_div_scale_f32 v121, s[4:5], v75, v75, v17
	v_rcp_f32_e32 v45, v102
	v_rcp_f32_e32 v39, v43
	v_fma_f32 v100, -v100, v60, v101
	s_mov_b64 vcc, s[60:61]
	v_exp_f32_e32 v58, v74
	v_div_scale_f32 v131, s[4:5], v69, v69, v4
	v_rcp_f32_e32 v91, v121
	v_div_fmas_f32 v60, v100, v104, v60
	v_rcp_f32_e32 v78, v131
	v_div_fixup_f32 v14, v60, v41, v14
	v_fma_f32 v41, -v116, v94, 1.0
	v_fmac_f32_e32 v94, v41, v94
	v_fma_f32 v41, -v126, v84, 1.0
	v_fma_f32 v59, -v102, v45, 1.0
	v_fmac_f32_e32 v84, v41, v84
	v_fma_f32 v41, -v43, v39, 1.0
	v_add_f32_e32 v83, 1.0, v58
	v_div_scale_f32 v58, s[62:63], v22, v61, v22
	v_fmac_f32_e32 v45, v59, v45
	v_fma_f32 v59, -v121, v91, 1.0
	v_fmac_f32_e32 v39, v41, v39
	v_div_scale_f32 v118, s[4:5], v76, v76, v21
	v_fmac_f32_e32 v91, v59, v91
	v_fma_f32 v59, -v131, v78, 1.0
	v_mul_f32_e32 v41, v58, v39
	v_rcp_f32_e32 v92, v118
	v_fmac_f32_e32 v78, v59, v78
	v_fma_f32 v59, -v43, v41, v58
	v_fmac_f32_e32 v41, v59, v39
	v_fma_f32 v43, -v43, v41, v58
	s_mov_b64 vcc, s[62:63]
	v_div_fmas_f32 v39, v43, v39, v41
	v_fma_f32 v60, -v118, v92, 1.0
	v_div_fixup_f32 v22, v39, v61, v22
	v_addc_co_u32_e64 v39, s[42:43], -1, v57, s[42:43]
	v_pk_fma_f32 v[30:31], v[50:51], v[14:15], v[30:31] op_sel_hi:[1,0,1]
	v_pk_fma_f32 v[32:33], v[52:53], v[14:15], v[32:33] op_sel_hi:[1,0,1]
	v_fmac_f32_e32 v92, v60, v92
	v_pk_fma_f32 v[58:59], v[50:51], v[22:23], v[26:27] op_sel_hi:[1,0,1]
	v_pk_fma_f32 v[60:61], v[52:53], v[22:23], v[28:29] op_sel_hi:[1,0,1]
	global_load_dwordx4 v[50:53], v[38:39], off nt
	v_mul_f32_e32 v49, 0xbfb8aa3b, v2
	v_mul_f32_e32 v44, 0xbfb8aa3b, v15
	v_exp_f32_e32 v49, v49
	v_mul_f32_e32 v63, 0xbfb8aa3b, v11
	v_exp_f32_e32 v44, v44
	v_mul_f32_e32 v66, 0xbfb8aa3b, v13
	v_exp_f32_e32 v63, v63
	v_exp_f32_e32 v66, v66
	v_add_f32_e32 v71, 1.0, v49
	v_div_scale_f32 v112, s[4:5], v82, v82, v20
	v_add_f32_e32 v138, 1.0, v44
	v_div_scale_f32 v123, s[4:5], v71, v71, v2
	v_rcp_f32_e32 v96, v112
	v_add_f32_e32 v81, 1.0, v63
	v_mul_f32_e32 v73, 0xbfb8aa3b, v7
	v_div_scale_f32 v107, s[4:5], v138, v138, v15
; #define GAS __attribute__((address_space(1)))
; __device__ __forceinline__ float silu_f(float v) { return v / (1.f + __expf(-v)); }
; __device__ __forceinline__ void p0_prologue(Frame& F) {
;     ...
; #pragma unroll 8
;             for (int k = kbeg; k < kbeg + DM / ADA_KS; ++k) {
;                 const f32x4 w = *(const GAS f32x4*)(W + (size_t)k * 6144);
;                 const float s0 = silu_f(c[k]), s1 = silu_f(c[DM + k]), s2 = silu_f(cctx[k]);
;                 a0 += w * s0; a1 += w * s1; a2 += w * s2;
;             }
	v_div_scale_f32 v133, s[4:5], v68, v68, v5
	v_rcp_f32_e32 v88, v123
	v_add_f32_e32 v72, 1.0, v66
	v_div_scale_f32 v66, s[8:9], v81, v81, v11
	v_exp_f32_e32 v49, v73
	v_rcp_f32_e32 v44, v107
	v_rcp_f32_e32 v73, v133
	v_div_scale_f32 v144, s[8:9], v72, v72, v13
	v_rcp_f32_e32 v89, v66
	v_rcp_f32_e32 v80, v144
	v_fma_f32 v14, -v112, v96, 1.0
	v_fmac_f32_e32 v96, v14, v96
	v_fma_f32 v14, -v123, v88, 1.0
	v_div_scale_f32 v105, s[54:55], v19, v139, v19
	v_fma_f32 v99, -v107, v44, 1.0
	v_fmac_f32_e32 v88, v14, v88
	v_fma_f32 v14, -v133, v73, 1.0
	v_fma_f32 v26, -v66, v89, 1.0
	v_div_scale_f32 v111, s[52:53], v15, v138, v15
	v_fmac_f32_e32 v44, v99, v44
	v_fmac_f32_e32 v73, v14, v73
	v_mul_f32_e32 v14, v105, v45
	v_fmac_f32_e32 v89, v26, v89
	v_fma_f32 v26, -v144, v80, 1.0
	v_div_scale_f32 v115, s[30:31], v20, v82, v20
	v_mul_f32_e32 v140, v111, v44
	v_fmac_f32_e32 v80, v26, v80
	v_fma_f32 v26, -v102, v14, v105
	v_div_scale_f32 v117, s[26:27], v16, v79, v16
	v_mul_f32_e32 v113, v115, v96
	v_fmac_f32_e32 v14, v26, v45
	v_fma_f32 v26, -v107, v140, v111
	v_mul_f32_e32 v65, 0xbfb8aa3b, v12
	v_div_scale_f32 v120, s[20:21], v21, v76, v21
	v_div_scale_f32 v63, s[8:9], v86, v86, v10
	v_mul_f32_e32 v114, v117, v94
	v_fmac_f32_e32 v140, v26, v44
	v_fma_f32 v26, -v112, v113, v115
	v_exp_f32_e32 v65, v65
	v_div_scale_f32 v122, s[18:19], v17, v75, v17
	v_rcp_f32_e32 v93, v63
	v_mul_f32_e32 v110, v120, v92
	v_fmac_f32_e32 v113, v26, v96
	v_fma_f32 v26, -v116, v114, v117
	v_div_scale_f32 v124, s[14:15], v2, v71, v2
	v_mul_f32_e32 v108, v122, v91
	v_fmac_f32_e32 v114, v26, v94
	v_fma_f32 v26, -v118, v110, v120
	v_div_scale_f32 v129, s[10:11], v3, v70, v3
	v_add_f32_e32 v97, 1.0, v46
	v_div_scale_f32 v67, s[22:23], v98, v98, v23
	v_mul_f32_e32 v106, v124, v88
	v_fmac_f32_e32 v110, v26, v92
	v_fma_f32 v26, -v121, v108, v122
	v_div_scale_f32 v132, s[6:7], v4, v69, v4
	v_div_scale_f32 v147, s[22:23], v97, v97, v24
	v_rcp_f32_e32 v18, v67
	v_mul_f32_e32 v104, v129, v84
	v_fmac_f32_e32 v108, v26, v91
	v_fma_f32 v26, -v123, v106, v124
	v_div_scale_f32 v134, s[4:5], v5, v68, v5
	v_add_f32_e32 v74, 1.0, v65
	v_div_scale_f32 v151, s[22:23], v90, v90, v6
	v_rcp_f32_e32 v103, v147
	v_fma_f32 v22, -v63, v93, 1.0
	v_mul_f32_e32 v100, v132, v78
	v_fmac_f32_e32 v106, v26, v88
	v_fma_f32 v26, -v126, v104, v129
	v_div_scale_f32 v136, s[8:9], v74, v74, v12
	v_add_f32_e32 v95, 1.0, v47
	v_div_scale_f32 v46, s[22:23], v83, v83, v8
	v_rcp_f32_e32 v99, v151
	v_fmac_f32_e32 v93, v22, v93
	v_mul_f32_e32 v22, v134, v73
	v_fmac_f32_e32 v104, v26, v84
	v_fma_f32 v26, -v131, v100, v132
	v_rcp_f32_e32 v85, v136
	v_div_scale_f32 v149, s[22:23], v95, v95, v25
	v_fmac_f32_e32 v100, v26, v78
	v_fma_f32 v26, -v133, v22, v134
	v_fma_f32 v142, -v102, v14, v105
	v_rcp_f32_e32 v105, v46
	v_add_f32_e32 v87, 1.0, v49
	v_rcp_f32_e32 v101, v149
	v_fmac_f32_e32 v22, v26, v73
	v_fma_f32 v26, -v67, v18, 1.0
	v_div_scale_f32 v153, s[22:23], v87, v87, v7
	v_fmac_f32_e32 v18, v26, v18
	v_fma_f32 v26, -v147, v103, 1.0
	v_div_scale_f32 v135, s[16:17], v11, v81, v11
	v_rcp_f32_e32 v109, v153
	v_fmac_f32_e32 v103, v26, v103
	v_fma_f32 v26, -v151, v99, 1.0
	v_div_scale_f32 v146, s[56:57], v23, v98, v23
	v_div_scale_f32 v48, s[22:23], v77, v77, v9
	v_fma_f32 v27, -v136, v85, 1.0
	v_fma_f32 v128, -v116, v114, v117
	v_mul_f32_e32 v116, v135, v89
	v_fmac_f32_e32 v99, v26, v99
	v_fma_f32 v26, -v46, v105, 1.0
	v_div_scale_f32 v148, s[40:41], v24, v97, v24
	v_fmac_f32_e32 v85, v27, v85
	v_rcp_f32_e32 v102, v48
	v_fma_f32 v27, -v149, v101, 1.0
	v_fmac_f32_e32 v105, v26, v105
	v_fma_f32 v26, -v66, v116, v135
	v_mul_f32_e32 v143, v146, v18
	v_div_scale_f32 v150, s[38:39], v25, v95, v25
	v_fma_f32 v130, -v112, v113, v115
	v_fmac_f32_e32 v101, v27, v101
	v_fma_f32 v112, -v133, v22, v134
	v_fmac_f32_e32 v116, v26, v89
	v_mul_f32_e32 v133, v148, v103
	v_fma_f32 v26, -v67, v143, v146
	v_div_scale_f32 v152, s[36:37], v6, v90, v6
	v_fma_f32 v27, -v153, v109, 1.0
	v_fma_f32 v117, -v131, v100, v132
	v_mul_f32_e32 v132, v150, v101
	v_fmac_f32_e32 v143, v26, v18
	v_fma_f32 v26, -v147, v133, v148
	v_div_scale_f32 v154, s[34:35], v7, v87, v7
	v_fma_f32 v127, -v118, v110, v120
	v_fma_f32 v120, -v126, v104, v129
	v_fmac_f32_e32 v109, v27, v109
	v_mul_f32_e32 v129, v152, v99
	v_fmac_f32_e32 v133, v26, v103
	v_fma_f32 v26, -v149, v132, v150
	v_div_scale_f32 v47, s[24:25], v8, v83, v8
	v_fma_f32 v123, -v123, v106, v124
	v_fma_f32 v27, -v48, v102, 1.0
	v_mul_f32_e32 v124, v154, v109
	v_fmac_f32_e32 v132, v26, v101
	v_fma_f32 v26, -v151, v129, v152
	v_div_scale_f32 v145, s[8:9], v13, v72, v13
	v_div_scale_f32 v49, s[22:23], v9, v77, v9
	v_fma_f32 v125, -v121, v108, v122
	v_fmac_f32_e32 v102, v27, v102
	v_mul_f32_e32 v121, v47, v105
	v_fmac_f32_e32 v129, v26, v99
	v_fma_f32 v26, -v153, v124, v154
	v_fma_f32 v141, -v107, v140, v111
	v_mul_f32_e32 v107, v145, v80
	v_mul_f32_e32 v115, v49, v102
	v_fmac_f32_e32 v124, v26, v109
	v_fma_f32 v26, -v46, v121, v47
	v_fma_f32 v27, -v144, v107, v145
	v_fmac_f32_e32 v121, v26, v105
	v_fma_f32 v26, -v48, v115, v49
	v_fmac_f32_e32 v107, v27, v80
	v_fmac_f32_e32 v115, v26, v102
	s_movk_i32 s60, 0xa000
	v_addc_co_u32_e64 v41, s[42:43], -1, v57, s[44:45]
	v_div_scale_f32 v65, s[28:29], v10, v86, v10
	v_fma_f32 v126, -v66, v116, v135
	v_fma_f32 v118, -v144, v107, v145
	v_fma_f32 v144, -v67, v143, v146
	v_add_co_u32_e32 v66, vcc, s60, v56
	v_fma_f32 v146, -v46, v121, v47
	v_fma_f32 v145, -v48, v115, v49
	global_load_dwordx4 v[46:49], v[40:41], off nt
	v_div_scale_f32 v137, s[12:13], v12, v74, v12
	v_mul_f32_e32 v119, v65, v93
	v_addc_co_u32_e32 v67, vcc, -1, v57, vcc
	v_mul_f32_e32 v111, v137, v85
	v_fma_f32 v28, -v63, v119, v65
	s_mov_b64 vcc, s[54:55]
	v_fma_f32 v29, -v136, v111, v137
	v_fmac_f32_e32 v119, v28, v93
	v_addc_co_u32_e64 v43, s[42:43], -1, v57, s[46:47]
	v_div_fmas_f32 v14, v142, v45, v14
	s_mov_b64 vcc, s[52:53]
	v_fmac_f32_e32 v111, v29, v85
	v_fma_f32 v131, -v63, v119, v65
	global_load_dwordx4 v[26:29], v[56:57], off nt
	v_addc_co_u32_e64 v65, s[42:43], -1, v57, s[48:49]
	v_div_fmas_f32 v141, v141, v44, v140
	global_load_dwordx4 v[42:45], v[42:43], off nt
	v_addc_co_u32_e64 v63, s[42:43], -1, v57, s[50:51]
	global_load_dwordx4 v[38:41], v[64:65], off nt
	s_mov_b64 vcc, s[56:57]
	v_div_fixup_f32 v14, v14, v139, v19
	v_div_fmas_f32 v140, v144, v18, v143
	s_waitcnt vmcnt(4)
; #define GAS __attribute__((address_space(1)))
; __device__ __forceinline__ float silu_f(float v) { return v / (1.f + __expf(-v)); }
; __device__ __forceinline__ void p0_prologue(Frame& F) {
;     ...
;             for (int k = kbeg; k < kbeg + DM / ADA_KS; ++k) {
;                 const f32x4 w = *(const GAS f32x4*)(W + (size_t)k * 6144);
;                 const float s0 = silu_f(c[k]), s1 = silu_f(c[DM + k]), s2 = silu_f(cctx[k]);
;                 a0 += w * s0; a1 += w * s1; a2 += w * s2;
;             }
;             float* P = (float*)(F.ws + WS_MODP) + ((size_t)(ks * 2 + l) * 3) * 6144 + cg * 256 + 4 * F.lane;
;             *(GAS f32x4*)(P) = a0; *(GAS f32x4*)(P + 6144) = a1; *(GAS f32x4*)(P + 2 * 6144) = a2;
;         }
	v_pk_fma_f32 v[18:19], v[52:53], v[14:15], v[36:37] op_sel_hi:[1,0,1]
	v_pk_fma_f32 v[64:65], v[50:51], v[14:15], v[34:35] op_sel_hi:[1,0,1]
	global_load_dwordx4 v[34:37], v[62:63], off nt
	v_div_fixup_f32 v62, v141, v138, v15
	v_pk_fma_f32 v[14:15], v[52:53], v[62:63], v[32:33] op_sel_hi:[1,0,1]
	v_pk_fma_f32 v[62:63], v[50:51], v[62:63], v[30:31] op_sel_hi:[1,0,1]
	global_load_dwordx4 v[30:33], v[66:67], off nt
	s_mov_b64 vcc, s[30:31]
	v_div_fixup_f32 v66, v140, v98, v23
	v_div_fmas_f32 v23, v130, v96, v113
	s_mov_b64 vcc, s[26:27]
	v_fma_f32 v122, -v136, v111, v137
	v_fma_f32 v137, -v147, v133, v148
	v_pk_fma_f32 v[52:53], v[52:53], v[66:67], v[60:61] op_sel_hi:[1,0,1]
	v_div_fmas_f32 v60, v128, v94, v114
	s_mov_b64 vcc, s[40:41]
	v_div_fixup_f32 v20, v23, v82, v20
	v_div_fmas_f32 v23, v137, v103, v133
	v_div_fixup_f32 v16, v60, v79, v16
	s_mov_b64 vcc, s[20:21]
	v_pk_fma_f32 v[50:51], v[50:51], v[66:67], v[58:59] op_sel_hi:[1,0,1]
	v_fma_f32 v136, -v149, v132, v150
	v_fma_f32 v135, -v151, v129, v152
	v_fma_f32 v134, -v153, v124, v154
	s_mov_b64 s[42:43], 0x30000
	v_lshl_add_u64 v[56:57], v[56:57], 0, s[42:43]
	s_waitcnt vmcnt(5)
	v_pk_fma_f32 v[58:59], v[46:47], v[20:21], v[64:65] op_sel_hi:[1,0,1]
	v_pk_fma_f32 v[18:19], v[48:49], v[20:21], v[18:19] op_sel_hi:[1,0,1]
	v_pk_fma_f32 v[60:61], v[46:47], v[16:17], v[62:63] op_sel_hi:[1,0,1]
	v_pk_fma_f32 v[14:15], v[48:49], v[16:17], v[14:15] op_sel_hi:[1,0,1]
	v_div_fixup_f32 v16, v23, v97, v24
	v_div_fmas_f32 v20, v127, v92, v110
	s_mov_b64 vcc, s[18:19]
	v_pk_fma_f32 v[46:47], v[46:47], v[16:17], v[50:51] op_sel_hi:[1,0,1]
	v_pk_fma_f32 v[48:49], v[48:49], v[16:17], v[52:53] op_sel_hi:[1,0,1]
	v_div_fixup_f32 v16, v20, v76, v21
	v_div_fmas_f32 v20, v125, v91, v108
	s_mov_b64 vcc, s[38:39]
	v_div_fmas_f32 v21, v136, v101, v132
	s_mov_b64 vcc, s[14:15]
	v_div_fixup_f32 v20, v20, v75, v17
	v_div_fixup_f32 v24, v21, v95, v25
	v_div_fmas_f32 v23, v123, v88, v106
	s_mov_b64 vcc, s[28:29]
	v_div_fixup_f32 v2, v23, v71, v2
	s_waitcnt vmcnt(3)
	v_pk_fma_f32 v[18:19], v[44:45], v[16:17], v[18:19] op_sel_hi:[1,0,1]
	v_pk_fma_f32 v[16:17], v[42:43], v[16:17], v[58:59] op_sel_hi:[1,0,1]
	v_pk_fma_f32 v[14:15], v[44:45], v[20:21], v[14:15] op_sel_hi:[1,0,1]
	v_pk_fma_f32 v[20:21], v[42:43], v[20:21], v[60:61] op_sel_hi:[1,0,1]
	v_pk_fma_f32 v[44:45], v[44:45], v[24:25], v[48:49] op_sel_hi:[1,0,1]
	v_pk_fma_f32 v[24:25], v[42:43], v[24:25], v[46:47] op_sel_hi:[1,0,1]
	v_div_fmas_f32 v42, v131, v93, v119
	s_mov_b64 vcc, s[36:37]
	v_div_fmas_f32 v23, v135, v99, v129
	s_waitcnt vmcnt(2)
	v_pk_fma_f32 v[16:17], v[38:39], v[2:3], v[16:17] op_sel_hi:[1,0,1]
	v_pk_fma_f32 v[18:19], v[40:41], v[2:3], v[18:19] op_sel_hi:[1,0,1]
	v_div_fixup_f32 v2, v42, v86, v10
	s_mov_b64 vcc, s[10:11]
	v_pk_fma_f32 v[20:21], v[38:39], v[2:3], v[20:21] op_sel_hi:[1,0,1]
	v_pk_fma_f32 v[14:15], v[40:41], v[2:3], v[14:15] op_sel_hi:[1,0,1]
	v_div_fixup_f32 v2, v23, v90, v6
	v_div_fmas_f32 v6, v120, v84, v104
	s_mov_b64 vcc, s[16:17]
	v_div_fmas_f32 v10, v126, v89, v116
	s_mov_b64 vcc, s[34:35]
	v_pk_fma_f32 v[24:25], v[38:39], v[2:3], v[24:25] op_sel_hi:[1,0,1]
	v_pk_fma_f32 v[38:39], v[40:41], v[2:3], v[44:45] op_sel_hi:[1,0,1]
	v_div_fixup_f32 v2, v6, v70, v3
	v_div_fmas_f32 v23, v134, v109, v124
	v_div_fixup_f32 v6, v10, v81, v11
	s_mov_b64 vcc, s[6:7]
	s_waitcnt vmcnt(1)
	v_pk_fma_f32 v[10:11], v[36:37], v[6:7], v[14:15] op_sel_hi:[1,0,1]
	v_pk_fma_f32 v[14:15], v[34:35], v[6:7], v[20:21] op_sel_hi:[1,0,1]
	v_div_fmas_f32 v20, v117, v78, v100
	s_mov_b64 vcc, s[12:13]
	v_pk_fma_f32 v[18:19], v[36:37], v[2:3], v[18:19] op_sel_hi:[1,0,1]
	v_pk_fma_f32 v[2:3], v[34:35], v[2:3], v[16:17] op_sel_hi:[1,0,1]
	v_div_fmas_f32 v21, v122, v85, v111
	v_div_fixup_f32 v4, v20, v69, v4
	s_mov_b64 vcc, s[24:25]
	v_div_fmas_f32 v20, v146, v105, v121
	s_waitcnt vmcnt(0)
	v_pk_fma_f32 v[2:3], v[30:31], v[4:5], v[2:3] op_sel_hi:[1,0,1]
	v_pk_fma_f32 v[18:19], v[32:33], v[4:5], v[18:19] op_sel_hi:[1,0,1]
	v_div_fixup_f32 v4, v21, v74, v12
	s_mov_b64 vcc, s[4:5]
	v_div_fixup_f32 v6, v23, v87, v7
	v_pk_fma_f32 v[14:15], v[30:31], v[4:5], v[14:15] op_sel_hi:[1,0,1]
	v_pk_fma_f32 v[10:11], v[32:33], v[4:5], v[10:11] op_sel_hi:[1,0,1]
	v_div_fmas_f32 v4, v112, v73, v22
	s_mov_b64 vcc, s[8:9]
	v_pk_fma_f32 v[16:17], v[36:37], v[6:7], v[38:39] op_sel_hi:[1,0,1]
	v_pk_fma_f32 v[6:7], v[34:35], v[6:7], v[24:25] op_sel_hi:[1,0,1]
	v_div_fixup_f32 v8, v20, v83, v8
	v_div_fixup_f32 v4, v4, v68, v5
	v_div_fmas_f32 v5, v118, v80, v107
	s_mov_b64 vcc, s[22:23]
	v_pk_fma_f32 v[6:7], v[30:31], v[8:9], v[6:7] op_sel_hi:[1,0,1]
	v_pk_fma_f32 v[16:17], v[32:33], v[8:9], v[16:17] op_sel_hi:[1,0,1]
	v_div_fixup_f32 v8, v5, v72, v13
	v_div_fmas_f32 v5, v145, v102, v115
	v_pk_fma_f32 v[34:35], v[26:27], v[4:5], v[2:3] op_sel_hi:[1,0,1]
	v_div_fixup_f32 v2, v5, v77, v9
	v_pk_fma_f32 v[36:37], v[28:29], v[4:5], v[18:19] op_sel_hi:[1,0,1]
	v_pk_fma_f32 v[32:33], v[28:29], v[8:9], v[10:11] op_sel_hi:[1,0,1]
	v_pk_fma_f32 v[30:31], v[26:27], v[8:9], v[14:15] op_sel_hi:[1,0,1]
	v_pk_fma_f32 v[28:29], v[28:29], v[2:3], v[16:17] op_sel_hi:[1,0,1]
	v_pk_fma_f32 v[26:27], v[26:27], v[2:3], v[6:7] op_sel_hi:[1,0,1]
	s_cbranch_scc0 .LBB0_1196
	s_lshl_b32 s4, s70, 1
	s_add_i32 s4, s4, s69
	s_mul_i32 s5, s4, 3
	s_mul_i32 s4, s4, 0x12000
	s_mul_hi_i32 s5, s5, 0x6000
	s_add_u32 s4, s67, s4
	s_addc_u32 s5, s68, s5
	s_add_u32 s0, s4, s0
	s_addc_u32 s1, s5, s1
	v_lshl_add_u64 v[2:3], s[0:1], 0, v[0:1]
	global_store_dwordx4 v0, v[34:37], s[0:1]
	v_add_co_u32_e32 v4, vcc, 0x6000, v2
	v_readlane_b32 s0, v243, 18
	s_nop 0
	v_addc_co_u32_e32 v5, vcc, 0, v3, vcc
	s_mul_i32 s0, s0, 3
	v_add_co_u32_e32 v2, vcc, 0xc000, v2
	s_add_i32 s66, s66, s0
	s_nop 0
	v_addc_co_u32_e32 v3, vcc, 0, v3, vcc
	s_cmpk_gt_i32 s66, 0x2ff
	global_store_dwordx4 v[4:5], v[30:33], off
	global_store_dwordx4 v[2:3], v[26:29], off
	s_cbranch_scc0 .LBB0_1195
